# GEMM K-loops: priority kept raised across both MFMA blocks of a segment (no setprio 0/1 toggle), redundant lgkmcnt(0) after the segment barrier removed; on top of v66
# speedup vs baseline: 1.0048x; 1.0009x over previous
; #define PG8_STAGE(bufoff, gbase, voff) do { _Pragma("unroll") for (int _i = 0; _i < 2; ++_i) \
;         __builtin_amdgcn_global_load_lds((const unsigned*)((const char*)(gbase) + (voff)[_i]), (LAS unsigned*)(lds + (bufoff) + ldsw + _i * 8192), 16, 0, 0); } while (0)
; #define PG8_LDA(dst, b, h) do { _Pragma("unroll") for (int m = 0; m < 4; ++m) _Pragma("unroll") for (int k = 0; k < 2; ++k) dst[m][k] = *(const LAS bf16x8*)(lds + PG8_SA(b, h) + aoff + m * 2048 + k * 1024); } while (0)
; #define PG8_LDB(dst, b, h) do { _Pragma("unroll") for (int n = 0; n < 2; ++n) _Pragma("unroll") for (int k = 0; k < 2; ++k) dst[n][k] = *(const LAS bf16x8*)(lds + PG8_SB(b, h) + boff + n * 2048 + k * 1024); } while (0)
; #define PG8_MMA(ai, bj, At, Bt) do { __builtin_amdgcn_s_setprio(1); _Pragma("unroll") for (int m = 0; m < 4; ++m) _Pragma("unroll") for (int n = 0; n < 2; ++n) _Pragma("unroll") for (int k = 0; k < 2; ++k) \
;         acc[ai][bj][m][n] = __builtin_amdgcn_mfma_f32_16x16x32_bf16(Bt[n][k], At[m][k], acc[ai][bj][m][n], 0, 0, 0); __builtin_amdgcn_s_setprio(0); } while (0)
; #define PG8_WAIT_V(n) asm volatile("s_waitcnt vmcnt(" #n ")" ::: "memory")
; #define PG8_WAIT_L(n) asm volatile("s_waitcnt lgkmcnt(" #n ")" ::: "memory")
; #define PG8_BAR __builtin_amdgcn_s_barrier()
; #define PG8_SCHED __builtin_amdgcn_sched_barrier(0)
; template <class Epi, bool SP2 = false>
; __device__ __forceinline__ void gemm_phase(LAS unsigned char* lds, const Gemm g, const StaticOrder& S, const Epi& E) {
;     ...
;             PG8_LDB(B0, 0, 0); PG8_LDB(B1, 0, 1); PG8_SCHED; PG8_LDA(At, 0, 0); PG8_STAGE(PG8_SA(1, 1), a1 + hstepA, voffA);
;             PG8_WAIT_V(8); PG8_WAIT_L(0); PG8_BAR; PG8_MMA(0, 0, At, B0); PG8_MMA(0, 1, At, B1); PG8_BAR; PG8_SCHED;
;             PG8_LDA(At, 0, 1); PG8_STAGE(PG8_SB(0, 0), b2, voffB); PG8_STAGE(PG8_SB(0, 1), b2 + hstepB, voffB); PG8_STAGE(PG8_SA(0, 0), a2, voffA);
;             PG8_WAIT_V(8); PG8_WAIT_L(0); PG8_BAR; PG8_MMA(1, 0, At, B0); PG8_MMA(1, 1, At, B1); PG8_BAR; PG8_SCHED;
.LBB0_263:
	ds_read_b128 v[152:155], v149
	ds_read_b128 v[156:159], v149 offset:1024
	ds_read_b128 v[160:163], v149 offset:2048
	ds_read_b128 v[164:167], v149 offset:3072
	ds_read_b128 v[168:171], v150
	ds_read_b128 v[172:175], v150 offset:1024
	ds_read_b128 v[176:179], v150 offset:2048
	ds_read_b128 v[180:183], v150 offset:3072
	s_add_u32 s44, s34, 0xfffc0080
	s_addc_u32 s45, s35, -1
	s_cmp_eq_u32 s75, 12
	s_cselect_b32 s51, s27, s45
	s_cselect_b32 s50, s67, s44
	s_cselect_b32 s45, s25, s74
	s_cselect_b32 s44, s72, s73
	v_lshl_add_u64 v[146:147], s[34:35], 0, v[138:139]
	s_add_i32 m0, s41, 0xc000
	ds_read_b128 v[184:187], v151
	ds_read_b128 v[188:191], v151 offset:1024
	ds_read_b128 v[192:195], v151 offset:2048
	ds_read_b128 v[196:199], v151 offset:3072
	ds_read_b128 v[200:203], v151 offset:4096
	ds_read_b128 v[204:207], v151 offset:5120
	ds_read_b128 v[208:211], v151 offset:6144
	ds_read_b128 v[212:215], v151 offset:7168
	global_load_lds_dwordx4 v[146:147], off
	v_lshl_add_u64 v[146:147], s[34:35], 0, v[140:141]
	s_add_i32 m0, s41, 0xe000
	s_nop 0
	global_load_lds_dwordx4 v[146:147], off
	s_waitcnt vmcnt(8)
	s_waitcnt lgkmcnt(0)
	s_barrier
	s_setprio 1
	v_mfma_f32_16x16x32_bf16 v[124:127], v[152:155], v[184:187], v[124:127]
	v_mfma_f32_16x16x32_bf16 v[120:123], v[160:163], v[184:187], v[120:123]
	v_mfma_f32_16x16x32_bf16 v[108:111], v[152:155], v[192:195], v[108:111]
	v_mfma_f32_16x16x32_bf16 v[104:107], v[160:163], v[192:195], v[104:107]
	v_mfma_f32_16x16x32_bf16 v[92:95], v[152:155], v[200:203], v[92:95]
	v_mfma_f32_16x16x32_bf16 v[88:91], v[160:163], v[200:203], v[88:91]
	v_mfma_f32_16x16x32_bf16 v[76:79], v[152:155], v[208:211], v[76:79]
	v_mfma_f32_16x16x32_bf16 v[72:75], v[160:163], v[208:211], v[72:75]
	v_mfma_f32_16x16x32_bf16 v[124:127], v[156:159], v[188:191], v[124:127]
	v_mfma_f32_16x16x32_bf16 v[120:123], v[164:167], v[188:191], v[120:123]
	v_mfma_f32_16x16x32_bf16 v[108:111], v[156:159], v[196:199], v[108:111]
	v_mfma_f32_16x16x32_bf16 v[104:107], v[164:167], v[196:199], v[104:107]
	v_mfma_f32_16x16x32_bf16 v[92:95], v[156:159], v[204:207], v[92:95]
	v_mfma_f32_16x16x32_bf16 v[88:91], v[164:167], v[204:207], v[88:91]
	v_mfma_f32_16x16x32_bf16 v[76:79], v[156:159], v[212:215], v[76:79]
	v_mfma_f32_16x16x32_bf16 v[72:75], v[164:167], v[212:215], v[72:75]
	v_mfma_f32_16x16x32_bf16 v[116:119], v[168:171], v[184:187], v[116:119]
	v_mfma_f32_16x16x32_bf16 v[112:115], v[176:179], v[184:187], v[112:115]
	v_mfma_f32_16x16x32_bf16 v[100:103], v[168:171], v[192:195], v[100:103]
	v_mfma_f32_16x16x32_bf16 v[96:99], v[176:179], v[192:195], v[96:99]
	v_mfma_f32_16x16x32_bf16 v[84:87], v[168:171], v[200:203], v[84:87]
	v_mfma_f32_16x16x32_bf16 v[80:83], v[176:179], v[200:203], v[80:83]
	v_mfma_f32_16x16x32_bf16 v[68:71], v[168:171], v[208:211], v[68:71]
	v_mfma_f32_16x16x32_bf16 v[64:67], v[176:179], v[208:211], v[64:67]
	v_mfma_f32_16x16x32_bf16 v[116:119], v[172:175], v[188:191], v[116:119]
	v_mfma_f32_16x16x32_bf16 v[112:115], v[180:183], v[188:191], v[112:115]
	v_mfma_f32_16x16x32_bf16 v[100:103], v[172:175], v[196:199], v[100:103]
	v_mfma_f32_16x16x32_bf16 v[96:99], v[180:183], v[196:199], v[96:99]
	v_mfma_f32_16x16x32_bf16 v[84:87], v[172:175], v[204:207], v[84:87]
	v_mfma_f32_16x16x32_bf16 v[80:83], v[180:183], v[204:207], v[80:83]
	v_mfma_f32_16x16x32_bf16 v[68:71], v[172:175], v[212:215], v[68:71]
	v_mfma_f32_16x16x32_bf16 v[64:67], v[180:183], v[212:215], v[64:67]
	s_setprio 0
	s_barrier
	s_add_i32 s68, s64, s3
	v_lshl_add_u64 v[146:147], s[44:45], 0, v[134:135]
	s_mov_b32 m0, s68
	ds_read_b128 v[184:187], v151 offset:16384
	ds_read_b128 v[188:191], v151 offset:17408
	ds_read_b128 v[192:195], v151 offset:18432
	ds_read_b128 v[196:199], v151 offset:19456
	ds_read_b128 v[200:203], v151 offset:20480
	ds_read_b128 v[204:207], v151 offset:21504
	ds_read_b128 v[208:211], v151 offset:22528
	ds_read_b128 v[212:215], v151 offset:23552
	global_load_lds_dwordx4 v[146:147], off
	s_add_i32 m0, s68, 0x2000
	s_add_u32 s68, s44, 0x40000
	v_lshl_add_u64 v[216:217], s[44:45], 0, v[130:131]
	s_addc_u32 s69, s45, 0
	s_add_i32 s70, s65, s3
	global_load_lds_dwordx4 v[216:217], off
	v_lshl_add_u64 v[218:219], s[68:69], 0, v[134:135]
	s_mov_b32 m0, s70
	v_lshl_add_u64 v[220:221], s[50:51], 0, v[132:133]
	global_load_lds_dwordx4 v[218:219], off
	v_lshl_add_u64 v[218:219], s[68:69], 0, v[130:131]
	s_add_i32 m0, s70, 0x2000
	s_nop 0
	global_load_lds_dwordx4 v[218:219], off
	v_lshl_add_u64 v[218:219], s[50:51], 0, v[136:137]
	s_mov_b32 m0, s41
	s_nop 0
	global_load_lds_dwordx4 v[218:219], off
	s_mov_b32 m0, s54
	s_nop 0
	global_load_lds_dwordx4 v[220:221], off
	s_waitcnt vmcnt(8)
	s_waitcnt lgkmcnt(0)
	s_barrier
; #define PG8_STAGE(bufoff, gbase, voff) do { _Pragma("unroll") for (int _i = 0; _i < 2; ++_i) \
;         __builtin_amdgcn_global_load_lds((const unsigned*)((const char*)(gbase) + (voff)[_i]), (LAS unsigned*)(lds + (bufoff) + ldsw + _i * 8192), 16, 0, 0); } while (0)
; #define PG8_LDA(dst, b, h) do { _Pragma("unroll") for (int m = 0; m < 4; ++m) _Pragma("unroll") for (int k = 0; k < 2; ++k) dst[m][k] = *(const LAS bf16x8*)(lds + PG8_SA(b, h) + aoff + m * 2048 + k * 1024); } while (0)
; #define PG8_LDB(dst, b, h) do { _Pragma("unroll") for (int n = 0; n < 2; ++n) _Pragma("unroll") for (int k = 0; k < 2; ++k) dst[n][k] = *(const LAS bf16x8*)(lds + PG8_SB(b, h) + boff + n * 2048 + k * 1024); } while (0)
; #define PG8_MMA(ai, bj, At, Bt) do { __builtin_amdgcn_s_setprio(1); _Pragma("unroll") for (int m = 0; m < 4; ++m) _Pragma("unroll") for (int n = 0; n < 2; ++n) _Pragma("unroll") for (int k = 0; k < 2; ++k) \
;         acc[ai][bj][m][n] = __builtin_amdgcn_mfma_f32_16x16x32_bf16(Bt[n][k], At[m][k], acc[ai][bj][m][n], 0, 0, 0); __builtin_amdgcn_s_setprio(0); } while (0)
; #define PG8_WAIT_V(n) asm volatile("s_waitcnt vmcnt(" #n ")" ::: "memory")
; #define PG8_WAIT_L(n) asm volatile("s_waitcnt lgkmcnt(" #n ")" ::: "memory")
; #define PG8_BAR __builtin_amdgcn_s_barrier()
; #define PG8_SCHED __builtin_amdgcn_sched_barrier(0)
; template <class Epi, bool SP2 = false>
; __device__ __forceinline__ void gemm_phase(LAS unsigned char* lds, const Gemm g, const StaticOrder& S, const Epi& E) {
;     ...
;             PG8_WAIT_V(8); PG8_WAIT_L(0); PG8_BAR; PG8_MMA(0, 0, At, B0); PG8_MMA(0, 1, At, B1); PG8_BAR; PG8_SCHED;
;             PG8_LDA(At, 0, 1); PG8_STAGE(PG8_SB(0, 0), b2, voffB); PG8_STAGE(PG8_SB(0, 1), b2 + hstepB, voffB); PG8_STAGE(PG8_SA(0, 0), a2, voffA);
;             PG8_WAIT_V(8); PG8_WAIT_L(0); PG8_BAR; PG8_MMA(1, 0, At, B0); PG8_MMA(1, 1, At, B1); PG8_BAR; PG8_SCHED;
;             PG8_LDB(B0, 1, 0); PG8_LDB(B1, 1, 1); PG8_SCHED; PG8_LDA(At, 1, 0); PG8_STAGE(PG8_SA(0, 1), a2 + hstepA, voffA);
;             PG8_WAIT_V(8); PG8_WAIT_L(0); PG8_BAR; PG8_MMA(0, 0, At, B0); PG8_MMA(0, 1, At, B1); PG8_BAR; PG8_SCHED;
	s_setprio 1
	v_mfma_f32_16x16x32_bf16 v[60:63], v[152:155], v[184:187], v[60:63]
	v_mfma_f32_16x16x32_bf16 v[56:59], v[160:163], v[184:187], v[56:59]
	v_mfma_f32_16x16x32_bf16 v[44:47], v[152:155], v[192:195], v[44:47]
	v_mfma_f32_16x16x32_bf16 v[40:43], v[160:163], v[192:195], v[40:43]
	v_mfma_f32_16x16x32_bf16 v[28:31], v[152:155], v[200:203], v[28:31]
	v_mfma_f32_16x16x32_bf16 v[24:27], v[160:163], v[200:203], v[24:27]
	v_mfma_f32_16x16x32_bf16 v[12:15], v[152:155], v[208:211], v[12:15]
	v_mfma_f32_16x16x32_bf16 v[8:11], v[160:163], v[208:211], v[8:11]
	v_mfma_f32_16x16x32_bf16 v[60:63], v[156:159], v[188:191], v[60:63]
	v_mfma_f32_16x16x32_bf16 v[56:59], v[164:167], v[188:191], v[56:59]
	v_mfma_f32_16x16x32_bf16 v[44:47], v[156:159], v[196:199], v[44:47]
	v_mfma_f32_16x16x32_bf16 v[40:43], v[164:167], v[196:199], v[40:43]
	v_mfma_f32_16x16x32_bf16 v[28:31], v[156:159], v[204:207], v[28:31]
	v_mfma_f32_16x16x32_bf16 v[24:27], v[164:167], v[204:207], v[24:27]
	v_mfma_f32_16x16x32_bf16 v[12:15], v[156:159], v[212:215], v[12:15]
	v_mfma_f32_16x16x32_bf16 v[8:11], v[164:167], v[212:215], v[8:11]
	v_mfma_f32_16x16x32_bf16 v[52:55], v[168:171], v[184:187], v[52:55]
	v_mfma_f32_16x16x32_bf16 v[48:51], v[176:179], v[184:187], v[48:51]
	v_mfma_f32_16x16x32_bf16 v[36:39], v[168:171], v[192:195], v[36:39]
	v_mfma_f32_16x16x32_bf16 v[32:35], v[176:179], v[192:195], v[32:35]
	v_mfma_f32_16x16x32_bf16 v[20:23], v[168:171], v[200:203], v[20:23]
	v_mfma_f32_16x16x32_bf16 v[16:19], v[176:179], v[200:203], v[16:19]
	v_mfma_f32_16x16x32_bf16 v[4:7], v[168:171], v[208:211], v[4:7]
	v_mfma_f32_16x16x32_bf16 v[0:3], v[176:179], v[208:211], v[0:3]
	v_mfma_f32_16x16x32_bf16 v[52:55], v[172:175], v[188:191], v[52:55]
	v_mfma_f32_16x16x32_bf16 v[48:51], v[180:183], v[188:191], v[48:51]
	v_mfma_f32_16x16x32_bf16 v[36:39], v[172:175], v[196:199], v[36:39]
	v_mfma_f32_16x16x32_bf16 v[32:35], v[180:183], v[196:199], v[32:35]
	v_mfma_f32_16x16x32_bf16 v[20:23], v[172:175], v[204:207], v[20:23]
	v_mfma_f32_16x16x32_bf16 v[16:19], v[180:183], v[204:207], v[16:19]
	v_mfma_f32_16x16x32_bf16 v[4:7], v[172:175], v[212:215], v[4:7]
	v_mfma_f32_16x16x32_bf16 v[0:3], v[180:183], v[212:215], v[0:3]
	s_setprio 0
	s_barrier
	s_add_i32 s68, 0, 0x18000
	s_add_i32 s69, 0, 0x1c000
	v_add_u32_e32 v164, s68, v148
	v_add_u32_e32 v180, s69, v148
	ds_read_b128 v[152:155], v164
	ds_read_b128 v[156:159], v164 offset:1024
	ds_read_b128 v[160:163], v164 offset:2048
	ds_read_b128 v[164:167], v164 offset:3072
	ds_read_b128 v[168:171], v180
	ds_read_b128 v[172:175], v180 offset:1024
	ds_read_b128 v[176:179], v180 offset:2048
	ds_read_b128 v[180:183], v180 offset:3072
	s_add_u32 s50, s50, 0x40000
	s_addc_u32 s51, s51, 0
	s_mov_b32 m0, s55
	v_lshl_add_u64 v[222:223], s[50:51], 0, v[136:137]
	ds_read_b128 v[184:187], v151 offset:32768
	ds_read_b128 v[188:191], v151 offset:33792
	ds_read_b128 v[192:195], v151 offset:34816
	ds_read_b128 v[196:199], v151 offset:35840
	ds_read_b128 v[200:203], v151 offset:36864
	ds_read_b128 v[204:207], v151 offset:37888
	ds_read_b128 v[208:211], v151 offset:38912
	ds_read_b128 v[212:215], v151 offset:39936
	global_load_lds_dwordx4 v[222:223], off
	v_lshl_add_u64 v[222:223], s[50:51], 0, v[132:133]
	s_mov_b32 m0, s56
	s_nop 0
	global_load_lds_dwordx4 v[222:223], off
	s_waitcnt vmcnt(8)
	s_waitcnt lgkmcnt(0)
	s_barrier
	s_setprio 1
	v_mfma_f32_16x16x32_bf16 v[124:127], v[152:155], v[184:187], v[124:127]
	v_mfma_f32_16x16x32_bf16 v[120:123], v[160:163], v[184:187], v[120:123]
	v_mfma_f32_16x16x32_bf16 v[108:111], v[152:155], v[192:195], v[108:111]
	v_mfma_f32_16x16x32_bf16 v[104:107], v[160:163], v[192:195], v[104:107]
	v_mfma_f32_16x16x32_bf16 v[92:95], v[152:155], v[200:203], v[92:95]
	v_mfma_f32_16x16x32_bf16 v[88:91], v[160:163], v[200:203], v[88:91]
	v_mfma_f32_16x16x32_bf16 v[76:79], v[152:155], v[208:211], v[76:79]
	v_mfma_f32_16x16x32_bf16 v[72:75], v[160:163], v[208:211], v[72:75]
	v_mfma_f32_16x16x32_bf16 v[124:127], v[156:159], v[188:191], v[124:127]
	v_mfma_f32_16x16x32_bf16 v[120:123], v[164:167], v[188:191], v[120:123]
	v_mfma_f32_16x16x32_bf16 v[108:111], v[156:159], v[196:199], v[108:111]
	v_mfma_f32_16x16x32_bf16 v[104:107], v[164:167], v[196:199], v[104:107]
	v_mfma_f32_16x16x32_bf16 v[92:95], v[156:159], v[204:207], v[92:95]
	v_mfma_f32_16x16x32_bf16 v[88:91], v[164:167], v[204:207], v[88:91]
	v_mfma_f32_16x16x32_bf16 v[76:79], v[156:159], v[212:215], v[76:79]
	v_mfma_f32_16x16x32_bf16 v[72:75], v[164:167], v[212:215], v[72:75]
	v_mfma_f32_16x16x32_bf16 v[116:119], v[168:171], v[184:187], v[116:119]
	v_mfma_f32_16x16x32_bf16 v[112:115], v[176:179], v[184:187], v[112:115]
	v_mfma_f32_16x16x32_bf16 v[100:103], v[168:171], v[192:195], v[100:103]
	v_mfma_f32_16x16x32_bf16 v[96:99], v[176:179], v[192:195], v[96:99]
	v_mfma_f32_16x16x32_bf16 v[84:87], v[168:171], v[200:203], v[84:87]
	v_mfma_f32_16x16x32_bf16 v[80:83], v[176:179], v[200:203], v[80:83]
	v_mfma_f32_16x16x32_bf16 v[68:71], v[168:171], v[208:211], v[68:71]
	v_mfma_f32_16x16x32_bf16 v[64:67], v[176:179], v[208:211], v[64:67]
	v_mfma_f32_16x16x32_bf16 v[116:119], v[172:175], v[188:191], v[116:119]
	v_mfma_f32_16x16x32_bf16 v[112:115], v[180:183], v[188:191], v[112:115]
	v_mfma_f32_16x16x32_bf16 v[100:103], v[172:175], v[196:199], v[100:103]
	v_mfma_f32_16x16x32_bf16 v[96:99], v[180:183], v[196:199], v[96:99]
	v_mfma_f32_16x16x32_bf16 v[84:87], v[172:175], v[204:207], v[84:87]
	v_mfma_f32_16x16x32_bf16 v[80:83], v[180:183], v[204:207], v[80:83]
	v_mfma_f32_16x16x32_bf16 v[68:71], v[172:175], v[212:215], v[68:71]
	v_mfma_f32_16x16x32_bf16 v[64:67], v[180:183], v[212:215], v[64:67]
	s_setprio 0
	s_barrier
; #define PG8_STAGE(bufoff, gbase, voff) do { _Pragma("unroll") for (int _i = 0; _i < 2; ++_i) \
;         __builtin_amdgcn_global_load_lds((const unsigned*)((const char*)(gbase) + (voff)[_i]), (LAS unsigned*)(lds + (bufoff) + ldsw + _i * 8192), 16, 0, 0); } while (0)
; #define PG8_LDA(dst, b, h) do { _Pragma("unroll") for (int m = 0; m < 4; ++m) _Pragma("unroll") for (int k = 0; k < 2; ++k) dst[m][k] = *(const LAS bf16x8*)(lds + PG8_SA(b, h) + aoff + m * 2048 + k * 1024); } while (0)
; #define PG8_MMA(ai, bj, At, Bt) do { __builtin_amdgcn_s_setprio(1); _Pragma("unroll") for (int m = 0; m < 4; ++m) _Pragma("unroll") for (int n = 0; n < 2; ++n) _Pragma("unroll") for (int k = 0; k < 2; ++k) \
;         acc[ai][bj][m][n] = __builtin_amdgcn_mfma_f32_16x16x32_bf16(Bt[n][k], At[m][k], acc[ai][bj][m][n], 0, 0, 0); __builtin_amdgcn_s_setprio(0); } while (0)
; #define PG8_WAIT_V(n) asm volatile("s_waitcnt vmcnt(" #n ")" ::: "memory")
; #define PG8_WAIT_L(n) asm volatile("s_waitcnt lgkmcnt(" #n ")" ::: "memory")
; #define PG8_BAR __builtin_amdgcn_s_barrier()
; #define PG8_SCHED __builtin_amdgcn_sched_barrier(0)
; template <class Epi, bool SP2 = false>
; __device__ __forceinline__ void gemm_phase(LAS unsigned char* lds, const Gemm g, const StaticOrder& S, const Epi& E) {
;     ...
;         for (int t = 0; t < nt; t += 2) {
;     ...
;             PG8_LDA(At, 1, 1); PG8_STAGE(PG8_SB(1, 0), b3, voffB); PG8_STAGE(PG8_SB(1, 1), b3 + hstepB, voffB); PG8_STAGE(PG8_SA(1, 0), a3, voffA);
;             PG8_WAIT_V(8); PG8_WAIT_L(0); PG8_BAR; PG8_MMA(1, 0, At, B0); PG8_MMA(1, 1, At, B1); PG8_BAR; PG8_SCHED;
	s_add_i32 s50, s68, s3
	v_lshl_add_u64 v[146:147], v[146:147], 0, s[12:13]
	s_mov_b32 m0, s50
	ds_read_b128 v[184:187], v151 offset:49152
	ds_read_b128 v[188:191], v151 offset:50176
	ds_read_b128 v[192:195], v151 offset:51200
	ds_read_b128 v[196:199], v151 offset:52224
	ds_read_b128 v[200:203], v151 offset:53248
	ds_read_b128 v[204:207], v151 offset:54272
	ds_read_b128 v[208:211], v151 offset:55296
	ds_read_b128 v[212:215], v151 offset:56320
	global_load_lds_dwordx4 v[146:147], off
	s_add_i32 m0, s50, 0x2000
	s_add_u32 s44, s44, 0x40080
	v_lshl_add_u64 v[146:147], v[216:217], 0, s[12:13]
	s_addc_u32 s45, s45, 0
	s_add_i32 s50, s69, s3
	global_load_lds_dwordx4 v[146:147], off
	v_lshl_add_u64 v[146:147], s[44:45], 0, v[134:135]
	s_mov_b32 m0, s50
	s_nop 0
	global_load_lds_dwordx4 v[146:147], off
	v_lshl_add_u64 v[146:147], s[44:45], 0, v[130:131]
	s_add_i32 m0, s50, 0x2000
	s_nop 0
	global_load_lds_dwordx4 v[146:147], off
	v_lshl_add_u64 v[146:147], v[218:219], 0, s[12:13]
	s_mov_b32 m0, s60
	s_nop 0
	global_load_lds_dwordx4 v[146:147], off
	v_lshl_add_u64 v[146:147], v[220:221], 0, s[12:13]
	s_mov_b32 m0, s61
	s_nop 0
	global_load_lds_dwordx4 v[146:147], off
	s_waitcnt vmcnt(8)
	s_waitcnt lgkmcnt(0)
	s_barrier
	s_setprio 1
	v_mfma_f32_16x16x32_bf16 v[60:63], v[152:155], v[184:187], v[60:63]
	v_mfma_f32_16x16x32_bf16 v[56:59], v[160:163], v[184:187], v[56:59]
	v_mfma_f32_16x16x32_bf16 v[44:47], v[152:155], v[192:195], v[44:47]
	v_mfma_f32_16x16x32_bf16 v[40:43], v[160:163], v[192:195], v[40:43]
	v_mfma_f32_16x16x32_bf16 v[28:31], v[152:155], v[200:203], v[28:31]
	v_mfma_f32_16x16x32_bf16 v[24:27], v[160:163], v[200:203], v[24:27]
	v_mfma_f32_16x16x32_bf16 v[12:15], v[152:155], v[208:211], v[12:15]
	v_mfma_f32_16x16x32_bf16 v[8:11], v[160:163], v[208:211], v[8:11]
	v_mfma_f32_16x16x32_bf16 v[60:63], v[156:159], v[188:191], v[60:63]
	v_mfma_f32_16x16x32_bf16 v[56:59], v[164:167], v[188:191], v[56:59]
	v_mfma_f32_16x16x32_bf16 v[44:47], v[156:159], v[196:199], v[44:47]
	v_mfma_f32_16x16x32_bf16 v[40:43], v[164:167], v[196:199], v[40:43]
	v_mfma_f32_16x16x32_bf16 v[28:31], v[156:159], v[204:207], v[28:31]
	v_mfma_f32_16x16x32_bf16 v[24:27], v[164:167], v[204:207], v[24:27]
	v_mfma_f32_16x16x32_bf16 v[12:15], v[156:159], v[212:215], v[12:15]
	v_mfma_f32_16x16x32_bf16 v[8:11], v[164:167], v[212:215], v[8:11]
	v_mfma_f32_16x16x32_bf16 v[52:55], v[168:171], v[184:187], v[52:55]
	v_mfma_f32_16x16x32_bf16 v[48:51], v[176:179], v[184:187], v[48:51]
	v_mfma_f32_16x16x32_bf16 v[36:39], v[168:171], v[192:195], v[36:39]
	v_mfma_f32_16x16x32_bf16 v[32:35], v[176:179], v[192:195], v[32:35]
	v_mfma_f32_16x16x32_bf16 v[20:23], v[168:171], v[200:203], v[20:23]
	v_mfma_f32_16x16x32_bf16 v[16:19], v[176:179], v[200:203], v[16:19]
	v_mfma_f32_16x16x32_bf16 v[4:7], v[168:171], v[208:211], v[4:7]
	v_mfma_f32_16x16x32_bf16 v[0:3], v[176:179], v[208:211], v[0:3]
	v_mfma_f32_16x16x32_bf16 v[52:55], v[172:175], v[188:191], v[52:55]
	v_mfma_f32_16x16x32_bf16 v[48:51], v[180:183], v[188:191], v[48:51]
	v_mfma_f32_16x16x32_bf16 v[36:39], v[172:175], v[196:199], v[36:39]
	v_mfma_f32_16x16x32_bf16 v[32:35], v[180:183], v[196:199], v[32:35]
	v_mfma_f32_16x16x32_bf16 v[20:23], v[172:175], v[204:207], v[20:23]
	v_mfma_f32_16x16x32_bf16 v[16:19], v[180:183], v[204:207], v[16:19]
	v_mfma_f32_16x16x32_bf16 v[4:7], v[172:175], v[212:215], v[4:7]
	v_mfma_f32_16x16x32_bf16 v[0:3], v[180:183], v[212:215], v[0:3]
	s_setprio 0
	s_barrier
	s_add_i32 s75, s75, 2
	s_add_u32 s34, s34, 0x100
	s_addc_u32 s35, s35, 0
	s_add_u32 s73, s73, 0x100
	s_addc_u32 s74, s74, 0
	s_cmp_gt_u32 s75, 13
	s_cbranch_scc0 .LBB0_263
	s_and_b64 vcc, exec, s[18:19]
	s_cbranch_vccz .LBB0_266
	s_barrier

; #define PG8_STAGE(bufoff, gbase, voff) do { _Pragma("unroll") for (int _i = 0; _i < 2; ++_i) \
;         __builtin_amdgcn_global_load_lds((const unsigned*)((const char*)(gbase) + (voff)[_i]), (LAS unsigned*)(lds + (bufoff) + ldsw + _i * 8192), 16, 0, 0); } while (0)
; #define PG8_LDA(dst, b, h) do { _Pragma("unroll") for (int m = 0; m < 4; ++m) _Pragma("unroll") for (int k = 0; k < 2; ++k) dst[m][k] = *(const LAS bf16x8*)(lds + PG8_SA(b, h) + aoff + m * 2048 + k * 1024); } while (0)
; #define PG8_LDB(dst, b, h) do { _Pragma("unroll") for (int n = 0; n < 2; ++n) _Pragma("unroll") for (int k = 0; k < 2; ++k) dst[n][k] = *(const LAS bf16x8*)(lds + PG8_SB(b, h) + boff + n * 2048 + k * 1024); } while (0)
; #define PG8_MMA(ai, bj, At, Bt) do { __builtin_amdgcn_s_setprio(1); _Pragma("unroll") for (int m = 0; m < 4; ++m) _Pragma("unroll") for (int n = 0; n < 2; ++n) _Pragma("unroll") for (int k = 0; k < 2; ++k) \
;         acc[ai][bj][m][n] = __builtin_amdgcn_mfma_f32_16x16x32_bf16(Bt[n][k], At[m][k], acc[ai][bj][m][n], 0, 0, 0); __builtin_amdgcn_s_setprio(0); } while (0)
; #define PG8_WAIT_V(n) asm volatile("s_waitcnt vmcnt(" #n ")" ::: "memory")
; #define PG8_WAIT_L(n) asm volatile("s_waitcnt lgkmcnt(" #n ")" ::: "memory")
; #define PG8_BAR __builtin_amdgcn_s_barrier()
; #define PG8_SCHED __builtin_amdgcn_sched_barrier(0)
; template <class Epi, bool SP2 = false>
; __device__ __forceinline__ void gemm_phase(LAS unsigned char* lds, const Gemm g, const StaticOrder& S, const Epi& E) {
;     ...
;             const bool last = (t == nt - 2);
;             const char* a1 = cA + (size_t)(t + 1) * kstep;
;             const char* a2 = last ? nA : cA + (size_t)(t + 2) * kstep; const char* b2 = last ? nB : cB + (size_t)(t + 2) * kstep;
;             const char* a3 = a2 + kstep; const char* b3 = b2 + kstep;
;             if constexpr (SP2) {
;             PG8_LDB(B0, 0, 0); PG8_LDB(B1, 0, 1); PG8_SCHED; PG8_LDA(At, 0, 0); PG8_STAGE(PG8_SA(1, 1), a1 + hstepA, voffA);
;             PG8_WAIT_V(8); PG8_WAIT_L(0); PG8_BAR; PG8_MMA(0, 0, At, B0); PG8_MMA(0, 1, At, B1); PG8_BAR; PG8_SCHED;
;             PG8_LDA(At, 0, 1); PG8_STAGE(PG8_SB(0, 0), b2, voffB); PG8_STAGE(PG8_SB(0, 1), b2 + hstepB, voffB); PG8_STAGE(PG8_SA(0, 0), a2, voffA);
;             PG8_WAIT_V(8); PG8_WAIT_L(0); PG8_BAR; PG8_MMA(1, 0, At, B0); PG8_MMA(1, 1, At, B1); PG8_BAR; PG8_SCHED;
.LBB0_334:
	ds_read_b128 v[150:153], v147
	ds_read_b128 v[154:157], v147 offset:1024
	ds_read_b128 v[158:161], v147 offset:2048
	ds_read_b128 v[162:165], v147 offset:3072
	ds_read_b128 v[166:169], v148
	ds_read_b128 v[170:173], v148 offset:1024
	ds_read_b128 v[174:177], v148 offset:2048
	ds_read_b128 v[178:181], v148 offset:3072
	s_add_u32 s52, s34, 0xfff50080
	s_addc_u32 s53, s35, -1
	s_cmp_eq_u32 s86, 40
	s_cselect_b32 s55, s5, s53
	s_cselect_b32 s54, s4, s52
	s_cselect_b32 s53, s51, s85
	s_cselect_b32 s52, s50, s84
	v_lshl_add_u64 v[214:215], s[34:35], 0, v[138:139]
	s_add_i32 m0, s59, 0xc000
	ds_read_b128 v[182:185], v149
	ds_read_b128 v[186:189], v149 offset:1024
	ds_read_b128 v[190:193], v149 offset:2048
	ds_read_b128 v[194:197], v149 offset:3072
	ds_read_b128 v[198:201], v149 offset:4096
	ds_read_b128 v[202:205], v149 offset:5120
	ds_read_b128 v[206:209], v149 offset:6144
	ds_read_b128 v[210:213], v149 offset:7168
	global_load_lds_dwordx4 v[214:215], off
	v_lshl_add_u64 v[214:215], s[34:35], 0, v[140:141]
	s_add_i32 m0, s59, 0xe000
	s_nop 0
	global_load_lds_dwordx4 v[214:215], off
	s_waitcnt vmcnt(8)
	s_waitcnt lgkmcnt(0)
	s_barrier
	s_setprio 1
	v_mfma_f32_16x16x32_bf16 v[124:127], v[150:153], v[182:185], v[124:127]
	v_mfma_f32_16x16x32_bf16 v[120:123], v[158:161], v[182:185], v[120:123]
	v_mfma_f32_16x16x32_bf16 v[116:119], v[150:153], v[190:193], v[116:119]
	v_mfma_f32_16x16x32_bf16 v[112:115], v[158:161], v[190:193], v[112:115]
	v_mfma_f32_16x16x32_bf16 v[100:103], v[150:153], v[198:201], v[100:103]
	v_mfma_f32_16x16x32_bf16 v[96:99], v[158:161], v[198:201], v[96:99]
	v_mfma_f32_16x16x32_bf16 v[84:87], v[150:153], v[206:209], v[84:87]
	v_mfma_f32_16x16x32_bf16 v[80:83], v[158:161], v[206:209], v[80:83]
	v_mfma_f32_16x16x32_bf16 v[124:127], v[154:157], v[186:189], v[124:127]
	v_mfma_f32_16x16x32_bf16 v[120:123], v[162:165], v[186:189], v[120:123]
	v_mfma_f32_16x16x32_bf16 v[116:119], v[154:157], v[194:197], v[116:119]
	v_mfma_f32_16x16x32_bf16 v[112:115], v[162:165], v[194:197], v[112:115]
	v_mfma_f32_16x16x32_bf16 v[100:103], v[154:157], v[202:205], v[100:103]
	v_mfma_f32_16x16x32_bf16 v[96:99], v[162:165], v[202:205], v[96:99]
	v_mfma_f32_16x16x32_bf16 v[84:87], v[154:157], v[210:213], v[84:87]
	v_mfma_f32_16x16x32_bf16 v[80:83], v[162:165], v[210:213], v[80:83]
	v_mfma_f32_16x16x32_bf16 v[108:111], v[166:169], v[182:185], v[108:111]
	v_mfma_f32_16x16x32_bf16 v[104:107], v[174:177], v[182:185], v[104:107]
	v_mfma_f32_16x16x32_bf16 v[92:95], v[166:169], v[190:193], v[92:95]
	v_mfma_f32_16x16x32_bf16 v[88:91], v[174:177], v[190:193], v[88:91]
	v_mfma_f32_16x16x32_bf16 v[76:79], v[166:169], v[198:201], v[76:79]
	v_mfma_f32_16x16x32_bf16 v[72:75], v[174:177], v[198:201], v[72:75]
	v_mfma_f32_16x16x32_bf16 v[68:71], v[166:169], v[206:209], v[68:71]
	v_mfma_f32_16x16x32_bf16 v[64:67], v[174:177], v[206:209], v[64:67]
	v_mfma_f32_16x16x32_bf16 v[108:111], v[170:173], v[186:189], v[108:111]
	v_mfma_f32_16x16x32_bf16 v[104:107], v[178:181], v[186:189], v[104:107]
	v_mfma_f32_16x16x32_bf16 v[92:95], v[170:173], v[194:197], v[92:95]
	v_mfma_f32_16x16x32_bf16 v[88:91], v[178:181], v[194:197], v[88:91]
	v_mfma_f32_16x16x32_bf16 v[76:79], v[170:173], v[202:205], v[76:79]
	v_mfma_f32_16x16x32_bf16 v[72:75], v[178:181], v[202:205], v[72:75]
	v_mfma_f32_16x16x32_bf16 v[68:71], v[170:173], v[210:213], v[68:71]
	v_mfma_f32_16x16x32_bf16 v[64:67], v[178:181], v[210:213], v[64:67]
	s_setprio 0
	s_barrier
	s_add_i32 s68, s74, s56
	v_lshl_add_u64 v[214:215], s[52:53], 0, v[134:135]
	s_mov_b32 m0, s68
	ds_read_b128 v[182:185], v149 offset:16384
	ds_read_b128 v[186:189], v149 offset:17408
	ds_read_b128 v[190:193], v149 offset:18432
	ds_read_b128 v[194:197], v149 offset:19456
	ds_read_b128 v[198:201], v149 offset:20480
	ds_read_b128 v[202:205], v149 offset:21504
	ds_read_b128 v[206:209], v149 offset:22528
	ds_read_b128 v[210:213], v149 offset:23552
	global_load_lds_dwordx4 v[214:215], off
	s_add_i32 m0, s68, 0x2000
	s_add_u32 s68, s52, 0xb0000
	v_lshl_add_u64 v[216:217], s[52:53], 0, v[130:131]
	s_addc_u32 s69, s53, 0
	s_add_i32 s70, s75, s56
	global_load_lds_dwordx4 v[216:217], off
	v_lshl_add_u64 v[218:219], s[68:69], 0, v[134:135]
	s_mov_b32 m0, s70
	v_lshl_add_u64 v[220:221], s[54:55], 0, v[132:133]
	global_load_lds_dwordx4 v[218:219], off
	v_lshl_add_u64 v[218:219], s[68:69], 0, v[130:131]
	s_add_i32 m0, s70, 0x2000
	s_nop 0
	global_load_lds_dwordx4 v[218:219], off
	v_lshl_add_u64 v[218:219], s[54:55], 0, v[136:137]
	s_mov_b32 m0, s59
	s_nop 0
	global_load_lds_dwordx4 v[218:219], off
	s_mov_b32 m0, s60
	s_nop 0
	global_load_lds_dwordx4 v[220:221], off
	s_waitcnt vmcnt(8)
	s_waitcnt lgkmcnt(0)
	s_barrier
; #define PG8_STAGE(bufoff, gbase, voff) do { _Pragma("unroll") for (int _i = 0; _i < 2; ++_i) \
;         __builtin_amdgcn_global_load_lds((const unsigned*)((const char*)(gbase) + (voff)[_i]), (LAS unsigned*)(lds + (bufoff) + ldsw + _i * 8192), 16, 0, 0); } while (0)
; #define PG8_LDA(dst, b, h) do { _Pragma("unroll") for (int m = 0; m < 4; ++m) _Pragma("unroll") for (int k = 0; k < 2; ++k) dst[m][k] = *(const LAS bf16x8*)(lds + PG8_SA(b, h) + aoff + m * 2048 + k * 1024); } while (0)
; #define PG8_LDB(dst, b, h) do { _Pragma("unroll") for (int n = 0; n < 2; ++n) _Pragma("unroll") for (int k = 0; k < 2; ++k) dst[n][k] = *(const LAS bf16x8*)(lds + PG8_SB(b, h) + boff + n * 2048 + k * 1024); } while (0)
; #define PG8_MMA(ai, bj, At, Bt) do { __builtin_amdgcn_s_setprio(1); _Pragma("unroll") for (int m = 0; m < 4; ++m) _Pragma("unroll") for (int n = 0; n < 2; ++n) _Pragma("unroll") for (int k = 0; k < 2; ++k) \
;         acc[ai][bj][m][n] = __builtin_amdgcn_mfma_f32_16x16x32_bf16(Bt[n][k], At[m][k], acc[ai][bj][m][n], 0, 0, 0); __builtin_amdgcn_s_setprio(0); } while (0)
; #define PG8_WAIT_V(n) asm volatile("s_waitcnt vmcnt(" #n ")" ::: "memory")
; #define PG8_WAIT_L(n) asm volatile("s_waitcnt lgkmcnt(" #n ")" ::: "memory")
; #define PG8_BAR __builtin_amdgcn_s_barrier()
; #define PG8_SCHED __builtin_amdgcn_sched_barrier(0)
; template <class Epi, bool SP2 = false>
; __device__ __forceinline__ void gemm_phase(LAS unsigned char* lds, const Gemm g, const StaticOrder& S, const Epi& E) {
;     ...
;             PG8_WAIT_V(8); PG8_WAIT_L(0); PG8_BAR; PG8_MMA(1, 0, At, B0); PG8_MMA(1, 1, At, B1); PG8_BAR; PG8_SCHED;
;             PG8_LDB(B0, 1, 0); PG8_LDB(B1, 1, 1); PG8_SCHED; PG8_LDA(At, 1, 0); PG8_STAGE(PG8_SA(0, 1), a2 + hstepA, voffA);
;             PG8_WAIT_V(8); PG8_WAIT_L(0); PG8_BAR; PG8_MMA(0, 0, At, B0); PG8_MMA(0, 1, At, B1); PG8_BAR; PG8_SCHED;
	s_setprio 1
	v_mfma_f32_16x16x32_bf16 v[60:63], v[150:153], v[182:185], v[60:63]
	v_mfma_f32_16x16x32_bf16 v[56:59], v[158:161], v[182:185], v[56:59]
	v_mfma_f32_16x16x32_bf16 v[52:55], v[150:153], v[190:193], v[52:55]
	v_mfma_f32_16x16x32_bf16 v[48:51], v[158:161], v[190:193], v[48:51]
	v_mfma_f32_16x16x32_bf16 v[36:39], v[150:153], v[198:201], v[36:39]
	v_mfma_f32_16x16x32_bf16 v[32:35], v[158:161], v[198:201], v[32:35]
	v_mfma_f32_16x16x32_bf16 v[20:23], v[150:153], v[206:209], v[20:23]
	v_mfma_f32_16x16x32_bf16 v[16:19], v[158:161], v[206:209], v[16:19]
	v_mfma_f32_16x16x32_bf16 v[60:63], v[154:157], v[186:189], v[60:63]
	v_mfma_f32_16x16x32_bf16 v[56:59], v[162:165], v[186:189], v[56:59]
	v_mfma_f32_16x16x32_bf16 v[52:55], v[154:157], v[194:197], v[52:55]
	v_mfma_f32_16x16x32_bf16 v[48:51], v[162:165], v[194:197], v[48:51]
	v_mfma_f32_16x16x32_bf16 v[36:39], v[154:157], v[202:205], v[36:39]
	v_mfma_f32_16x16x32_bf16 v[32:35], v[162:165], v[202:205], v[32:35]
	v_mfma_f32_16x16x32_bf16 v[20:23], v[154:157], v[210:213], v[20:23]
	v_mfma_f32_16x16x32_bf16 v[16:19], v[162:165], v[210:213], v[16:19]
	v_mfma_f32_16x16x32_bf16 v[44:47], v[166:169], v[182:185], v[44:47]
	v_mfma_f32_16x16x32_bf16 v[40:43], v[174:177], v[182:185], v[40:43]
	v_mfma_f32_16x16x32_bf16 v[28:31], v[166:169], v[190:193], v[28:31]
	v_mfma_f32_16x16x32_bf16 v[24:27], v[174:177], v[190:193], v[24:27]
	v_mfma_f32_16x16x32_bf16 v[12:15], v[166:169], v[198:201], v[12:15]
	v_mfma_f32_16x16x32_bf16 v[8:11], v[174:177], v[198:201], v[8:11]
	v_mfma_f32_16x16x32_bf16 v[4:7], v[166:169], v[206:209], v[4:7]
	v_mfma_f32_16x16x32_bf16 v[0:3], v[174:177], v[206:209], v[0:3]
	v_mfma_f32_16x16x32_bf16 v[44:47], v[170:173], v[186:189], v[44:47]
	v_mfma_f32_16x16x32_bf16 v[40:43], v[178:181], v[186:189], v[40:43]
	v_mfma_f32_16x16x32_bf16 v[28:31], v[170:173], v[194:197], v[28:31]
	v_mfma_f32_16x16x32_bf16 v[24:27], v[178:181], v[194:197], v[24:27]
	v_mfma_f32_16x16x32_bf16 v[12:15], v[170:173], v[202:205], v[12:15]
	v_mfma_f32_16x16x32_bf16 v[8:11], v[178:181], v[202:205], v[8:11]
	v_mfma_f32_16x16x32_bf16 v[4:7], v[170:173], v[210:213], v[4:7]
	v_mfma_f32_16x16x32_bf16 v[0:3], v[178:181], v[210:213], v[0:3]
	s_setprio 0
	s_barrier
	s_add_i32 s68, 0, 0x18000
	s_add_i32 s69, 0, 0x1c000
	v_add_u32_e32 v162, s68, v146
	v_add_u32_e32 v178, s69, v146
	ds_read_b128 v[150:153], v162
	ds_read_b128 v[154:157], v162 offset:1024
	ds_read_b128 v[158:161], v162 offset:2048
	ds_read_b128 v[162:165], v162 offset:3072
	ds_read_b128 v[166:169], v178
	ds_read_b128 v[170:173], v178 offset:1024
	ds_read_b128 v[174:177], v178 offset:2048
	ds_read_b128 v[178:181], v178 offset:3072
	s_add_u32 s54, s54, 0xb0000
	s_addc_u32 s55, s55, 0
	s_mov_b32 m0, s61
	v_lshl_add_u64 v[222:223], s[54:55], 0, v[136:137]
	ds_read_b128 v[182:185], v149 offset:32768
	ds_read_b128 v[186:189], v149 offset:33792
	ds_read_b128 v[190:193], v149 offset:34816
	ds_read_b128 v[194:197], v149 offset:35840
	ds_read_b128 v[198:201], v149 offset:36864
	ds_read_b128 v[202:205], v149 offset:37888
	ds_read_b128 v[206:209], v149 offset:38912
	ds_read_b128 v[210:213], v149 offset:39936
	global_load_lds_dwordx4 v[222:223], off
	v_lshl_add_u64 v[222:223], s[54:55], 0, v[132:133]
	s_mov_b32 m0, s62
	s_nop 0
	global_load_lds_dwordx4 v[222:223], off
	s_waitcnt vmcnt(8)
	s_waitcnt lgkmcnt(0)
	s_barrier
	s_setprio 1
	v_mfma_f32_16x16x32_bf16 v[124:127], v[150:153], v[182:185], v[124:127]
	v_mfma_f32_16x16x32_bf16 v[120:123], v[158:161], v[182:185], v[120:123]
	v_mfma_f32_16x16x32_bf16 v[116:119], v[150:153], v[190:193], v[116:119]
	v_mfma_f32_16x16x32_bf16 v[112:115], v[158:161], v[190:193], v[112:115]
	v_mfma_f32_16x16x32_bf16 v[100:103], v[150:153], v[198:201], v[100:103]
	v_mfma_f32_16x16x32_bf16 v[96:99], v[158:161], v[198:201], v[96:99]
	v_mfma_f32_16x16x32_bf16 v[84:87], v[150:153], v[206:209], v[84:87]
	v_mfma_f32_16x16x32_bf16 v[80:83], v[158:161], v[206:209], v[80:83]
	v_mfma_f32_16x16x32_bf16 v[124:127], v[154:157], v[186:189], v[124:127]
	v_mfma_f32_16x16x32_bf16 v[120:123], v[162:165], v[186:189], v[120:123]
	v_mfma_f32_16x16x32_bf16 v[116:119], v[154:157], v[194:197], v[116:119]
	v_mfma_f32_16x16x32_bf16 v[112:115], v[162:165], v[194:197], v[112:115]
	v_mfma_f32_16x16x32_bf16 v[100:103], v[154:157], v[202:205], v[100:103]
	v_mfma_f32_16x16x32_bf16 v[96:99], v[162:165], v[202:205], v[96:99]
	v_mfma_f32_16x16x32_bf16 v[84:87], v[154:157], v[210:213], v[84:87]
	v_mfma_f32_16x16x32_bf16 v[80:83], v[162:165], v[210:213], v[80:83]
	v_mfma_f32_16x16x32_bf16 v[108:111], v[166:169], v[182:185], v[108:111]
	v_mfma_f32_16x16x32_bf16 v[104:107], v[174:177], v[182:185], v[104:107]
	v_mfma_f32_16x16x32_bf16 v[92:95], v[166:169], v[190:193], v[92:95]
	v_mfma_f32_16x16x32_bf16 v[88:91], v[174:177], v[190:193], v[88:91]
	v_mfma_f32_16x16x32_bf16 v[76:79], v[166:169], v[198:201], v[76:79]
	v_mfma_f32_16x16x32_bf16 v[72:75], v[174:177], v[198:201], v[72:75]
	v_mfma_f32_16x16x32_bf16 v[68:71], v[166:169], v[206:209], v[68:71]
	v_mfma_f32_16x16x32_bf16 v[64:67], v[174:177], v[206:209], v[64:67]
	v_mfma_f32_16x16x32_bf16 v[108:111], v[170:173], v[186:189], v[108:111]
	v_mfma_f32_16x16x32_bf16 v[104:107], v[178:181], v[186:189], v[104:107]
	v_mfma_f32_16x16x32_bf16 v[92:95], v[170:173], v[194:197], v[92:95]
	v_mfma_f32_16x16x32_bf16 v[88:91], v[178:181], v[194:197], v[88:91]
	v_mfma_f32_16x16x32_bf16 v[76:79], v[170:173], v[202:205], v[76:79]
	v_mfma_f32_16x16x32_bf16 v[72:75], v[178:181], v[202:205], v[72:75]
	v_mfma_f32_16x16x32_bf16 v[68:71], v[170:173], v[210:213], v[68:71]
	v_mfma_f32_16x16x32_bf16 v[64:67], v[178:181], v[210:213], v[64:67]
	s_setprio 0
	s_barrier
; #define PG8_STAGE(bufoff, gbase, voff) do { _Pragma("unroll") for (int _i = 0; _i < 2; ++_i) \
;         __builtin_amdgcn_global_load_lds((const unsigned*)((const char*)(gbase) + (voff)[_i]), (LAS unsigned*)(lds + (bufoff) + ldsw + _i * 8192), 16, 0, 0); } while (0)
; #define PG8_LDA(dst, b, h) do { _Pragma("unroll") for (int m = 0; m < 4; ++m) _Pragma("unroll") for (int k = 0; k < 2; ++k) dst[m][k] = *(const LAS bf16x8*)(lds + PG8_SA(b, h) + aoff + m * 2048 + k * 1024); } while (0)
; #define PG8_MMA(ai, bj, At, Bt) do { __builtin_amdgcn_s_setprio(1); _Pragma("unroll") for (int m = 0; m < 4; ++m) _Pragma("unroll") for (int n = 0; n < 2; ++n) _Pragma("unroll") for (int k = 0; k < 2; ++k) \
;         acc[ai][bj][m][n] = __builtin_amdgcn_mfma_f32_16x16x32_bf16(Bt[n][k], At[m][k], acc[ai][bj][m][n], 0, 0, 0); __builtin_amdgcn_s_setprio(0); } while (0)
; #define PG8_WAIT_V(n) asm volatile("s_waitcnt vmcnt(" #n ")" ::: "memory")
; #define PG8_WAIT_L(n) asm volatile("s_waitcnt lgkmcnt(" #n ")" ::: "memory")
; #define PG8_BAR __builtin_amdgcn_s_barrier()
; #define PG8_SCHED __builtin_amdgcn_sched_barrier(0)
; template <class Epi, bool SP2 = false>
; __device__ __forceinline__ void gemm_phase(LAS unsigned char* lds, const Gemm g, const StaticOrder& S, const Epi& E) {
;     ...
;             PG8_LDA(At, 1, 1); PG8_STAGE(PG8_SB(1, 0), b3, voffB); PG8_STAGE(PG8_SB(1, 1), b3 + hstepB, voffB); PG8_STAGE(PG8_SA(1, 0), a3, voffA);
;             PG8_WAIT_V(8); PG8_WAIT_L(0); PG8_BAR; PG8_MMA(1, 0, At, B0); PG8_MMA(1, 1, At, B1); PG8_BAR; PG8_SCHED;
;     ...
;         if constexpr (SP2) { if (wr == 0) PG8_BAR; }
	s_add_i32 s54, s68, s56
	v_lshl_add_u64 v[214:215], v[214:215], 0, s[24:25]
	s_mov_b32 m0, s54
	ds_read_b128 v[182:185], v149 offset:49152
	ds_read_b128 v[186:189], v149 offset:50176
	ds_read_b128 v[190:193], v149 offset:51200
	ds_read_b128 v[194:197], v149 offset:52224
	ds_read_b128 v[198:201], v149 offset:53248
	ds_read_b128 v[202:205], v149 offset:54272
	ds_read_b128 v[206:209], v149 offset:55296
	ds_read_b128 v[210:213], v149 offset:56320
	global_load_lds_dwordx4 v[214:215], off
	s_add_i32 m0, s54, 0x2000
	s_add_u32 s52, s52, 0xb0080
	v_lshl_add_u64 v[214:215], v[216:217], 0, s[24:25]
	s_addc_u32 s53, s53, 0
	s_add_i32 s54, s69, s56
	global_load_lds_dwordx4 v[214:215], off
	v_lshl_add_u64 v[214:215], s[52:53], 0, v[134:135]
	s_mov_b32 m0, s54
	s_nop 0
	global_load_lds_dwordx4 v[214:215], off
	v_lshl_add_u64 v[214:215], s[52:53], 0, v[130:131]
	s_add_i32 m0, s54, 0x2000
	s_nop 0
	global_load_lds_dwordx4 v[214:215], off
	v_lshl_add_u64 v[214:215], v[218:219], 0, s[24:25]
	s_mov_b32 m0, s66
	s_nop 0
	global_load_lds_dwordx4 v[214:215], off
	v_lshl_add_u64 v[214:215], v[220:221], 0, s[24:25]
	s_mov_b32 m0, s67
	s_nop 0
	global_load_lds_dwordx4 v[214:215], off
	s_waitcnt vmcnt(8)
	s_waitcnt lgkmcnt(0)
	s_barrier
	s_setprio 1
	v_mfma_f32_16x16x32_bf16 v[60:63], v[150:153], v[182:185], v[60:63]
	v_mfma_f32_16x16x32_bf16 v[56:59], v[158:161], v[182:185], v[56:59]
	v_mfma_f32_16x16x32_bf16 v[52:55], v[150:153], v[190:193], v[52:55]
	v_mfma_f32_16x16x32_bf16 v[48:51], v[158:161], v[190:193], v[48:51]
	v_mfma_f32_16x16x32_bf16 v[36:39], v[150:153], v[198:201], v[36:39]
	v_mfma_f32_16x16x32_bf16 v[32:35], v[158:161], v[198:201], v[32:35]
	v_mfma_f32_16x16x32_bf16 v[20:23], v[150:153], v[206:209], v[20:23]
	v_mfma_f32_16x16x32_bf16 v[16:19], v[158:161], v[206:209], v[16:19]
	v_mfma_f32_16x16x32_bf16 v[60:63], v[154:157], v[186:189], v[60:63]
	v_mfma_f32_16x16x32_bf16 v[56:59], v[162:165], v[186:189], v[56:59]
	v_mfma_f32_16x16x32_bf16 v[52:55], v[154:157], v[194:197], v[52:55]
	v_mfma_f32_16x16x32_bf16 v[48:51], v[162:165], v[194:197], v[48:51]
	v_mfma_f32_16x16x32_bf16 v[36:39], v[154:157], v[202:205], v[36:39]
	v_mfma_f32_16x16x32_bf16 v[32:35], v[162:165], v[202:205], v[32:35]
	v_mfma_f32_16x16x32_bf16 v[20:23], v[154:157], v[210:213], v[20:23]
	v_mfma_f32_16x16x32_bf16 v[16:19], v[162:165], v[210:213], v[16:19]
	v_mfma_f32_16x16x32_bf16 v[44:47], v[166:169], v[182:185], v[44:47]
	v_mfma_f32_16x16x32_bf16 v[40:43], v[174:177], v[182:185], v[40:43]
	v_mfma_f32_16x16x32_bf16 v[28:31], v[166:169], v[190:193], v[28:31]
	v_mfma_f32_16x16x32_bf16 v[24:27], v[174:177], v[190:193], v[24:27]
	v_mfma_f32_16x16x32_bf16 v[12:15], v[166:169], v[198:201], v[12:15]
	v_mfma_f32_16x16x32_bf16 v[8:11], v[174:177], v[198:201], v[8:11]
	v_mfma_f32_16x16x32_bf16 v[4:7], v[166:169], v[206:209], v[4:7]
	v_mfma_f32_16x16x32_bf16 v[0:3], v[174:177], v[206:209], v[0:3]
	v_mfma_f32_16x16x32_bf16 v[44:47], v[170:173], v[186:189], v[44:47]
	v_mfma_f32_16x16x32_bf16 v[40:43], v[178:181], v[186:189], v[40:43]
	v_mfma_f32_16x16x32_bf16 v[28:31], v[170:173], v[194:197], v[28:31]
	v_mfma_f32_16x16x32_bf16 v[24:27], v[178:181], v[194:197], v[24:27]
	v_mfma_f32_16x16x32_bf16 v[12:15], v[170:173], v[202:205], v[12:15]
	v_mfma_f32_16x16x32_bf16 v[8:11], v[178:181], v[202:205], v[8:11]
	v_mfma_f32_16x16x32_bf16 v[4:7], v[170:173], v[210:213], v[4:7]
	v_mfma_f32_16x16x32_bf16 v[0:3], v[178:181], v[210:213], v[0:3]
	s_setprio 0
	s_barrier
	s_add_i32 s86, s86, 2
	s_add_u32 s34, s34, 0x100
	s_addc_u32 s35, s35, 0
	s_add_u32 s84, s84, 0x100
	s_addc_u32 s85, s85, 0
	s_cmp_gt_u32 s86, 41
	s_cbranch_scc0 .LBB0_334
	s_and_b64 vcc, exec, s[26:27]
	s_cbranch_vccz .LBB0_337
	s_barrier

; #define PG8_STAGE(bufoff, gbase, voff) do { _Pragma("unroll") for (int _i = 0; _i < 2; ++_i) \
;         __builtin_amdgcn_global_load_lds((const unsigned*)((const char*)(gbase) + (voff)[_i]), (LAS unsigned*)(lds + (bufoff) + ldsw + _i * 8192), 16, 0, 0); } while (0)
; #define PG8_LDA(dst, b, h) do { _Pragma("unroll") for (int m = 0; m < 4; ++m) _Pragma("unroll") for (int k = 0; k < 2; ++k) dst[m][k] = *(const LAS bf16x8*)(lds + PG8_SA(b, h) + aoff + m * 2048 + k * 1024); } while (0)
; #define PG8_LDB(dst, b, h) do { _Pragma("unroll") for (int n = 0; n < 2; ++n) _Pragma("unroll") for (int k = 0; k < 2; ++k) dst[n][k] = *(const LAS bf16x8*)(lds + PG8_SB(b, h) + boff + n * 2048 + k * 1024); } while (0)
; #define PG8_MMA(ai, bj, At, Bt) do { __builtin_amdgcn_s_setprio(1); _Pragma("unroll") for (int m = 0; m < 4; ++m) _Pragma("unroll") for (int n = 0; n < 2; ++n) _Pragma("unroll") for (int k = 0; k < 2; ++k) \
;         acc[ai][bj][m][n] = __builtin_amdgcn_mfma_f32_16x16x32_bf16(Bt[n][k], At[m][k], acc[ai][bj][m][n], 0, 0, 0); __builtin_amdgcn_s_setprio(0); } while (0)
; #define PG8_WAIT_V(n) asm volatile("s_waitcnt vmcnt(" #n ")" ::: "memory")
; #define PG8_WAIT_L(n) asm volatile("s_waitcnt lgkmcnt(" #n ")" ::: "memory")
; #define PG8_BAR __builtin_amdgcn_s_barrier()
; #define PG8_SCHED __builtin_amdgcn_sched_barrier(0)
; template <class Epi, bool SP2 = false>
; __device__ __forceinline__ void gemm_phase(LAS unsigned char* lds, const Gemm g, const StaticOrder& S, const Epi& E) {
;     ...
;             const bool last = (t == nt - 2);
;             const char* a1 = cA + (size_t)(t + 1) * kstep;
;             const char* a2 = last ? nA : cA + (size_t)(t + 2) * kstep; const char* b2 = last ? nB : cB + (size_t)(t + 2) * kstep;
;             const char* a3 = a2 + kstep; const char* b3 = b2 + kstep;
;             if constexpr (SP2) {
;             PG8_LDB(B0, 0, 0); PG8_LDB(B1, 0, 1); PG8_SCHED; PG8_LDA(At, 0, 0); PG8_STAGE(PG8_SA(1, 1), a1 + hstepA, voffA);
;             PG8_WAIT_V(8); PG8_WAIT_L(0); PG8_BAR; PG8_MMA(0, 0, At, B0); PG8_MMA(0, 1, At, B1); PG8_BAR; PG8_SCHED;
;             PG8_LDA(At, 0, 1); PG8_STAGE(PG8_SB(0, 0), b2, voffB); PG8_STAGE(PG8_SB(0, 1), b2 + hstepB, voffB); PG8_STAGE(PG8_SA(0, 0), a2, voffA);
;             PG8_WAIT_V(8); PG8_WAIT_L(0); PG8_BAR; PG8_MMA(1, 0, At, B0); PG8_MMA(1, 1, At, B1); PG8_BAR; PG8_SCHED;
.LBB0_462:
	ds_read_b128 v[146:149], v153
	ds_read_b128 v[156:159], v153 offset:1024
	ds_read_b128 v[160:163], v153 offset:2048
	ds_read_b128 v[164:167], v153 offset:3072
	ds_read_b128 v[168:171], v154
	ds_read_b128 v[172:175], v154 offset:1024
	ds_read_b128 v[176:179], v154 offset:2048
	ds_read_b128 v[180:183], v154 offset:3072
	s_add_u32 s44, s34, 0xfffc0080
	s_addc_u32 s45, s35, -1
	s_cmp_eq_u32 s74, 12
	s_cselect_b32 s51, s5, s45
	s_cselect_b32 s50, s27, s44
	s_cselect_b32 s45, s25, s73
	s_cselect_b32 s44, s33, s72
	v_lshl_add_u64 v[150:151], s[34:35], 0, v[138:139]
	s_add_i32 m0, s31, 0xc000
	ds_read_b128 v[184:187], v155
	ds_read_b128 v[188:191], v155 offset:1024
	ds_read_b128 v[192:195], v155 offset:2048
	ds_read_b128 v[196:199], v155 offset:3072
	ds_read_b128 v[200:203], v155 offset:4096
	ds_read_b128 v[204:207], v155 offset:5120
	ds_read_b128 v[208:211], v155 offset:6144
	ds_read_b128 v[212:215], v155 offset:7168
	global_load_lds_dwordx4 v[150:151], off
	v_lshl_add_u64 v[150:151], s[34:35], 0, v[140:141]
	s_add_i32 m0, s31, 0xe000
	s_nop 0
	global_load_lds_dwordx4 v[150:151], off
	s_waitcnt vmcnt(8)
	s_waitcnt lgkmcnt(0)
	s_barrier
	s_setprio 1
	v_mfma_f32_16x16x32_bf16 v[124:127], v[146:149], v[184:187], v[124:127]
	v_mfma_f32_16x16x32_bf16 v[120:123], v[160:163], v[184:187], v[120:123]
	v_mfma_f32_16x16x32_bf16 v[108:111], v[146:149], v[192:195], v[108:111]
	v_mfma_f32_16x16x32_bf16 v[104:107], v[160:163], v[192:195], v[104:107]
	v_mfma_f32_16x16x32_bf16 v[92:95], v[146:149], v[200:203], v[92:95]
	v_mfma_f32_16x16x32_bf16 v[88:91], v[160:163], v[200:203], v[88:91]
	v_mfma_f32_16x16x32_bf16 v[76:79], v[146:149], v[208:211], v[76:79]
	v_mfma_f32_16x16x32_bf16 v[72:75], v[160:163], v[208:211], v[72:75]
	v_mfma_f32_16x16x32_bf16 v[124:127], v[156:159], v[188:191], v[124:127]
	v_mfma_f32_16x16x32_bf16 v[120:123], v[164:167], v[188:191], v[120:123]
	v_mfma_f32_16x16x32_bf16 v[108:111], v[156:159], v[196:199], v[108:111]
	v_mfma_f32_16x16x32_bf16 v[104:107], v[164:167], v[196:199], v[104:107]
	v_mfma_f32_16x16x32_bf16 v[92:95], v[156:159], v[204:207], v[92:95]
	v_mfma_f32_16x16x32_bf16 v[88:91], v[164:167], v[204:207], v[88:91]
	v_mfma_f32_16x16x32_bf16 v[76:79], v[156:159], v[212:215], v[76:79]
	v_mfma_f32_16x16x32_bf16 v[72:75], v[164:167], v[212:215], v[72:75]
	v_mfma_f32_16x16x32_bf16 v[116:119], v[168:171], v[184:187], v[116:119]
	v_mfma_f32_16x16x32_bf16 v[112:115], v[176:179], v[184:187], v[112:115]
	v_mfma_f32_16x16x32_bf16 v[100:103], v[168:171], v[192:195], v[100:103]
	v_mfma_f32_16x16x32_bf16 v[96:99], v[176:179], v[192:195], v[96:99]
	v_mfma_f32_16x16x32_bf16 v[84:87], v[168:171], v[200:203], v[84:87]
	v_mfma_f32_16x16x32_bf16 v[80:83], v[176:179], v[200:203], v[80:83]
	v_mfma_f32_16x16x32_bf16 v[68:71], v[168:171], v[208:211], v[68:71]
	v_mfma_f32_16x16x32_bf16 v[64:67], v[176:179], v[208:211], v[64:67]
	v_mfma_f32_16x16x32_bf16 v[116:119], v[172:175], v[188:191], v[116:119]
	v_mfma_f32_16x16x32_bf16 v[112:115], v[180:183], v[188:191], v[112:115]
	v_mfma_f32_16x16x32_bf16 v[100:103], v[172:175], v[196:199], v[100:103]
	v_mfma_f32_16x16x32_bf16 v[96:99], v[180:183], v[196:199], v[96:99]
	v_mfma_f32_16x16x32_bf16 v[84:87], v[172:175], v[204:207], v[84:87]
	v_mfma_f32_16x16x32_bf16 v[80:83], v[180:183], v[204:207], v[80:83]
	v_mfma_f32_16x16x32_bf16 v[68:71], v[172:175], v[212:215], v[68:71]
	v_mfma_f32_16x16x32_bf16 v[64:67], v[180:183], v[212:215], v[64:67]
	s_setprio 0
	s_barrier
	s_add_i32 s68, s66, s53
	v_lshl_add_u64 v[150:151], s[44:45], 0, v[132:133]
	s_mov_b32 m0, s68
	ds_read_b128 v[184:187], v155 offset:16384
	ds_read_b128 v[188:191], v155 offset:17408
	ds_read_b128 v[192:195], v155 offset:18432
	ds_read_b128 v[196:199], v155 offset:19456
	ds_read_b128 v[200:203], v155 offset:20480
	ds_read_b128 v[204:207], v155 offset:21504
	ds_read_b128 v[208:211], v155 offset:22528
	ds_read_b128 v[212:215], v155 offset:23552
	global_load_lds_dwordx4 v[150:151], off
	s_add_i32 m0, s68, 0x2000
	s_add_u32 s68, s44, 0x40000
	v_lshl_add_u64 v[216:217], s[44:45], 0, v[136:137]
	s_addc_u32 s69, s45, 0
	s_add_i32 s70, s67, s53
	global_load_lds_dwordx4 v[216:217], off
	v_lshl_add_u64 v[218:219], s[68:69], 0, v[132:133]
	s_mov_b32 m0, s70
	v_lshl_add_u64 v[220:221], s[50:51], 0, v[134:135]
	global_load_lds_dwordx4 v[218:219], off
	v_lshl_add_u64 v[218:219], s[68:69], 0, v[136:137]
	s_add_i32 m0, s70, 0x2000
	s_nop 0
	global_load_lds_dwordx4 v[218:219], off
	v_lshl_add_u64 v[218:219], s[50:51], 0, v[130:131]
	s_mov_b32 m0, s31
	s_nop 0
	global_load_lds_dwordx4 v[218:219], off
	s_mov_b32 m0, s54
	s_nop 0
	global_load_lds_dwordx4 v[220:221], off
	s_waitcnt vmcnt(8)
	s_waitcnt lgkmcnt(0)
	s_barrier
; #define PG8_STAGE(bufoff, gbase, voff) do { _Pragma("unroll") for (int _i = 0; _i < 2; ++_i) \
;         __builtin_amdgcn_global_load_lds((const unsigned*)((const char*)(gbase) + (voff)[_i]), (LAS unsigned*)(lds + (bufoff) + ldsw + _i * 8192), 16, 0, 0); } while (0)
; #define PG8_LDA(dst, b, h) do { _Pragma("unroll") for (int m = 0; m < 4; ++m) _Pragma("unroll") for (int k = 0; k < 2; ++k) dst[m][k] = *(const LAS bf16x8*)(lds + PG8_SA(b, h) + aoff + m * 2048 + k * 1024); } while (0)
; #define PG8_LDB(dst, b, h) do { _Pragma("unroll") for (int n = 0; n < 2; ++n) _Pragma("unroll") for (int k = 0; k < 2; ++k) dst[n][k] = *(const LAS bf16x8*)(lds + PG8_SB(b, h) + boff + n * 2048 + k * 1024); } while (0)
; #define PG8_MMA(ai, bj, At, Bt) do { __builtin_amdgcn_s_setprio(1); _Pragma("unroll") for (int m = 0; m < 4; ++m) _Pragma("unroll") for (int n = 0; n < 2; ++n) _Pragma("unroll") for (int k = 0; k < 2; ++k) \
;         acc[ai][bj][m][n] = __builtin_amdgcn_mfma_f32_16x16x32_bf16(Bt[n][k], At[m][k], acc[ai][bj][m][n], 0, 0, 0); __builtin_amdgcn_s_setprio(0); } while (0)
; #define PG8_WAIT_V(n) asm volatile("s_waitcnt vmcnt(" #n ")" ::: "memory")
; #define PG8_WAIT_L(n) asm volatile("s_waitcnt lgkmcnt(" #n ")" ::: "memory")
; #define PG8_BAR __builtin_amdgcn_s_barrier()
; #define PG8_SCHED __builtin_amdgcn_sched_barrier(0)
; template <class Epi, bool SP2 = false>
; __device__ __forceinline__ void gemm_phase(LAS unsigned char* lds, const Gemm g, const StaticOrder& S, const Epi& E) {
;     ...
;             PG8_WAIT_V(8); PG8_WAIT_L(0); PG8_BAR; PG8_MMA(1, 0, At, B0); PG8_MMA(1, 1, At, B1); PG8_BAR; PG8_SCHED;
;             PG8_LDB(B0, 1, 0); PG8_LDB(B1, 1, 1); PG8_SCHED; PG8_LDA(At, 1, 0); PG8_STAGE(PG8_SA(0, 1), a2 + hstepA, voffA);
;             PG8_WAIT_V(8); PG8_WAIT_L(0); PG8_BAR; PG8_MMA(0, 0, At, B0); PG8_MMA(0, 1, At, B1); PG8_BAR; PG8_SCHED;
	s_setprio 1
	v_mfma_f32_16x16x32_bf16 v[60:63], v[146:149], v[184:187], v[60:63]
	v_mfma_f32_16x16x32_bf16 v[56:59], v[160:163], v[184:187], v[56:59]
	v_mfma_f32_16x16x32_bf16 v[44:47], v[146:149], v[192:195], v[44:47]
	v_mfma_f32_16x16x32_bf16 v[40:43], v[160:163], v[192:195], v[40:43]
	v_mfma_f32_16x16x32_bf16 v[28:31], v[146:149], v[200:203], v[28:31]
	v_mfma_f32_16x16x32_bf16 v[24:27], v[160:163], v[200:203], v[24:27]
	v_mfma_f32_16x16x32_bf16 v[12:15], v[146:149], v[208:211], v[12:15]
	v_mfma_f32_16x16x32_bf16 v[8:11], v[160:163], v[208:211], v[8:11]
	v_mfma_f32_16x16x32_bf16 v[60:63], v[156:159], v[188:191], v[60:63]
	v_mfma_f32_16x16x32_bf16 v[56:59], v[164:167], v[188:191], v[56:59]
	v_mfma_f32_16x16x32_bf16 v[44:47], v[156:159], v[196:199], v[44:47]
	v_mfma_f32_16x16x32_bf16 v[40:43], v[164:167], v[196:199], v[40:43]
	v_mfma_f32_16x16x32_bf16 v[28:31], v[156:159], v[204:207], v[28:31]
	v_mfma_f32_16x16x32_bf16 v[24:27], v[164:167], v[204:207], v[24:27]
	v_mfma_f32_16x16x32_bf16 v[12:15], v[156:159], v[212:215], v[12:15]
	v_mfma_f32_16x16x32_bf16 v[8:11], v[164:167], v[212:215], v[8:11]
	v_mfma_f32_16x16x32_bf16 v[52:55], v[168:171], v[184:187], v[52:55]
	v_mfma_f32_16x16x32_bf16 v[48:51], v[176:179], v[184:187], v[48:51]
	v_mfma_f32_16x16x32_bf16 v[36:39], v[168:171], v[192:195], v[36:39]
	v_mfma_f32_16x16x32_bf16 v[32:35], v[176:179], v[192:195], v[32:35]
	v_mfma_f32_16x16x32_bf16 v[20:23], v[168:171], v[200:203], v[20:23]
	v_mfma_f32_16x16x32_bf16 v[16:19], v[176:179], v[200:203], v[16:19]
	v_mfma_f32_16x16x32_bf16 v[4:7], v[168:171], v[208:211], v[4:7]
	v_mfma_f32_16x16x32_bf16 v[0:3], v[176:179], v[208:211], v[0:3]
	v_mfma_f32_16x16x32_bf16 v[52:55], v[172:175], v[188:191], v[52:55]
	v_mfma_f32_16x16x32_bf16 v[48:51], v[180:183], v[188:191], v[48:51]
	v_mfma_f32_16x16x32_bf16 v[36:39], v[172:175], v[196:199], v[36:39]
	v_mfma_f32_16x16x32_bf16 v[32:35], v[180:183], v[196:199], v[32:35]
	v_mfma_f32_16x16x32_bf16 v[20:23], v[172:175], v[204:207], v[20:23]
	v_mfma_f32_16x16x32_bf16 v[16:19], v[180:183], v[204:207], v[16:19]
	v_mfma_f32_16x16x32_bf16 v[4:7], v[172:175], v[212:215], v[4:7]
	v_mfma_f32_16x16x32_bf16 v[0:3], v[180:183], v[212:215], v[0:3]
	s_setprio 0
	s_barrier
	s_add_i32 s68, 0, 0x18000
	s_add_i32 s69, 0, 0x1c000
	v_add_u32_e32 v164, s68, v152
	v_add_u32_e32 v180, s69, v152
	ds_read_b128 v[146:149], v164
	ds_read_b128 v[156:159], v164 offset:1024
	ds_read_b128 v[160:163], v164 offset:2048
	ds_read_b128 v[164:167], v164 offset:3072
	ds_read_b128 v[168:171], v180
	ds_read_b128 v[172:175], v180 offset:1024
	ds_read_b128 v[176:179], v180 offset:2048
	ds_read_b128 v[180:183], v180 offset:3072
	s_add_u32 s50, s50, 0x40000
	s_addc_u32 s51, s51, 0
	s_mov_b32 m0, s55
	v_lshl_add_u64 v[222:223], s[50:51], 0, v[130:131]
	ds_read_b128 v[184:187], v155 offset:32768
	ds_read_b128 v[188:191], v155 offset:33792
	ds_read_b128 v[192:195], v155 offset:34816
	ds_read_b128 v[196:199], v155 offset:35840
	ds_read_b128 v[200:203], v155 offset:36864
	ds_read_b128 v[204:207], v155 offset:37888
	ds_read_b128 v[208:211], v155 offset:38912
	ds_read_b128 v[212:215], v155 offset:39936
	global_load_lds_dwordx4 v[222:223], off
	v_lshl_add_u64 v[222:223], s[50:51], 0, v[134:135]
	s_mov_b32 m0, s56
	s_nop 0
	global_load_lds_dwordx4 v[222:223], off
	s_waitcnt vmcnt(8)
	s_waitcnt lgkmcnt(0)
	s_barrier
	s_setprio 1
	v_mfma_f32_16x16x32_bf16 v[124:127], v[146:149], v[184:187], v[124:127]
	v_mfma_f32_16x16x32_bf16 v[120:123], v[160:163], v[184:187], v[120:123]
	v_mfma_f32_16x16x32_bf16 v[108:111], v[146:149], v[192:195], v[108:111]
	v_mfma_f32_16x16x32_bf16 v[104:107], v[160:163], v[192:195], v[104:107]
	v_mfma_f32_16x16x32_bf16 v[92:95], v[146:149], v[200:203], v[92:95]
	v_mfma_f32_16x16x32_bf16 v[88:91], v[160:163], v[200:203], v[88:91]
	v_mfma_f32_16x16x32_bf16 v[76:79], v[146:149], v[208:211], v[76:79]
	v_mfma_f32_16x16x32_bf16 v[72:75], v[160:163], v[208:211], v[72:75]
	v_mfma_f32_16x16x32_bf16 v[124:127], v[156:159], v[188:191], v[124:127]
	v_mfma_f32_16x16x32_bf16 v[120:123], v[164:167], v[188:191], v[120:123]
	v_mfma_f32_16x16x32_bf16 v[108:111], v[156:159], v[196:199], v[108:111]
	v_mfma_f32_16x16x32_bf16 v[104:107], v[164:167], v[196:199], v[104:107]
	v_mfma_f32_16x16x32_bf16 v[92:95], v[156:159], v[204:207], v[92:95]
	v_mfma_f32_16x16x32_bf16 v[88:91], v[164:167], v[204:207], v[88:91]
	v_mfma_f32_16x16x32_bf16 v[76:79], v[156:159], v[212:215], v[76:79]
	v_mfma_f32_16x16x32_bf16 v[72:75], v[164:167], v[212:215], v[72:75]
	v_mfma_f32_16x16x32_bf16 v[116:119], v[168:171], v[184:187], v[116:119]
	v_mfma_f32_16x16x32_bf16 v[112:115], v[176:179], v[184:187], v[112:115]
	v_mfma_f32_16x16x32_bf16 v[100:103], v[168:171], v[192:195], v[100:103]
	v_mfma_f32_16x16x32_bf16 v[96:99], v[176:179], v[192:195], v[96:99]
	v_mfma_f32_16x16x32_bf16 v[84:87], v[168:171], v[200:203], v[84:87]
	v_mfma_f32_16x16x32_bf16 v[80:83], v[176:179], v[200:203], v[80:83]
	v_mfma_f32_16x16x32_bf16 v[68:71], v[168:171], v[208:211], v[68:71]
	v_mfma_f32_16x16x32_bf16 v[64:67], v[176:179], v[208:211], v[64:67]
	v_mfma_f32_16x16x32_bf16 v[116:119], v[172:175], v[188:191], v[116:119]
	v_mfma_f32_16x16x32_bf16 v[112:115], v[180:183], v[188:191], v[112:115]
	v_mfma_f32_16x16x32_bf16 v[100:103], v[172:175], v[196:199], v[100:103]
	v_mfma_f32_16x16x32_bf16 v[96:99], v[180:183], v[196:199], v[96:99]
	v_mfma_f32_16x16x32_bf16 v[84:87], v[172:175], v[204:207], v[84:87]
	v_mfma_f32_16x16x32_bf16 v[80:83], v[180:183], v[204:207], v[80:83]
	v_mfma_f32_16x16x32_bf16 v[68:71], v[172:175], v[212:215], v[68:71]
	v_mfma_f32_16x16x32_bf16 v[64:67], v[180:183], v[212:215], v[64:67]
	s_setprio 0
	s_barrier
; #define PG8_STAGE(bufoff, gbase, voff) do { _Pragma("unroll") for (int _i = 0; _i < 2; ++_i) \
;         __builtin_amdgcn_global_load_lds((const unsigned*)((const char*)(gbase) + (voff)[_i]), (LAS unsigned*)(lds + (bufoff) + ldsw + _i * 8192), 16, 0, 0); } while (0)
; #define PG8_LDA(dst, b, h) do { _Pragma("unroll") for (int m = 0; m < 4; ++m) _Pragma("unroll") for (int k = 0; k < 2; ++k) dst[m][k] = *(const LAS bf16x8*)(lds + PG8_SA(b, h) + aoff + m * 2048 + k * 1024); } while (0)
; #define PG8_MMA(ai, bj, At, Bt) do { __builtin_amdgcn_s_setprio(1); _Pragma("unroll") for (int m = 0; m < 4; ++m) _Pragma("unroll") for (int n = 0; n < 2; ++n) _Pragma("unroll") for (int k = 0; k < 2; ++k) \
;         acc[ai][bj][m][n] = __builtin_amdgcn_mfma_f32_16x16x32_bf16(Bt[n][k], At[m][k], acc[ai][bj][m][n], 0, 0, 0); __builtin_amdgcn_s_setprio(0); } while (0)
; #define PG8_WAIT_V(n) asm volatile("s_waitcnt vmcnt(" #n ")" ::: "memory")
; #define PG8_WAIT_L(n) asm volatile("s_waitcnt lgkmcnt(" #n ")" ::: "memory")
; #define PG8_BAR __builtin_amdgcn_s_barrier()
; #define PG8_SCHED __builtin_amdgcn_sched_barrier(0)
; template <class Epi, bool SP2 = false>
; __device__ __forceinline__ void gemm_phase(LAS unsigned char* lds, const Gemm g, const StaticOrder& S, const Epi& E) {
;     ...
;             PG8_LDA(At, 1, 1); PG8_STAGE(PG8_SB(1, 0), b3, voffB); PG8_STAGE(PG8_SB(1, 1), b3 + hstepB, voffB); PG8_STAGE(PG8_SA(1, 0), a3, voffA);
;             PG8_WAIT_V(8); PG8_WAIT_L(0); PG8_BAR; PG8_MMA(1, 0, At, B0); PG8_MMA(1, 1, At, B1); PG8_BAR; PG8_SCHED;
;     ...
;         if constexpr (SP2) { if (wr == 0) PG8_BAR; }
	s_add_i32 s50, s68, s53
	v_lshl_add_u64 v[150:151], v[150:151], 0, s[10:11]
	s_mov_b32 m0, s50
	ds_read_b128 v[184:187], v155 offset:49152
	ds_read_b128 v[188:191], v155 offset:50176
	ds_read_b128 v[192:195], v155 offset:51200
	ds_read_b128 v[196:199], v155 offset:52224
	ds_read_b128 v[200:203], v155 offset:53248
	ds_read_b128 v[204:207], v155 offset:54272
	ds_read_b128 v[208:211], v155 offset:55296
	ds_read_b128 v[212:215], v155 offset:56320
	global_load_lds_dwordx4 v[150:151], off
	s_add_i32 m0, s50, 0x2000
	s_add_u32 s44, s44, 0x40080
	v_lshl_add_u64 v[150:151], v[216:217], 0, s[10:11]
	s_addc_u32 s45, s45, 0
	s_add_i32 s50, s69, s53
	global_load_lds_dwordx4 v[150:151], off
	v_lshl_add_u64 v[150:151], s[44:45], 0, v[132:133]
	s_mov_b32 m0, s50
	s_nop 0
	global_load_lds_dwordx4 v[150:151], off
	v_lshl_add_u64 v[150:151], s[44:45], 0, v[136:137]
	s_add_i32 m0, s50, 0x2000
	s_nop 0
	global_load_lds_dwordx4 v[150:151], off
	v_lshl_add_u64 v[150:151], v[218:219], 0, s[10:11]
	s_mov_b32 m0, s60
	s_nop 0
	global_load_lds_dwordx4 v[150:151], off
	v_lshl_add_u64 v[150:151], v[220:221], 0, s[10:11]
	s_mov_b32 m0, s61
	s_nop 0
	global_load_lds_dwordx4 v[150:151], off
	s_waitcnt vmcnt(8)
	s_waitcnt lgkmcnt(0)
	s_barrier
	s_setprio 1
	v_mfma_f32_16x16x32_bf16 v[60:63], v[146:149], v[184:187], v[60:63]
	v_mfma_f32_16x16x32_bf16 v[56:59], v[160:163], v[184:187], v[56:59]
	v_mfma_f32_16x16x32_bf16 v[44:47], v[146:149], v[192:195], v[44:47]
	v_mfma_f32_16x16x32_bf16 v[40:43], v[160:163], v[192:195], v[40:43]
	v_mfma_f32_16x16x32_bf16 v[28:31], v[146:149], v[200:203], v[28:31]
	v_mfma_f32_16x16x32_bf16 v[24:27], v[160:163], v[200:203], v[24:27]
	v_mfma_f32_16x16x32_bf16 v[12:15], v[146:149], v[208:211], v[12:15]
	v_mfma_f32_16x16x32_bf16 v[8:11], v[160:163], v[208:211], v[8:11]
	v_mfma_f32_16x16x32_bf16 v[60:63], v[156:159], v[188:191], v[60:63]
	v_mfma_f32_16x16x32_bf16 v[56:59], v[164:167], v[188:191], v[56:59]
	v_mfma_f32_16x16x32_bf16 v[44:47], v[156:159], v[196:199], v[44:47]
	v_mfma_f32_16x16x32_bf16 v[40:43], v[164:167], v[196:199], v[40:43]
	v_mfma_f32_16x16x32_bf16 v[28:31], v[156:159], v[204:207], v[28:31]
	v_mfma_f32_16x16x32_bf16 v[24:27], v[164:167], v[204:207], v[24:27]
	v_mfma_f32_16x16x32_bf16 v[12:15], v[156:159], v[212:215], v[12:15]
	v_mfma_f32_16x16x32_bf16 v[8:11], v[164:167], v[212:215], v[8:11]
	v_mfma_f32_16x16x32_bf16 v[52:55], v[168:171], v[184:187], v[52:55]
	v_mfma_f32_16x16x32_bf16 v[48:51], v[176:179], v[184:187], v[48:51]
	v_mfma_f32_16x16x32_bf16 v[36:39], v[168:171], v[192:195], v[36:39]
	v_mfma_f32_16x16x32_bf16 v[32:35], v[176:179], v[192:195], v[32:35]
	v_mfma_f32_16x16x32_bf16 v[20:23], v[168:171], v[200:203], v[20:23]
	v_mfma_f32_16x16x32_bf16 v[16:19], v[176:179], v[200:203], v[16:19]
	v_mfma_f32_16x16x32_bf16 v[4:7], v[168:171], v[208:211], v[4:7]
	v_mfma_f32_16x16x32_bf16 v[0:3], v[176:179], v[208:211], v[0:3]
	v_mfma_f32_16x16x32_bf16 v[52:55], v[172:175], v[188:191], v[52:55]
	v_mfma_f32_16x16x32_bf16 v[48:51], v[180:183], v[188:191], v[48:51]
	v_mfma_f32_16x16x32_bf16 v[36:39], v[172:175], v[196:199], v[36:39]
	v_mfma_f32_16x16x32_bf16 v[32:35], v[180:183], v[196:199], v[32:35]
	v_mfma_f32_16x16x32_bf16 v[20:23], v[172:175], v[204:207], v[20:23]
	v_mfma_f32_16x16x32_bf16 v[16:19], v[180:183], v[204:207], v[16:19]
	v_mfma_f32_16x16x32_bf16 v[4:7], v[172:175], v[212:215], v[4:7]
	v_mfma_f32_16x16x32_bf16 v[0:3], v[180:183], v[212:215], v[0:3]
	s_setprio 0
	s_barrier
	s_add_i32 s74, s74, 2
	s_add_u32 s34, s34, 0x100
	s_addc_u32 s35, s35, 0
	s_add_u32 s72, s72, 0x100
	s_addc_u32 s73, s73, 0
	s_cmp_gt_u32 s74, 13
	s_cbranch_scc0 .LBB0_462
	s_and_b64 vcc, exec, s[12:13]
	s_cbranch_vccz .LBB0_465
	s_barrier

; #define PG8_STAGE(bufoff, gbase, voff) do { _Pragma("unroll") for (int _i = 0; _i < 2; ++_i) \
;         __builtin_amdgcn_global_load_lds((const unsigned*)((const char*)(gbase) + (voff)[_i]), (LAS unsigned*)(lds + (bufoff) + ldsw + _i * 8192), 16, 0, 0); } while (0)
; #define PG8_LDA(dst, b, h) do { _Pragma("unroll") for (int m = 0; m < 4; ++m) _Pragma("unroll") for (int k = 0; k < 2; ++k) dst[m][k] = *(const LAS bf16x8*)(lds + PG8_SA(b, h) + aoff + m * 2048 + k * 1024); } while (0)
; #define PG8_LDB(dst, b, h) do { _Pragma("unroll") for (int n = 0; n < 2; ++n) _Pragma("unroll") for (int k = 0; k < 2; ++k) dst[n][k] = *(const LAS bf16x8*)(lds + PG8_SB(b, h) + boff + n * 2048 + k * 1024); } while (0)
; #define PG8_MMA(ai, bj, At, Bt) do { __builtin_amdgcn_s_setprio(1); _Pragma("unroll") for (int m = 0; m < 4; ++m) _Pragma("unroll") for (int n = 0; n < 2; ++n) _Pragma("unroll") for (int k = 0; k < 2; ++k) \
;         acc[ai][bj][m][n] = __builtin_amdgcn_mfma_f32_16x16x32_bf16(Bt[n][k], At[m][k], acc[ai][bj][m][n], 0, 0, 0); __builtin_amdgcn_s_setprio(0); } while (0)
; #define PG8_WAIT_V(n) asm volatile("s_waitcnt vmcnt(" #n ")" ::: "memory")
; #define PG8_WAIT_L(n) asm volatile("s_waitcnt lgkmcnt(" #n ")" ::: "memory")
; #define PG8_BAR __builtin_amdgcn_s_barrier()
; #define PG8_SCHED __builtin_amdgcn_sched_barrier(0)
; template <class Epi, bool SP2 = false>
; __device__ __forceinline__ void gemm_phase(LAS unsigned char* lds, const Gemm g, const StaticOrder& S, const Epi& E) {
;     ...
;             const bool last = (t == nt - 2);
;             const char* a1 = cA + (size_t)(t + 1) * kstep;
;             const char* a2 = last ? nA : cA + (size_t)(t + 2) * kstep; const char* b2 = last ? nB : cB + (size_t)(t + 2) * kstep;
;             const char* a3 = a2 + kstep; const char* b3 = b2 + kstep;
;             if constexpr (SP2) {
;             PG8_LDB(B0, 0, 0); PG8_LDB(B1, 0, 1); PG8_SCHED; PG8_LDA(At, 0, 0); PG8_STAGE(PG8_SA(1, 1), a1 + hstepA, voffA);
;             PG8_WAIT_V(8); PG8_WAIT_L(0); PG8_BAR; PG8_MMA(0, 0, At, B0); PG8_MMA(0, 1, At, B1); PG8_BAR; PG8_SCHED;
;             PG8_LDA(At, 0, 1); PG8_STAGE(PG8_SB(0, 0), b2, voffB); PG8_STAGE(PG8_SB(0, 1), b2 + hstepB, voffB); PG8_STAGE(PG8_SA(0, 0), a2, voffA);
;             PG8_WAIT_V(8); PG8_WAIT_L(0); PG8_BAR; PG8_MMA(1, 0, At, B0); PG8_MMA(1, 1, At, B1); PG8_BAR; PG8_SCHED;
.LBB0_805:
	ds_read_b128 v[146:149], v153
	ds_read_b128 v[156:159], v153 offset:1024
	ds_read_b128 v[160:163], v153 offset:2048
	ds_read_b128 v[164:167], v153 offset:3072
	ds_read_b128 v[168:171], v154
	ds_read_b128 v[172:175], v154 offset:1024
	ds_read_b128 v[176:179], v154 offset:2048
	ds_read_b128 v[180:183], v154 offset:3072
	s_add_u32 s48, s34, 0xfffc0080
	s_addc_u32 s49, s35, -1
	s_cmp_eq_u32 s80, 12
	s_cselect_b32 s51, s43, s49
	s_cselect_b32 s50, s76, s48
	s_cselect_b32 s49, s41, s79
	s_cselect_b32 s48, s77, s78
	v_lshl_add_u64 v[150:151], s[34:35], 0, v[138:139]
	s_add_i32 m0, s31, 0xc000
	ds_read_b128 v[184:187], v155
	ds_read_b128 v[188:191], v155 offset:1024
	ds_read_b128 v[192:195], v155 offset:2048
	ds_read_b128 v[196:199], v155 offset:3072
	ds_read_b128 v[200:203], v155 offset:4096
	ds_read_b128 v[204:207], v155 offset:5120
	ds_read_b128 v[208:211], v155 offset:6144
	ds_read_b128 v[212:215], v155 offset:7168
	global_load_lds_dwordx4 v[150:151], off
	v_lshl_add_u64 v[150:151], s[34:35], 0, v[140:141]
	s_add_i32 m0, s31, 0xe000
	s_nop 0
	global_load_lds_dwordx4 v[150:151], off
	s_waitcnt vmcnt(8)
	s_waitcnt lgkmcnt(0)
	s_barrier
	s_setprio 1
	v_mfma_f32_16x16x32_bf16 v[124:127], v[146:149], v[184:187], v[124:127]
	v_mfma_f32_16x16x32_bf16 v[120:123], v[160:163], v[184:187], v[120:123]
	v_mfma_f32_16x16x32_bf16 v[108:111], v[146:149], v[192:195], v[108:111]
	v_mfma_f32_16x16x32_bf16 v[104:107], v[160:163], v[192:195], v[104:107]
	v_mfma_f32_16x16x32_bf16 v[92:95], v[146:149], v[200:203], v[92:95]
	v_mfma_f32_16x16x32_bf16 v[88:91], v[160:163], v[200:203], v[88:91]
	v_mfma_f32_16x16x32_bf16 v[76:79], v[146:149], v[208:211], v[76:79]
	v_mfma_f32_16x16x32_bf16 v[72:75], v[160:163], v[208:211], v[72:75]
	v_mfma_f32_16x16x32_bf16 v[124:127], v[156:159], v[188:191], v[124:127]
	v_mfma_f32_16x16x32_bf16 v[120:123], v[164:167], v[188:191], v[120:123]
	v_mfma_f32_16x16x32_bf16 v[108:111], v[156:159], v[196:199], v[108:111]
	v_mfma_f32_16x16x32_bf16 v[104:107], v[164:167], v[196:199], v[104:107]
	v_mfma_f32_16x16x32_bf16 v[92:95], v[156:159], v[204:207], v[92:95]
	v_mfma_f32_16x16x32_bf16 v[88:91], v[164:167], v[204:207], v[88:91]
	v_mfma_f32_16x16x32_bf16 v[76:79], v[156:159], v[212:215], v[76:79]
	v_mfma_f32_16x16x32_bf16 v[72:75], v[164:167], v[212:215], v[72:75]
	v_mfma_f32_16x16x32_bf16 v[116:119], v[168:171], v[184:187], v[116:119]
	v_mfma_f32_16x16x32_bf16 v[112:115], v[176:179], v[184:187], v[112:115]
	v_mfma_f32_16x16x32_bf16 v[100:103], v[168:171], v[192:195], v[100:103]
	v_mfma_f32_16x16x32_bf16 v[96:99], v[176:179], v[192:195], v[96:99]
	v_mfma_f32_16x16x32_bf16 v[84:87], v[168:171], v[200:203], v[84:87]
	v_mfma_f32_16x16x32_bf16 v[80:83], v[176:179], v[200:203], v[80:83]
	v_mfma_f32_16x16x32_bf16 v[68:71], v[168:171], v[208:211], v[68:71]
	v_mfma_f32_16x16x32_bf16 v[64:67], v[176:179], v[208:211], v[64:67]
	v_mfma_f32_16x16x32_bf16 v[116:119], v[172:175], v[188:191], v[116:119]
	v_mfma_f32_16x16x32_bf16 v[112:115], v[180:183], v[188:191], v[112:115]
	v_mfma_f32_16x16x32_bf16 v[100:103], v[172:175], v[196:199], v[100:103]
	v_mfma_f32_16x16x32_bf16 v[96:99], v[180:183], v[196:199], v[96:99]
	v_mfma_f32_16x16x32_bf16 v[84:87], v[172:175], v[204:207], v[84:87]
	v_mfma_f32_16x16x32_bf16 v[80:83], v[180:183], v[204:207], v[80:83]
	v_mfma_f32_16x16x32_bf16 v[68:71], v[172:175], v[212:215], v[68:71]
	v_mfma_f32_16x16x32_bf16 v[64:67], v[180:183], v[212:215], v[64:67]
	s_setprio 0
	s_barrier
	s_add_i32 s68, s66, s53
	v_lshl_add_u64 v[150:151], s[48:49], 0, v[134:135]
	s_mov_b32 m0, s68
	ds_read_b128 v[184:187], v155 offset:16384
	ds_read_b128 v[188:191], v155 offset:17408
	ds_read_b128 v[192:195], v155 offset:18432
	ds_read_b128 v[196:199], v155 offset:19456
	ds_read_b128 v[200:203], v155 offset:20480
	ds_read_b128 v[204:207], v155 offset:21504
	ds_read_b128 v[208:211], v155 offset:22528
	ds_read_b128 v[212:215], v155 offset:23552
	global_load_lds_dwordx4 v[150:151], off
	s_add_i32 m0, s68, 0x2000
	s_add_u32 s68, s48, 0x40000
	v_lshl_add_u64 v[216:217], s[48:49], 0, v[130:131]
	s_addc_u32 s69, s49, 0
	s_add_i32 s70, s67, s53
	global_load_lds_dwordx4 v[216:217], off
	v_lshl_add_u64 v[218:219], s[68:69], 0, v[134:135]
	s_mov_b32 m0, s70
	v_lshl_add_u64 v[220:221], s[50:51], 0, v[132:133]
	global_load_lds_dwordx4 v[218:219], off
	v_lshl_add_u64 v[218:219], s[68:69], 0, v[130:131]
	s_add_i32 m0, s70, 0x2000
	s_nop 0
	global_load_lds_dwordx4 v[218:219], off
	v_lshl_add_u64 v[218:219], s[50:51], 0, v[136:137]
	s_mov_b32 m0, s31
	s_nop 0
	global_load_lds_dwordx4 v[218:219], off
	s_mov_b32 m0, s56
	s_nop 0
	global_load_lds_dwordx4 v[220:221], off
	s_waitcnt vmcnt(8)
	s_waitcnt lgkmcnt(0)
	s_barrier
; #define PG8_STAGE(bufoff, gbase, voff) do { _Pragma("unroll") for (int _i = 0; _i < 2; ++_i) \
;         __builtin_amdgcn_global_load_lds((const unsigned*)((const char*)(gbase) + (voff)[_i]), (LAS unsigned*)(lds + (bufoff) + ldsw + _i * 8192), 16, 0, 0); } while (0)
; #define PG8_LDA(dst, b, h) do { _Pragma("unroll") for (int m = 0; m < 4; ++m) _Pragma("unroll") for (int k = 0; k < 2; ++k) dst[m][k] = *(const LAS bf16x8*)(lds + PG8_SA(b, h) + aoff + m * 2048 + k * 1024); } while (0)
; #define PG8_LDB(dst, b, h) do { _Pragma("unroll") for (int n = 0; n < 2; ++n) _Pragma("unroll") for (int k = 0; k < 2; ++k) dst[n][k] = *(const LAS bf16x8*)(lds + PG8_SB(b, h) + boff + n * 2048 + k * 1024); } while (0)
; #define PG8_MMA(ai, bj, At, Bt) do { __builtin_amdgcn_s_setprio(1); _Pragma("unroll") for (int m = 0; m < 4; ++m) _Pragma("unroll") for (int n = 0; n < 2; ++n) _Pragma("unroll") for (int k = 0; k < 2; ++k) \
;         acc[ai][bj][m][n] = __builtin_amdgcn_mfma_f32_16x16x32_bf16(Bt[n][k], At[m][k], acc[ai][bj][m][n], 0, 0, 0); __builtin_amdgcn_s_setprio(0); } while (0)
; #define PG8_WAIT_V(n) asm volatile("s_waitcnt vmcnt(" #n ")" ::: "memory")
; #define PG8_WAIT_L(n) asm volatile("s_waitcnt lgkmcnt(" #n ")" ::: "memory")
; #define PG8_BAR __builtin_amdgcn_s_barrier()
; #define PG8_SCHED __builtin_amdgcn_sched_barrier(0)
; template <class Epi, bool SP2 = false>
; __device__ __forceinline__ void gemm_phase(LAS unsigned char* lds, const Gemm g, const StaticOrder& S, const Epi& E) {
;     ...
;             PG8_WAIT_V(8); PG8_WAIT_L(0); PG8_BAR; PG8_MMA(1, 0, At, B0); PG8_MMA(1, 1, At, B1); PG8_BAR; PG8_SCHED;
;             PG8_LDB(B0, 1, 0); PG8_LDB(B1, 1, 1); PG8_SCHED; PG8_LDA(At, 1, 0); PG8_STAGE(PG8_SA(0, 1), a2 + hstepA, voffA);
;             PG8_WAIT_V(8); PG8_WAIT_L(0); PG8_BAR; PG8_MMA(0, 0, At, B0); PG8_MMA(0, 1, At, B1); PG8_BAR; PG8_SCHED;
	s_setprio 1
	v_mfma_f32_16x16x32_bf16 v[60:63], v[146:149], v[184:187], v[60:63]
	v_mfma_f32_16x16x32_bf16 v[56:59], v[160:163], v[184:187], v[56:59]
	v_mfma_f32_16x16x32_bf16 v[44:47], v[146:149], v[192:195], v[44:47]
	v_mfma_f32_16x16x32_bf16 v[40:43], v[160:163], v[192:195], v[40:43]
	v_mfma_f32_16x16x32_bf16 v[28:31], v[146:149], v[200:203], v[28:31]
	v_mfma_f32_16x16x32_bf16 v[24:27], v[160:163], v[200:203], v[24:27]
	v_mfma_f32_16x16x32_bf16 v[12:15], v[146:149], v[208:211], v[12:15]
	v_mfma_f32_16x16x32_bf16 v[8:11], v[160:163], v[208:211], v[8:11]
	v_mfma_f32_16x16x32_bf16 v[60:63], v[156:159], v[188:191], v[60:63]
	v_mfma_f32_16x16x32_bf16 v[56:59], v[164:167], v[188:191], v[56:59]
	v_mfma_f32_16x16x32_bf16 v[44:47], v[156:159], v[196:199], v[44:47]
	v_mfma_f32_16x16x32_bf16 v[40:43], v[164:167], v[196:199], v[40:43]
	v_mfma_f32_16x16x32_bf16 v[28:31], v[156:159], v[204:207], v[28:31]
	v_mfma_f32_16x16x32_bf16 v[24:27], v[164:167], v[204:207], v[24:27]
	v_mfma_f32_16x16x32_bf16 v[12:15], v[156:159], v[212:215], v[12:15]
	v_mfma_f32_16x16x32_bf16 v[8:11], v[164:167], v[212:215], v[8:11]
	v_mfma_f32_16x16x32_bf16 v[52:55], v[168:171], v[184:187], v[52:55]
	v_mfma_f32_16x16x32_bf16 v[48:51], v[176:179], v[184:187], v[48:51]
	v_mfma_f32_16x16x32_bf16 v[36:39], v[168:171], v[192:195], v[36:39]
	v_mfma_f32_16x16x32_bf16 v[32:35], v[176:179], v[192:195], v[32:35]
	v_mfma_f32_16x16x32_bf16 v[20:23], v[168:171], v[200:203], v[20:23]
	v_mfma_f32_16x16x32_bf16 v[16:19], v[176:179], v[200:203], v[16:19]
	v_mfma_f32_16x16x32_bf16 v[4:7], v[168:171], v[208:211], v[4:7]
	v_mfma_f32_16x16x32_bf16 v[0:3], v[176:179], v[208:211], v[0:3]
	v_mfma_f32_16x16x32_bf16 v[52:55], v[172:175], v[188:191], v[52:55]
	v_mfma_f32_16x16x32_bf16 v[48:51], v[180:183], v[188:191], v[48:51]
	v_mfma_f32_16x16x32_bf16 v[36:39], v[172:175], v[196:199], v[36:39]
	v_mfma_f32_16x16x32_bf16 v[32:35], v[180:183], v[196:199], v[32:35]
	v_mfma_f32_16x16x32_bf16 v[20:23], v[172:175], v[204:207], v[20:23]
	v_mfma_f32_16x16x32_bf16 v[16:19], v[180:183], v[204:207], v[16:19]
	v_mfma_f32_16x16x32_bf16 v[4:7], v[172:175], v[212:215], v[4:7]
	v_mfma_f32_16x16x32_bf16 v[0:3], v[180:183], v[212:215], v[0:3]
	s_setprio 0
	s_barrier
	s_add_i32 s68, 0, 0x18000
	s_add_i32 s69, 0, 0x1c000
	v_add_u32_e32 v164, s68, v152
	v_add_u32_e32 v180, s69, v152
	ds_read_b128 v[146:149], v164
	ds_read_b128 v[156:159], v164 offset:1024
	ds_read_b128 v[160:163], v164 offset:2048
	ds_read_b128 v[164:167], v164 offset:3072
	ds_read_b128 v[168:171], v180
	ds_read_b128 v[172:175], v180 offset:1024
	ds_read_b128 v[176:179], v180 offset:2048
	ds_read_b128 v[180:183], v180 offset:3072
	s_add_u32 s50, s50, 0x40000
	s_addc_u32 s51, s51, 0
	s_mov_b32 m0, s57
	v_lshl_add_u64 v[222:223], s[50:51], 0, v[136:137]
	ds_read_b128 v[184:187], v155 offset:32768
	ds_read_b128 v[188:191], v155 offset:33792
	ds_read_b128 v[192:195], v155 offset:34816
	ds_read_b128 v[196:199], v155 offset:35840
	ds_read_b128 v[200:203], v155 offset:36864
	ds_read_b128 v[204:207], v155 offset:37888
	ds_read_b128 v[208:211], v155 offset:38912
	ds_read_b128 v[212:215], v155 offset:39936
	global_load_lds_dwordx4 v[222:223], off
	v_lshl_add_u64 v[222:223], s[50:51], 0, v[132:133]
	s_mov_b32 m0, s58
	s_nop 0
	global_load_lds_dwordx4 v[222:223], off
	s_waitcnt vmcnt(8)
	s_waitcnt lgkmcnt(0)
	s_barrier
	s_setprio 1
	v_mfma_f32_16x16x32_bf16 v[124:127], v[146:149], v[184:187], v[124:127]
	v_mfma_f32_16x16x32_bf16 v[120:123], v[160:163], v[184:187], v[120:123]
	v_mfma_f32_16x16x32_bf16 v[108:111], v[146:149], v[192:195], v[108:111]
	v_mfma_f32_16x16x32_bf16 v[104:107], v[160:163], v[192:195], v[104:107]
	v_mfma_f32_16x16x32_bf16 v[92:95], v[146:149], v[200:203], v[92:95]
	v_mfma_f32_16x16x32_bf16 v[88:91], v[160:163], v[200:203], v[88:91]
	v_mfma_f32_16x16x32_bf16 v[76:79], v[146:149], v[208:211], v[76:79]
	v_mfma_f32_16x16x32_bf16 v[72:75], v[160:163], v[208:211], v[72:75]
	v_mfma_f32_16x16x32_bf16 v[124:127], v[156:159], v[188:191], v[124:127]
	v_mfma_f32_16x16x32_bf16 v[120:123], v[164:167], v[188:191], v[120:123]
	v_mfma_f32_16x16x32_bf16 v[108:111], v[156:159], v[196:199], v[108:111]
	v_mfma_f32_16x16x32_bf16 v[104:107], v[164:167], v[196:199], v[104:107]
	v_mfma_f32_16x16x32_bf16 v[92:95], v[156:159], v[204:207], v[92:95]
	v_mfma_f32_16x16x32_bf16 v[88:91], v[164:167], v[204:207], v[88:91]
	v_mfma_f32_16x16x32_bf16 v[76:79], v[156:159], v[212:215], v[76:79]
	v_mfma_f32_16x16x32_bf16 v[72:75], v[164:167], v[212:215], v[72:75]
	v_mfma_f32_16x16x32_bf16 v[116:119], v[168:171], v[184:187], v[116:119]
	v_mfma_f32_16x16x32_bf16 v[112:115], v[176:179], v[184:187], v[112:115]
	v_mfma_f32_16x16x32_bf16 v[100:103], v[168:171], v[192:195], v[100:103]
	v_mfma_f32_16x16x32_bf16 v[96:99], v[176:179], v[192:195], v[96:99]
	v_mfma_f32_16x16x32_bf16 v[84:87], v[168:171], v[200:203], v[84:87]
	v_mfma_f32_16x16x32_bf16 v[80:83], v[176:179], v[200:203], v[80:83]
	v_mfma_f32_16x16x32_bf16 v[68:71], v[168:171], v[208:211], v[68:71]
	v_mfma_f32_16x16x32_bf16 v[64:67], v[176:179], v[208:211], v[64:67]
	v_mfma_f32_16x16x32_bf16 v[116:119], v[172:175], v[188:191], v[116:119]
	v_mfma_f32_16x16x32_bf16 v[112:115], v[180:183], v[188:191], v[112:115]
	v_mfma_f32_16x16x32_bf16 v[100:103], v[172:175], v[196:199], v[100:103]
	v_mfma_f32_16x16x32_bf16 v[96:99], v[180:183], v[196:199], v[96:99]
	v_mfma_f32_16x16x32_bf16 v[84:87], v[172:175], v[204:207], v[84:87]
	v_mfma_f32_16x16x32_bf16 v[80:83], v[180:183], v[204:207], v[80:83]
	v_mfma_f32_16x16x32_bf16 v[68:71], v[172:175], v[212:215], v[68:71]
	v_mfma_f32_16x16x32_bf16 v[64:67], v[180:183], v[212:215], v[64:67]
	s_setprio 0
	s_barrier
; #define PG8_STAGE(bufoff, gbase, voff) do { _Pragma("unroll") for (int _i = 0; _i < 2; ++_i) \
;         __builtin_amdgcn_global_load_lds((const unsigned*)((const char*)(gbase) + (voff)[_i]), (LAS unsigned*)(lds + (bufoff) + ldsw + _i * 8192), 16, 0, 0); } while (0)
; #define PG8_LDA(dst, b, h) do { _Pragma("unroll") for (int m = 0; m < 4; ++m) _Pragma("unroll") for (int k = 0; k < 2; ++k) dst[m][k] = *(const LAS bf16x8*)(lds + PG8_SA(b, h) + aoff + m * 2048 + k * 1024); } while (0)
; #define PG8_MMA(ai, bj, At, Bt) do { __builtin_amdgcn_s_setprio(1); _Pragma("unroll") for (int m = 0; m < 4; ++m) _Pragma("unroll") for (int n = 0; n < 2; ++n) _Pragma("unroll") for (int k = 0; k < 2; ++k) \
;         acc[ai][bj][m][n] = __builtin_amdgcn_mfma_f32_16x16x32_bf16(Bt[n][k], At[m][k], acc[ai][bj][m][n], 0, 0, 0); __builtin_amdgcn_s_setprio(0); } while (0)
; #define PG8_WAIT_V(n) asm volatile("s_waitcnt vmcnt(" #n ")" ::: "memory")
; #define PG8_WAIT_L(n) asm volatile("s_waitcnt lgkmcnt(" #n ")" ::: "memory")
; #define PG8_BAR __builtin_amdgcn_s_barrier()
; #define PG8_SCHED __builtin_amdgcn_sched_barrier(0)
; template <class Epi, bool SP2 = false>
; __device__ __forceinline__ void gemm_phase(LAS unsigned char* lds, const Gemm g, const StaticOrder& S, const Epi& E) {
;     ...
;             PG8_LDA(At, 1, 1); PG8_STAGE(PG8_SB(1, 0), b3, voffB); PG8_STAGE(PG8_SB(1, 1), b3 + hstepB, voffB); PG8_STAGE(PG8_SA(1, 0), a3, voffA);
;             PG8_WAIT_V(8); PG8_WAIT_L(0); PG8_BAR; PG8_MMA(1, 0, At, B0); PG8_MMA(1, 1, At, B1); PG8_BAR; PG8_SCHED;
;     ...
;         if constexpr (SP2) { if (wr == 0) PG8_BAR; }
	s_add_i32 s50, s68, s53
	v_lshl_add_u64 v[150:151], v[150:151], 0, s[10:11]
	s_mov_b32 m0, s50
	ds_read_b128 v[184:187], v155 offset:49152
	ds_read_b128 v[188:191], v155 offset:50176
	ds_read_b128 v[192:195], v155 offset:51200
	ds_read_b128 v[196:199], v155 offset:52224
	ds_read_b128 v[200:203], v155 offset:53248
	ds_read_b128 v[204:207], v155 offset:54272
	ds_read_b128 v[208:211], v155 offset:55296
	ds_read_b128 v[212:215], v155 offset:56320
	global_load_lds_dwordx4 v[150:151], off
	s_add_i32 m0, s50, 0x2000
	s_add_u32 s48, s48, 0x40080
	v_lshl_add_u64 v[150:151], v[216:217], 0, s[10:11]
	s_addc_u32 s49, s49, 0
	s_add_i32 s50, s69, s53
	global_load_lds_dwordx4 v[150:151], off
	v_lshl_add_u64 v[150:151], s[48:49], 0, v[134:135]
	s_mov_b32 m0, s50
	s_nop 0
	global_load_lds_dwordx4 v[150:151], off
	v_lshl_add_u64 v[150:151], s[48:49], 0, v[130:131]
	s_add_i32 m0, s50, 0x2000
	s_nop 0
	global_load_lds_dwordx4 v[150:151], off
	v_lshl_add_u64 v[150:151], v[218:219], 0, s[10:11]
	s_mov_b32 m0, s62
	s_nop 0
	global_load_lds_dwordx4 v[150:151], off
	v_lshl_add_u64 v[150:151], v[220:221], 0, s[10:11]
	s_mov_b32 m0, s63
	s_nop 0
	global_load_lds_dwordx4 v[150:151], off
	s_waitcnt vmcnt(8)
	s_waitcnt lgkmcnt(0)
	s_barrier
	s_setprio 1
	v_mfma_f32_16x16x32_bf16 v[60:63], v[146:149], v[184:187], v[60:63]
	v_mfma_f32_16x16x32_bf16 v[56:59], v[160:163], v[184:187], v[56:59]
	v_mfma_f32_16x16x32_bf16 v[44:47], v[146:149], v[192:195], v[44:47]
	v_mfma_f32_16x16x32_bf16 v[40:43], v[160:163], v[192:195], v[40:43]
	v_mfma_f32_16x16x32_bf16 v[28:31], v[146:149], v[200:203], v[28:31]
	v_mfma_f32_16x16x32_bf16 v[24:27], v[160:163], v[200:203], v[24:27]
	v_mfma_f32_16x16x32_bf16 v[12:15], v[146:149], v[208:211], v[12:15]
	v_mfma_f32_16x16x32_bf16 v[8:11], v[160:163], v[208:211], v[8:11]
	v_mfma_f32_16x16x32_bf16 v[60:63], v[156:159], v[188:191], v[60:63]
	v_mfma_f32_16x16x32_bf16 v[56:59], v[164:167], v[188:191], v[56:59]
	v_mfma_f32_16x16x32_bf16 v[44:47], v[156:159], v[196:199], v[44:47]
	v_mfma_f32_16x16x32_bf16 v[40:43], v[164:167], v[196:199], v[40:43]
	v_mfma_f32_16x16x32_bf16 v[28:31], v[156:159], v[204:207], v[28:31]
	v_mfma_f32_16x16x32_bf16 v[24:27], v[164:167], v[204:207], v[24:27]
	v_mfma_f32_16x16x32_bf16 v[12:15], v[156:159], v[212:215], v[12:15]
	v_mfma_f32_16x16x32_bf16 v[8:11], v[164:167], v[212:215], v[8:11]
	v_mfma_f32_16x16x32_bf16 v[52:55], v[168:171], v[184:187], v[52:55]
	v_mfma_f32_16x16x32_bf16 v[48:51], v[176:179], v[184:187], v[48:51]
	v_mfma_f32_16x16x32_bf16 v[36:39], v[168:171], v[192:195], v[36:39]
	v_mfma_f32_16x16x32_bf16 v[32:35], v[176:179], v[192:195], v[32:35]
	v_mfma_f32_16x16x32_bf16 v[20:23], v[168:171], v[200:203], v[20:23]
	v_mfma_f32_16x16x32_bf16 v[16:19], v[176:179], v[200:203], v[16:19]
	v_mfma_f32_16x16x32_bf16 v[4:7], v[168:171], v[208:211], v[4:7]
	v_mfma_f32_16x16x32_bf16 v[0:3], v[176:179], v[208:211], v[0:3]
	v_mfma_f32_16x16x32_bf16 v[52:55], v[172:175], v[188:191], v[52:55]
	v_mfma_f32_16x16x32_bf16 v[48:51], v[180:183], v[188:191], v[48:51]
	v_mfma_f32_16x16x32_bf16 v[36:39], v[172:175], v[196:199], v[36:39]
	v_mfma_f32_16x16x32_bf16 v[32:35], v[180:183], v[196:199], v[32:35]
	v_mfma_f32_16x16x32_bf16 v[20:23], v[172:175], v[204:207], v[20:23]
	v_mfma_f32_16x16x32_bf16 v[16:19], v[180:183], v[204:207], v[16:19]
	v_mfma_f32_16x16x32_bf16 v[4:7], v[172:175], v[212:215], v[4:7]
	v_mfma_f32_16x16x32_bf16 v[0:3], v[180:183], v[212:215], v[0:3]
	s_setprio 0
	s_barrier
	s_add_i32 s80, s80, 2
	s_add_u32 s34, s34, 0x100
	s_addc_u32 s35, s35, 0
	s_add_u32 s78, s78, 0x100
	s_addc_u32 s79, s79, 0
	s_cmp_gt_u32 s80, 13
	s_cbranch_scc0 .LBB0_805
	s_and_b64 vcc, exec, s[12:13]
	s_cbranch_vccz .LBB0_808
	s_barrier

; #define PG8_STAGE(bufoff, gbase, voff) do { _Pragma("unroll") for (int _i = 0; _i < 2; ++_i) \
;         __builtin_amdgcn_global_load_lds((const unsigned*)((const char*)(gbase) + (voff)[_i]), (LAS unsigned*)(lds + (bufoff) + ldsw + _i * 8192), 16, 0, 0); } while (0)
; #define PG8_LDA(dst, b, h) do { _Pragma("unroll") for (int m = 0; m < 4; ++m) _Pragma("unroll") for (int k = 0; k < 2; ++k) dst[m][k] = *(const LAS bf16x8*)(lds + PG8_SA(b, h) + aoff + m * 2048 + k * 1024); } while (0)
; #define PG8_LDB(dst, b, h) do { _Pragma("unroll") for (int n = 0; n < 2; ++n) _Pragma("unroll") for (int k = 0; k < 2; ++k) dst[n][k] = *(const LAS bf16x8*)(lds + PG8_SB(b, h) + boff + n * 2048 + k * 1024); } while (0)
; #define PG8_MMA(ai, bj, At, Bt) do { __builtin_amdgcn_s_setprio(1); _Pragma("unroll") for (int m = 0; m < 4; ++m) _Pragma("unroll") for (int n = 0; n < 2; ++n) _Pragma("unroll") for (int k = 0; k < 2; ++k) \
;         acc[ai][bj][m][n] = __builtin_amdgcn_mfma_f32_16x16x32_bf16(Bt[n][k], At[m][k], acc[ai][bj][m][n], 0, 0, 0); __builtin_amdgcn_s_setprio(0); } while (0)
; #define PG8_WAIT_V(n) asm volatile("s_waitcnt vmcnt(" #n ")" ::: "memory")
; #define PG8_WAIT_L(n) asm volatile("s_waitcnt lgkmcnt(" #n ")" ::: "memory")
; #define PG8_BAR __builtin_amdgcn_s_barrier()
; #define PG8_SCHED __builtin_amdgcn_sched_barrier(0)
; template <class Epi, bool SP2 = false>
; __device__ __forceinline__ void gemm_phase(LAS unsigned char* lds, const Gemm g, const StaticOrder& S, const Epi& E) {
;     ...
;             const bool last = (t == nt - 2);
;             const char* a1 = cA + (size_t)(t + 1) * kstep;
;             const char* a2 = last ? nA : cA + (size_t)(t + 2) * kstep; const char* b2 = last ? nB : cB + (size_t)(t + 2) * kstep;
;             const char* a3 = a2 + kstep; const char* b3 = b2 + kstep;
;             if constexpr (SP2) {
;             PG8_LDB(B0, 0, 0); PG8_LDB(B1, 0, 1); PG8_SCHED; PG8_LDA(At, 0, 0); PG8_STAGE(PG8_SA(1, 1), a1 + hstepA, voffA);
;             PG8_WAIT_V(8); PG8_WAIT_L(0); PG8_BAR; PG8_MMA(0, 0, At, B0); PG8_MMA(0, 1, At, B1); PG8_BAR; PG8_SCHED;
;             PG8_LDA(At, 0, 1); PG8_STAGE(PG8_SB(0, 0), b2, voffB); PG8_STAGE(PG8_SB(0, 1), b2 + hstepB, voffB); PG8_STAGE(PG8_SA(0, 0), a2, voffA);
;             PG8_WAIT_V(8); PG8_WAIT_L(0); PG8_BAR; PG8_MMA(1, 0, At, B0); PG8_MMA(1, 1, At, B1); PG8_BAR; PG8_SCHED;
.LBB0_872:
	ds_read_b128 v[146:149], v166
	ds_read_b128 v[170:173], v166 offset:1024
	ds_read_b128 v[174:177], v166 offset:2048
	ds_read_b128 v[178:181], v166 offset:3072
	ds_read_b128 v[182:185], v167
	ds_read_b128 v[186:189], v167 offset:1024
	ds_read_b128 v[190:193], v167 offset:2048
	ds_read_b128 v[194:197], v167 offset:3072
	s_add_u32 s50, s34, 0xfffe0080
	s_addc_u32 s51, s35, -1
	s_cmp_eq_u32 s82, 4
	s_cselect_b32 s53, s45, s51
	s_cselect_b32 s52, s78, s50
	s_cselect_b32 s51, s43, s81
	s_cselect_b32 s50, s79, s80
	v_lshl_add_u64 v[150:151], s[34:35], 0, v[138:139]
	s_add_i32 m0, s31, 0xc000
	ds_read_b128 v[198:201], v168
	ds_read_b128 v[202:205], v168 offset:1024
	ds_read_b128 v[206:209], v168 offset:2048
	ds_read_b128 v[210:213], v168 offset:3072
	ds_read_b128 v[214:217], v168 offset:4096
	ds_read_b128 v[218:221], v168 offset:5120
	ds_read_b128 v[222:225], v168 offset:6144
	ds_read_b128 v[226:229], v168 offset:7168
	global_load_lds_dwordx4 v[150:151], off
	v_lshl_add_u64 v[150:151], s[34:35], 0, v[140:141]
	s_add_i32 m0, s31, 0xe000
	s_nop 0
	global_load_lds_dwordx4 v[150:151], off
	s_waitcnt vmcnt(8)
	s_waitcnt lgkmcnt(0)
	s_barrier
	s_setprio 1
	v_mfma_f32_16x16x32_bf16 v[124:127], v[146:149], v[198:201], v[124:127]
	v_mfma_f32_16x16x32_bf16 v[120:123], v[174:177], v[198:201], v[120:123]
	v_mfma_f32_16x16x32_bf16 v[108:111], v[146:149], v[206:209], v[108:111]
	v_mfma_f32_16x16x32_bf16 v[104:107], v[174:177], v[206:209], v[104:107]
	v_mfma_f32_16x16x32_bf16 v[92:95], v[146:149], v[214:217], v[92:95]
	v_mfma_f32_16x16x32_bf16 v[88:91], v[174:177], v[214:217], v[88:91]
	v_mfma_f32_16x16x32_bf16 v[76:79], v[146:149], v[222:225], v[76:79]
	v_mfma_f32_16x16x32_bf16 v[72:75], v[174:177], v[222:225], v[72:75]
	v_mfma_f32_16x16x32_bf16 v[124:127], v[170:173], v[202:205], v[124:127]
	v_mfma_f32_16x16x32_bf16 v[120:123], v[178:181], v[202:205], v[120:123]
	v_mfma_f32_16x16x32_bf16 v[108:111], v[170:173], v[210:213], v[108:111]
	v_mfma_f32_16x16x32_bf16 v[104:107], v[178:181], v[210:213], v[104:107]
	v_mfma_f32_16x16x32_bf16 v[92:95], v[170:173], v[218:221], v[92:95]
	v_mfma_f32_16x16x32_bf16 v[88:91], v[178:181], v[218:221], v[88:91]
	v_mfma_f32_16x16x32_bf16 v[76:79], v[170:173], v[226:229], v[76:79]
	v_mfma_f32_16x16x32_bf16 v[72:75], v[178:181], v[226:229], v[72:75]
	v_mfma_f32_16x16x32_bf16 v[116:119], v[182:185], v[198:201], v[116:119]
	v_mfma_f32_16x16x32_bf16 v[112:115], v[190:193], v[198:201], v[112:115]
	v_mfma_f32_16x16x32_bf16 v[100:103], v[182:185], v[206:209], v[100:103]
	v_mfma_f32_16x16x32_bf16 v[96:99], v[190:193], v[206:209], v[96:99]
	v_mfma_f32_16x16x32_bf16 v[84:87], v[182:185], v[214:217], v[84:87]
	v_mfma_f32_16x16x32_bf16 v[80:83], v[190:193], v[214:217], v[80:83]
	v_mfma_f32_16x16x32_bf16 v[68:71], v[182:185], v[222:225], v[68:71]
	v_mfma_f32_16x16x32_bf16 v[64:67], v[190:193], v[222:225], v[64:67]
	v_mfma_f32_16x16x32_bf16 v[116:119], v[186:189], v[202:205], v[116:119]
	v_mfma_f32_16x16x32_bf16 v[112:115], v[194:197], v[202:205], v[112:115]
	v_mfma_f32_16x16x32_bf16 v[100:103], v[186:189], v[210:213], v[100:103]
	v_mfma_f32_16x16x32_bf16 v[96:99], v[194:197], v[210:213], v[96:99]
	v_mfma_f32_16x16x32_bf16 v[84:87], v[186:189], v[218:221], v[84:87]
	v_mfma_f32_16x16x32_bf16 v[80:83], v[194:197], v[218:221], v[80:83]
	v_mfma_f32_16x16x32_bf16 v[68:71], v[186:189], v[226:229], v[68:71]
	v_mfma_f32_16x16x32_bf16 v[64:67], v[194:197], v[226:229], v[64:67]
	s_setprio 0
	s_barrier
	s_add_i32 s68, s72, s55
	v_lshl_add_u64 v[150:151], s[50:51], 0, v[134:135]
	s_mov_b32 m0, s68
	ds_read_b128 v[198:201], v168 offset:16384
	ds_read_b128 v[202:205], v168 offset:17408
	ds_read_b128 v[206:209], v168 offset:18432
	ds_read_b128 v[210:213], v168 offset:19456
	ds_read_b128 v[214:217], v168 offset:20480
	ds_read_b128 v[218:221], v168 offset:21504
	ds_read_b128 v[222:225], v168 offset:22528
	ds_read_b128 v[226:229], v168 offset:23552
	global_load_lds_dwordx4 v[150:151], off
	s_add_i32 m0, s68, 0x2000
	s_add_u32 s68, s50, 0x20000
	v_lshl_add_u64 v[230:231], s[50:51], 0, v[130:131]
	s_addc_u32 s69, s51, 0
	s_add_i32 s70, s73, s55
	global_load_lds_dwordx4 v[230:231], off
	v_lshl_add_u64 v[232:233], s[68:69], 0, v[134:135]
	s_mov_b32 m0, s70
	v_lshl_add_u64 v[234:235], s[52:53], 0, v[132:133]
	global_load_lds_dwordx4 v[232:233], off
	v_lshl_add_u64 v[232:233], s[68:69], 0, v[130:131]
	s_add_i32 m0, s70, 0x2000
	s_nop 0
	global_load_lds_dwordx4 v[232:233], off
	v_lshl_add_u64 v[232:233], s[52:53], 0, v[136:137]
	s_mov_b32 m0, s31
	s_nop 0
	global_load_lds_dwordx4 v[232:233], off
	s_mov_b32 m0, s58
	s_nop 0
	global_load_lds_dwordx4 v[234:235], off
	s_waitcnt vmcnt(8)
	s_waitcnt lgkmcnt(0)
	s_barrier
; #define PG8_STAGE(bufoff, gbase, voff) do { _Pragma("unroll") for (int _i = 0; _i < 2; ++_i) \
;         __builtin_amdgcn_global_load_lds((const unsigned*)((const char*)(gbase) + (voff)[_i]), (LAS unsigned*)(lds + (bufoff) + ldsw + _i * 8192), 16, 0, 0); } while (0)
; #define PG8_LDA(dst, b, h) do { _Pragma("unroll") for (int m = 0; m < 4; ++m) _Pragma("unroll") for (int k = 0; k < 2; ++k) dst[m][k] = *(const LAS bf16x8*)(lds + PG8_SA(b, h) + aoff + m * 2048 + k * 1024); } while (0)
; #define PG8_LDB(dst, b, h) do { _Pragma("unroll") for (int n = 0; n < 2; ++n) _Pragma("unroll") for (int k = 0; k < 2; ++k) dst[n][k] = *(const LAS bf16x8*)(lds + PG8_SB(b, h) + boff + n * 2048 + k * 1024); } while (0)
; #define PG8_MMA(ai, bj, At, Bt) do { __builtin_amdgcn_s_setprio(1); _Pragma("unroll") for (int m = 0; m < 4; ++m) _Pragma("unroll") for (int n = 0; n < 2; ++n) _Pragma("unroll") for (int k = 0; k < 2; ++k) \
;         acc[ai][bj][m][n] = __builtin_amdgcn_mfma_f32_16x16x32_bf16(Bt[n][k], At[m][k], acc[ai][bj][m][n], 0, 0, 0); __builtin_amdgcn_s_setprio(0); } while (0)
; #define PG8_WAIT_V(n) asm volatile("s_waitcnt vmcnt(" #n ")" ::: "memory")
; #define PG8_WAIT_L(n) asm volatile("s_waitcnt lgkmcnt(" #n ")" ::: "memory")
; #define PG8_BAR __builtin_amdgcn_s_barrier()
; #define PG8_SCHED __builtin_amdgcn_sched_barrier(0)
; template <class Epi, bool SP2 = false>
; __device__ __forceinline__ void gemm_phase(LAS unsigned char* lds, const Gemm g, const StaticOrder& S, const Epi& E) {
;     ...
;             PG8_WAIT_V(8); PG8_WAIT_L(0); PG8_BAR; PG8_MMA(1, 0, At, B0); PG8_MMA(1, 1, At, B1); PG8_BAR; PG8_SCHED;
;             PG8_LDB(B0, 1, 0); PG8_LDB(B1, 1, 1); PG8_SCHED; PG8_LDA(At, 1, 0); PG8_STAGE(PG8_SA(0, 1), a2 + hstepA, voffA);
;             PG8_WAIT_V(8); PG8_WAIT_L(0); PG8_BAR; PG8_MMA(0, 0, At, B0); PG8_MMA(0, 1, At, B1); PG8_BAR; PG8_SCHED;
	s_setprio 1
	v_mfma_f32_16x16x32_bf16 v[60:63], v[146:149], v[198:201], v[60:63]
	v_mfma_f32_16x16x32_bf16 v[56:59], v[174:177], v[198:201], v[56:59]
	v_mfma_f32_16x16x32_bf16 v[44:47], v[146:149], v[206:209], v[44:47]
	v_mfma_f32_16x16x32_bf16 v[40:43], v[174:177], v[206:209], v[40:43]
	v_mfma_f32_16x16x32_bf16 v[28:31], v[146:149], v[214:217], v[28:31]
	v_mfma_f32_16x16x32_bf16 v[24:27], v[174:177], v[214:217], v[24:27]
	v_mfma_f32_16x16x32_bf16 v[12:15], v[146:149], v[222:225], v[12:15]
	v_mfma_f32_16x16x32_bf16 v[8:11], v[174:177], v[222:225], v[8:11]
	v_mfma_f32_16x16x32_bf16 v[60:63], v[170:173], v[202:205], v[60:63]
	v_mfma_f32_16x16x32_bf16 v[56:59], v[178:181], v[202:205], v[56:59]
	v_mfma_f32_16x16x32_bf16 v[44:47], v[170:173], v[210:213], v[44:47]
	v_mfma_f32_16x16x32_bf16 v[40:43], v[178:181], v[210:213], v[40:43]
	v_mfma_f32_16x16x32_bf16 v[28:31], v[170:173], v[218:221], v[28:31]
	v_mfma_f32_16x16x32_bf16 v[24:27], v[178:181], v[218:221], v[24:27]
	v_mfma_f32_16x16x32_bf16 v[12:15], v[170:173], v[226:229], v[12:15]
	v_mfma_f32_16x16x32_bf16 v[8:11], v[178:181], v[226:229], v[8:11]
	v_mfma_f32_16x16x32_bf16 v[52:55], v[182:185], v[198:201], v[52:55]
	v_mfma_f32_16x16x32_bf16 v[48:51], v[190:193], v[198:201], v[48:51]
	v_mfma_f32_16x16x32_bf16 v[36:39], v[182:185], v[206:209], v[36:39]
	v_mfma_f32_16x16x32_bf16 v[32:35], v[190:193], v[206:209], v[32:35]
	v_mfma_f32_16x16x32_bf16 v[20:23], v[182:185], v[214:217], v[20:23]
	v_mfma_f32_16x16x32_bf16 v[16:19], v[190:193], v[214:217], v[16:19]
	v_mfma_f32_16x16x32_bf16 v[4:7], v[182:185], v[222:225], v[4:7]
	v_mfma_f32_16x16x32_bf16 v[0:3], v[190:193], v[222:225], v[0:3]
	v_mfma_f32_16x16x32_bf16 v[52:55], v[186:189], v[202:205], v[52:55]
	v_mfma_f32_16x16x32_bf16 v[48:51], v[194:197], v[202:205], v[48:51]
	v_mfma_f32_16x16x32_bf16 v[36:39], v[186:189], v[210:213], v[36:39]
	v_mfma_f32_16x16x32_bf16 v[32:35], v[194:197], v[210:213], v[32:35]
	v_mfma_f32_16x16x32_bf16 v[20:23], v[186:189], v[218:221], v[20:23]
	v_mfma_f32_16x16x32_bf16 v[16:19], v[194:197], v[218:221], v[16:19]
	v_mfma_f32_16x16x32_bf16 v[4:7], v[186:189], v[226:229], v[4:7]
	v_mfma_f32_16x16x32_bf16 v[0:3], v[194:197], v[226:229], v[0:3]
	s_setprio 0
	s_barrier
	s_add_i32 s68, 0, 0x18000
	v_add_u32_e32 v169, s68, v165
	s_add_i32 s69, 0, 0x1c000
	ds_read_b128 v[146:149], v169
	ds_read_b128 v[170:173], v169 offset:1024
	ds_read_b128 v[174:177], v169 offset:2048
	ds_read_b128 v[178:181], v169 offset:3072
	v_add_u32_e32 v169, s69, v165
	ds_read_b128 v[182:185], v169
	ds_read_b128 v[186:189], v169 offset:1024
	ds_read_b128 v[190:193], v169 offset:2048
	ds_read_b128 v[194:197], v169 offset:3072
	s_add_u32 s52, s52, 0x20000
	s_addc_u32 s53, s53, 0
	s_mov_b32 m0, s59
	v_lshl_add_u64 v[236:237], s[52:53], 0, v[136:137]
	ds_read_b128 v[198:201], v168 offset:32768
	ds_read_b128 v[202:205], v168 offset:33792
	ds_read_b128 v[206:209], v168 offset:34816
	ds_read_b128 v[210:213], v168 offset:35840
	ds_read_b128 v[214:217], v168 offset:36864
	ds_read_b128 v[218:221], v168 offset:37888
	ds_read_b128 v[222:225], v168 offset:38912
	ds_read_b128 v[226:229], v168 offset:39936
	global_load_lds_dwordx4 v[236:237], off
	v_lshl_add_u64 v[236:237], s[52:53], 0, v[132:133]
	s_mov_b32 m0, s60
	s_nop 0
	global_load_lds_dwordx4 v[236:237], off
	s_waitcnt vmcnt(8)
	s_waitcnt lgkmcnt(0)
	s_barrier
	s_setprio 1
	v_mfma_f32_16x16x32_bf16 v[124:127], v[146:149], v[198:201], v[124:127]
	v_mfma_f32_16x16x32_bf16 v[120:123], v[174:177], v[198:201], v[120:123]
	v_mfma_f32_16x16x32_bf16 v[108:111], v[146:149], v[206:209], v[108:111]
	v_mfma_f32_16x16x32_bf16 v[104:107], v[174:177], v[206:209], v[104:107]
	v_mfma_f32_16x16x32_bf16 v[92:95], v[146:149], v[214:217], v[92:95]
	v_mfma_f32_16x16x32_bf16 v[88:91], v[174:177], v[214:217], v[88:91]
	v_mfma_f32_16x16x32_bf16 v[76:79], v[146:149], v[222:225], v[76:79]
	v_mfma_f32_16x16x32_bf16 v[72:75], v[174:177], v[222:225], v[72:75]
	v_mfma_f32_16x16x32_bf16 v[124:127], v[170:173], v[202:205], v[124:127]
	v_mfma_f32_16x16x32_bf16 v[120:123], v[178:181], v[202:205], v[120:123]
	v_mfma_f32_16x16x32_bf16 v[108:111], v[170:173], v[210:213], v[108:111]
	v_mfma_f32_16x16x32_bf16 v[104:107], v[178:181], v[210:213], v[104:107]
	v_mfma_f32_16x16x32_bf16 v[92:95], v[170:173], v[218:221], v[92:95]
	v_mfma_f32_16x16x32_bf16 v[88:91], v[178:181], v[218:221], v[88:91]
	v_mfma_f32_16x16x32_bf16 v[76:79], v[170:173], v[226:229], v[76:79]
	v_mfma_f32_16x16x32_bf16 v[72:75], v[178:181], v[226:229], v[72:75]
	v_mfma_f32_16x16x32_bf16 v[116:119], v[182:185], v[198:201], v[116:119]
	v_mfma_f32_16x16x32_bf16 v[112:115], v[190:193], v[198:201], v[112:115]
	v_mfma_f32_16x16x32_bf16 v[100:103], v[182:185], v[206:209], v[100:103]
	v_mfma_f32_16x16x32_bf16 v[96:99], v[190:193], v[206:209], v[96:99]
	v_mfma_f32_16x16x32_bf16 v[84:87], v[182:185], v[214:217], v[84:87]
	v_mfma_f32_16x16x32_bf16 v[80:83], v[190:193], v[214:217], v[80:83]
	v_mfma_f32_16x16x32_bf16 v[68:71], v[182:185], v[222:225], v[68:71]
	v_mfma_f32_16x16x32_bf16 v[64:67], v[190:193], v[222:225], v[64:67]
	v_mfma_f32_16x16x32_bf16 v[116:119], v[186:189], v[202:205], v[116:119]
	v_mfma_f32_16x16x32_bf16 v[112:115], v[194:197], v[202:205], v[112:115]
	v_mfma_f32_16x16x32_bf16 v[100:103], v[186:189], v[210:213], v[100:103]
	v_mfma_f32_16x16x32_bf16 v[96:99], v[194:197], v[210:213], v[96:99]
	v_mfma_f32_16x16x32_bf16 v[84:87], v[186:189], v[218:221], v[84:87]
	v_mfma_f32_16x16x32_bf16 v[80:83], v[194:197], v[218:221], v[80:83]
	v_mfma_f32_16x16x32_bf16 v[68:71], v[186:189], v[226:229], v[68:71]
	v_mfma_f32_16x16x32_bf16 v[64:67], v[194:197], v[226:229], v[64:67]
	s_setprio 0
	s_barrier
; #define PG8_STAGE(bufoff, gbase, voff) do { _Pragma("unroll") for (int _i = 0; _i < 2; ++_i) \
;         __builtin_amdgcn_global_load_lds((const unsigned*)((const char*)(gbase) + (voff)[_i]), (LAS unsigned*)(lds + (bufoff) + ldsw + _i * 8192), 16, 0, 0); } while (0)
; #define PG8_LDA(dst, b, h) do { _Pragma("unroll") for (int m = 0; m < 4; ++m) _Pragma("unroll") for (int k = 0; k < 2; ++k) dst[m][k] = *(const LAS bf16x8*)(lds + PG8_SA(b, h) + aoff + m * 2048 + k * 1024); } while (0)
; #define PG8_MMA(ai, bj, At, Bt) do { __builtin_amdgcn_s_setprio(1); _Pragma("unroll") for (int m = 0; m < 4; ++m) _Pragma("unroll") for (int n = 0; n < 2; ++n) _Pragma("unroll") for (int k = 0; k < 2; ++k) \
;         acc[ai][bj][m][n] = __builtin_amdgcn_mfma_f32_16x16x32_bf16(Bt[n][k], At[m][k], acc[ai][bj][m][n], 0, 0, 0); __builtin_amdgcn_s_setprio(0); } while (0)
; #define PG8_WAIT_V(n) asm volatile("s_waitcnt vmcnt(" #n ")" ::: "memory")
; #define PG8_WAIT_L(n) asm volatile("s_waitcnt lgkmcnt(" #n ")" ::: "memory")
; #define PG8_BAR __builtin_amdgcn_s_barrier()
; #define PG8_SCHED __builtin_amdgcn_sched_barrier(0)
; template <class Epi, bool SP2 = false>
; __device__ __forceinline__ void gemm_phase(LAS unsigned char* lds, const Gemm g, const StaticOrder& S, const Epi& E) {
;     ...
;             PG8_LDA(At, 1, 1); PG8_STAGE(PG8_SB(1, 0), b3, voffB); PG8_STAGE(PG8_SB(1, 1), b3 + hstepB, voffB); PG8_STAGE(PG8_SA(1, 0), a3, voffA);
;             PG8_WAIT_V(8); PG8_WAIT_L(0); PG8_BAR; PG8_MMA(1, 0, At, B0); PG8_MMA(1, 1, At, B1); PG8_BAR; PG8_SCHED;
;     ...
;         if constexpr (SP2) { if (wr == 0) PG8_BAR; }
	s_add_i32 s52, s68, s55
	v_lshl_add_u64 v[150:151], v[150:151], 0, s[10:11]
	s_mov_b32 m0, s52
	ds_read_b128 v[198:201], v168 offset:49152
	ds_read_b128 v[202:205], v168 offset:50176
	ds_read_b128 v[206:209], v168 offset:51200
	ds_read_b128 v[210:213], v168 offset:52224
	ds_read_b128 v[214:217], v168 offset:53248
	ds_read_b128 v[218:221], v168 offset:54272
	ds_read_b128 v[222:225], v168 offset:55296
	ds_read_b128 v[226:229], v168 offset:56320
	global_load_lds_dwordx4 v[150:151], off
	s_add_i32 m0, s52, 0x2000
	s_add_u32 s50, s50, 0x20080
	v_lshl_add_u64 v[150:151], v[230:231], 0, s[10:11]
	s_addc_u32 s51, s51, 0
	s_add_i32 s52, s69, s55
	global_load_lds_dwordx4 v[150:151], off
	v_lshl_add_u64 v[150:151], s[50:51], 0, v[134:135]
	s_mov_b32 m0, s52
	s_nop 0
	global_load_lds_dwordx4 v[150:151], off
	v_lshl_add_u64 v[150:151], s[50:51], 0, v[130:131]
	s_add_i32 m0, s52, 0x2000
	s_nop 0
	global_load_lds_dwordx4 v[150:151], off
	v_lshl_add_u64 v[150:151], v[232:233], 0, s[10:11]
	s_mov_b32 m0, s64
	s_nop 0
	global_load_lds_dwordx4 v[150:151], off
	v_lshl_add_u64 v[150:151], v[234:235], 0, s[10:11]
	s_mov_b32 m0, s65
	s_nop 0
	global_load_lds_dwordx4 v[150:151], off
	s_waitcnt vmcnt(8)
	s_waitcnt lgkmcnt(0)
	s_barrier
	s_setprio 1
	v_mfma_f32_16x16x32_bf16 v[60:63], v[146:149], v[198:201], v[60:63]
	v_mfma_f32_16x16x32_bf16 v[56:59], v[174:177], v[198:201], v[56:59]
	v_mfma_f32_16x16x32_bf16 v[44:47], v[146:149], v[206:209], v[44:47]
	v_mfma_f32_16x16x32_bf16 v[40:43], v[174:177], v[206:209], v[40:43]
	v_mfma_f32_16x16x32_bf16 v[28:31], v[146:149], v[214:217], v[28:31]
	v_mfma_f32_16x16x32_bf16 v[24:27], v[174:177], v[214:217], v[24:27]
	v_mfma_f32_16x16x32_bf16 v[12:15], v[146:149], v[222:225], v[12:15]
	v_mfma_f32_16x16x32_bf16 v[8:11], v[174:177], v[222:225], v[8:11]
	v_mfma_f32_16x16x32_bf16 v[60:63], v[170:173], v[202:205], v[60:63]
	v_mfma_f32_16x16x32_bf16 v[56:59], v[178:181], v[202:205], v[56:59]
	v_mfma_f32_16x16x32_bf16 v[44:47], v[170:173], v[210:213], v[44:47]
	v_mfma_f32_16x16x32_bf16 v[40:43], v[178:181], v[210:213], v[40:43]
	v_mfma_f32_16x16x32_bf16 v[28:31], v[170:173], v[218:221], v[28:31]
	v_mfma_f32_16x16x32_bf16 v[24:27], v[178:181], v[218:221], v[24:27]
	v_mfma_f32_16x16x32_bf16 v[12:15], v[170:173], v[226:229], v[12:15]
	v_mfma_f32_16x16x32_bf16 v[8:11], v[178:181], v[226:229], v[8:11]
	v_mfma_f32_16x16x32_bf16 v[52:55], v[182:185], v[198:201], v[52:55]
	v_mfma_f32_16x16x32_bf16 v[48:51], v[190:193], v[198:201], v[48:51]
	v_mfma_f32_16x16x32_bf16 v[36:39], v[182:185], v[206:209], v[36:39]
	v_mfma_f32_16x16x32_bf16 v[32:35], v[190:193], v[206:209], v[32:35]
	v_mfma_f32_16x16x32_bf16 v[20:23], v[182:185], v[214:217], v[20:23]
	v_mfma_f32_16x16x32_bf16 v[16:19], v[190:193], v[214:217], v[16:19]
	v_mfma_f32_16x16x32_bf16 v[4:7], v[182:185], v[222:225], v[4:7]
	v_mfma_f32_16x16x32_bf16 v[0:3], v[190:193], v[222:225], v[0:3]
	v_mfma_f32_16x16x32_bf16 v[52:55], v[186:189], v[202:205], v[52:55]
	v_mfma_f32_16x16x32_bf16 v[48:51], v[194:197], v[202:205], v[48:51]
	v_mfma_f32_16x16x32_bf16 v[36:39], v[186:189], v[210:213], v[36:39]
	v_mfma_f32_16x16x32_bf16 v[32:35], v[194:197], v[210:213], v[32:35]
	v_mfma_f32_16x16x32_bf16 v[20:23], v[186:189], v[218:221], v[20:23]
	v_mfma_f32_16x16x32_bf16 v[16:19], v[194:197], v[218:221], v[16:19]
	v_mfma_f32_16x16x32_bf16 v[4:7], v[186:189], v[226:229], v[4:7]
	v_mfma_f32_16x16x32_bf16 v[0:3], v[194:197], v[226:229], v[0:3]
	s_setprio 0
	s_barrier
	s_add_i32 s82, s82, 2
	s_add_u32 s34, s34, 0x100
	s_addc_u32 s35, s35, 0
	s_add_u32 s80, s80, 0x100
	s_addc_u32 s81, s81, 0
	s_cmp_gt_u32 s82, 5
	s_cbranch_scc0 .LBB0_872
	s_and_b64 vcc, exec, s[12:13]
	s_cbranch_vccz .LBB0_875
	s_barrier

; #define PG8_STAGE(bufoff, gbase, voff) do { _Pragma("unroll") for (int _i = 0; _i < 2; ++_i) \
;         __builtin_amdgcn_global_load_lds((const unsigned*)((const char*)(gbase) + (voff)[_i]), (LAS unsigned*)(lds + (bufoff) + ldsw + _i * 8192), 16, 0, 0); } while (0)
; #define PG8_LDA(dst, b, h) do { _Pragma("unroll") for (int m = 0; m < 4; ++m) _Pragma("unroll") for (int k = 0; k < 2; ++k) dst[m][k] = *(const LAS bf16x8*)(lds + PG8_SA(b, h) + aoff + m * 2048 + k * 1024); } while (0)
; #define PG8_LDB(dst, b, h) do { _Pragma("unroll") for (int n = 0; n < 2; ++n) _Pragma("unroll") for (int k = 0; k < 2; ++k) dst[n][k] = *(const LAS bf16x8*)(lds + PG8_SB(b, h) + boff + n * 2048 + k * 1024); } while (0)
; #define PG8_MMA(ai, bj, At, Bt) do { __builtin_amdgcn_s_setprio(1); _Pragma("unroll") for (int m = 0; m < 4; ++m) _Pragma("unroll") for (int n = 0; n < 2; ++n) _Pragma("unroll") for (int k = 0; k < 2; ++k) \
;         acc[ai][bj][m][n] = __builtin_amdgcn_mfma_f32_16x16x32_bf16(Bt[n][k], At[m][k], acc[ai][bj][m][n], 0, 0, 0); __builtin_amdgcn_s_setprio(0); } while (0)
; #define PG8_WAIT_V(n) asm volatile("s_waitcnt vmcnt(" #n ")" ::: "memory")
; #define PG8_WAIT_L(n) asm volatile("s_waitcnt lgkmcnt(" #n ")" ::: "memory")
; #define PG8_BAR __builtin_amdgcn_s_barrier()
; #define PG8_SCHED __builtin_amdgcn_sched_barrier(0)
; template <class Epi, bool SP2 = false>
; __device__ __forceinline__ void gemm_phase(LAS unsigned char* lds, const Gemm g, const StaticOrder& S, const Epi& E) {
;     ...
;             const bool last = (t == nt - 2);
;             const char* a1 = cA + (size_t)(t + 1) * kstep;
;             const char* a2 = last ? nA : cA + (size_t)(t + 2) * kstep; const char* b2 = last ? nB : cB + (size_t)(t + 2) * kstep;
;             const char* a3 = a2 + kstep; const char* b3 = b2 + kstep;
;             if constexpr (SP2) {
;             PG8_LDB(B0, 0, 0); PG8_LDB(B1, 0, 1); PG8_SCHED; PG8_LDA(At, 0, 0); PG8_STAGE(PG8_SA(1, 1), a1 + hstepA, voffA);
;             PG8_WAIT_V(8); PG8_WAIT_L(0); PG8_BAR; PG8_MMA(0, 0, At, B0); PG8_MMA(0, 1, At, B1); PG8_BAR; PG8_SCHED;
;             PG8_LDA(At, 0, 1); PG8_STAGE(PG8_SB(0, 0), b2, voffB); PG8_STAGE(PG8_SB(0, 1), b2 + hstepB, voffB); PG8_STAGE(PG8_SA(0, 0), a2, voffA);
;             PG8_WAIT_V(8); PG8_WAIT_L(0); PG8_BAR; PG8_MMA(1, 0, At, B0); PG8_MMA(1, 1, At, B1); PG8_BAR; PG8_SCHED;
.LBB0_888:
	ds_read_b128 v[146:149], v152
	ds_read_b128 v[156:159], v152 offset:1024
	ds_read_b128 v[160:163], v152 offset:2048
	ds_read_b128 v[164:167], v152 offset:3072
	ds_read_b128 v[168:171], v153
	ds_read_b128 v[172:175], v153 offset:1024
	ds_read_b128 v[176:179], v153 offset:2048
	ds_read_b128 v[180:183], v153 offset:3072
	s_add_u32 s48, s34, 0xfffc0080
	s_addc_u32 s49, s35, -1
	s_cmp_eq_u32 s76, 12
	s_cselect_b32 s51, s43, s49
	s_cselect_b32 s50, s72, s48
	s_cselect_b32 s49, s41, s75
	s_cselect_b32 s48, s73, s74
	v_lshl_add_u64 v[150:151], s[34:35], 0, v[138:139]
	s_add_i32 m0, s31, 0xc000
	ds_read_b128 v[184:187], v155
	ds_read_b128 v[188:191], v155 offset:1024
	ds_read_b128 v[192:195], v155 offset:2048
	ds_read_b128 v[196:199], v155 offset:3072
	ds_read_b128 v[200:203], v155 offset:4096
	ds_read_b128 v[204:207], v155 offset:5120
	ds_read_b128 v[208:211], v155 offset:6144
	ds_read_b128 v[212:215], v155 offset:7168
	global_load_lds_dwordx4 v[150:151], off
	v_lshl_add_u64 v[150:151], s[34:35], 0, v[140:141]
	s_add_i32 m0, s31, 0xe000
	s_nop 0
	global_load_lds_dwordx4 v[150:151], off
	s_waitcnt vmcnt(8)
	s_waitcnt lgkmcnt(0)
	s_barrier
	s_setprio 1
	v_mfma_f32_16x16x32_bf16 v[124:127], v[146:149], v[184:187], v[124:127]
	v_mfma_f32_16x16x32_bf16 v[120:123], v[160:163], v[184:187], v[120:123]
	v_mfma_f32_16x16x32_bf16 v[108:111], v[146:149], v[192:195], v[108:111]
	v_mfma_f32_16x16x32_bf16 v[104:107], v[160:163], v[192:195], v[104:107]
	v_mfma_f32_16x16x32_bf16 v[92:95], v[146:149], v[200:203], v[92:95]
	v_mfma_f32_16x16x32_bf16 v[88:91], v[160:163], v[200:203], v[88:91]
	v_mfma_f32_16x16x32_bf16 v[76:79], v[146:149], v[208:211], v[76:79]
	v_mfma_f32_16x16x32_bf16 v[72:75], v[160:163], v[208:211], v[72:75]
	v_mfma_f32_16x16x32_bf16 v[124:127], v[156:159], v[188:191], v[124:127]
	v_mfma_f32_16x16x32_bf16 v[120:123], v[164:167], v[188:191], v[120:123]
	v_mfma_f32_16x16x32_bf16 v[108:111], v[156:159], v[196:199], v[108:111]
	v_mfma_f32_16x16x32_bf16 v[104:107], v[164:167], v[196:199], v[104:107]
	v_mfma_f32_16x16x32_bf16 v[92:95], v[156:159], v[204:207], v[92:95]
	v_mfma_f32_16x16x32_bf16 v[88:91], v[164:167], v[204:207], v[88:91]
	v_mfma_f32_16x16x32_bf16 v[76:79], v[156:159], v[212:215], v[76:79]
	v_mfma_f32_16x16x32_bf16 v[72:75], v[164:167], v[212:215], v[72:75]
	v_mfma_f32_16x16x32_bf16 v[116:119], v[168:171], v[184:187], v[116:119]
	v_mfma_f32_16x16x32_bf16 v[112:115], v[176:179], v[184:187], v[112:115]
	v_mfma_f32_16x16x32_bf16 v[100:103], v[168:171], v[192:195], v[100:103]
	v_mfma_f32_16x16x32_bf16 v[96:99], v[176:179], v[192:195], v[96:99]
	v_mfma_f32_16x16x32_bf16 v[84:87], v[168:171], v[200:203], v[84:87]
	v_mfma_f32_16x16x32_bf16 v[80:83], v[176:179], v[200:203], v[80:83]
	v_mfma_f32_16x16x32_bf16 v[68:71], v[168:171], v[208:211], v[68:71]
	v_mfma_f32_16x16x32_bf16 v[64:67], v[176:179], v[208:211], v[64:67]
	v_mfma_f32_16x16x32_bf16 v[116:119], v[172:175], v[188:191], v[116:119]
	v_mfma_f32_16x16x32_bf16 v[112:115], v[180:183], v[188:191], v[112:115]
	v_mfma_f32_16x16x32_bf16 v[100:103], v[172:175], v[196:199], v[100:103]
	v_mfma_f32_16x16x32_bf16 v[96:99], v[180:183], v[196:199], v[96:99]
	v_mfma_f32_16x16x32_bf16 v[84:87], v[172:175], v[204:207], v[84:87]
	v_mfma_f32_16x16x32_bf16 v[80:83], v[180:183], v[204:207], v[80:83]
	v_mfma_f32_16x16x32_bf16 v[68:71], v[172:175], v[212:215], v[68:71]
	v_mfma_f32_16x16x32_bf16 v[64:67], v[180:183], v[212:215], v[64:67]
	s_setprio 0
	s_barrier
	s_add_i32 s68, s66, s53
	v_lshl_add_u64 v[150:151], s[48:49], 0, v[134:135]
	s_mov_b32 m0, s68
	ds_read_b128 v[184:187], v155 offset:16384
	ds_read_b128 v[188:191], v155 offset:17408
	ds_read_b128 v[192:195], v155 offset:18432
	ds_read_b128 v[196:199], v155 offset:19456
	ds_read_b128 v[200:203], v155 offset:20480
	ds_read_b128 v[204:207], v155 offset:21504
	ds_read_b128 v[208:211], v155 offset:22528
	ds_read_b128 v[212:215], v155 offset:23552
	global_load_lds_dwordx4 v[150:151], off
	s_add_i32 m0, s68, 0x2000
	s_add_u32 s68, s48, 0x40000
	v_lshl_add_u64 v[216:217], s[48:49], 0, v[130:131]
	s_addc_u32 s69, s49, 0
	s_add_i32 s70, s67, s53
	global_load_lds_dwordx4 v[216:217], off
	v_lshl_add_u64 v[218:219], s[68:69], 0, v[134:135]
	s_mov_b32 m0, s70
	v_lshl_add_u64 v[220:221], s[50:51], 0, v[132:133]
	global_load_lds_dwordx4 v[218:219], off
	v_lshl_add_u64 v[218:219], s[68:69], 0, v[130:131]
	s_add_i32 m0, s70, 0x2000
	s_nop 0
	global_load_lds_dwordx4 v[218:219], off
	v_lshl_add_u64 v[218:219], s[50:51], 0, v[136:137]
	s_mov_b32 m0, s31
	s_nop 0
	global_load_lds_dwordx4 v[218:219], off
	s_mov_b32 m0, s56
	s_nop 0
	global_load_lds_dwordx4 v[220:221], off
	s_waitcnt vmcnt(8)
	s_waitcnt lgkmcnt(0)
	s_barrier
; #define PG8_STAGE(bufoff, gbase, voff) do { _Pragma("unroll") for (int _i = 0; _i < 2; ++_i) \
;         __builtin_amdgcn_global_load_lds((const unsigned*)((const char*)(gbase) + (voff)[_i]), (LAS unsigned*)(lds + (bufoff) + ldsw + _i * 8192), 16, 0, 0); } while (0)
; #define PG8_LDA(dst, b, h) do { _Pragma("unroll") for (int m = 0; m < 4; ++m) _Pragma("unroll") for (int k = 0; k < 2; ++k) dst[m][k] = *(const LAS bf16x8*)(lds + PG8_SA(b, h) + aoff + m * 2048 + k * 1024); } while (0)
; #define PG8_LDB(dst, b, h) do { _Pragma("unroll") for (int n = 0; n < 2; ++n) _Pragma("unroll") for (int k = 0; k < 2; ++k) dst[n][k] = *(const LAS bf16x8*)(lds + PG8_SB(b, h) + boff + n * 2048 + k * 1024); } while (0)
; #define PG8_MMA(ai, bj, At, Bt) do { __builtin_amdgcn_s_setprio(1); _Pragma("unroll") for (int m = 0; m < 4; ++m) _Pragma("unroll") for (int n = 0; n < 2; ++n) _Pragma("unroll") for (int k = 0; k < 2; ++k) \
;         acc[ai][bj][m][n] = __builtin_amdgcn_mfma_f32_16x16x32_bf16(Bt[n][k], At[m][k], acc[ai][bj][m][n], 0, 0, 0); __builtin_amdgcn_s_setprio(0); } while (0)
; #define PG8_WAIT_V(n) asm volatile("s_waitcnt vmcnt(" #n ")" ::: "memory")
; #define PG8_WAIT_L(n) asm volatile("s_waitcnt lgkmcnt(" #n ")" ::: "memory")
; #define PG8_BAR __builtin_amdgcn_s_barrier()
; #define PG8_SCHED __builtin_amdgcn_sched_barrier(0)
; template <class Epi, bool SP2 = false>
; __device__ __forceinline__ void gemm_phase(LAS unsigned char* lds, const Gemm g, const StaticOrder& S, const Epi& E) {
;     ...
;             PG8_WAIT_V(8); PG8_WAIT_L(0); PG8_BAR; PG8_MMA(1, 0, At, B0); PG8_MMA(1, 1, At, B1); PG8_BAR; PG8_SCHED;
;             PG8_LDB(B0, 1, 0); PG8_LDB(B1, 1, 1); PG8_SCHED; PG8_LDA(At, 1, 0); PG8_STAGE(PG8_SA(0, 1), a2 + hstepA, voffA);
;             PG8_WAIT_V(8); PG8_WAIT_L(0); PG8_BAR; PG8_MMA(0, 0, At, B0); PG8_MMA(0, 1, At, B1); PG8_BAR; PG8_SCHED;
	s_setprio 1
	v_mfma_f32_16x16x32_bf16 v[60:63], v[146:149], v[184:187], v[60:63]
	v_mfma_f32_16x16x32_bf16 v[56:59], v[160:163], v[184:187], v[56:59]
	v_mfma_f32_16x16x32_bf16 v[44:47], v[146:149], v[192:195], v[44:47]
	v_mfma_f32_16x16x32_bf16 v[40:43], v[160:163], v[192:195], v[40:43]
	v_mfma_f32_16x16x32_bf16 v[28:31], v[146:149], v[200:203], v[28:31]
	v_mfma_f32_16x16x32_bf16 v[24:27], v[160:163], v[200:203], v[24:27]
	v_mfma_f32_16x16x32_bf16 v[12:15], v[146:149], v[208:211], v[12:15]
	v_mfma_f32_16x16x32_bf16 v[8:11], v[160:163], v[208:211], v[8:11]
	v_mfma_f32_16x16x32_bf16 v[60:63], v[156:159], v[188:191], v[60:63]
	v_mfma_f32_16x16x32_bf16 v[56:59], v[164:167], v[188:191], v[56:59]
	v_mfma_f32_16x16x32_bf16 v[44:47], v[156:159], v[196:199], v[44:47]
	v_mfma_f32_16x16x32_bf16 v[40:43], v[164:167], v[196:199], v[40:43]
	v_mfma_f32_16x16x32_bf16 v[28:31], v[156:159], v[204:207], v[28:31]
	v_mfma_f32_16x16x32_bf16 v[24:27], v[164:167], v[204:207], v[24:27]
	v_mfma_f32_16x16x32_bf16 v[12:15], v[156:159], v[212:215], v[12:15]
	v_mfma_f32_16x16x32_bf16 v[8:11], v[164:167], v[212:215], v[8:11]
	v_mfma_f32_16x16x32_bf16 v[52:55], v[168:171], v[184:187], v[52:55]
	v_mfma_f32_16x16x32_bf16 v[48:51], v[176:179], v[184:187], v[48:51]
	v_mfma_f32_16x16x32_bf16 v[36:39], v[168:171], v[192:195], v[36:39]
	v_mfma_f32_16x16x32_bf16 v[32:35], v[176:179], v[192:195], v[32:35]
	v_mfma_f32_16x16x32_bf16 v[20:23], v[168:171], v[200:203], v[20:23]
	v_mfma_f32_16x16x32_bf16 v[16:19], v[176:179], v[200:203], v[16:19]
	v_mfma_f32_16x16x32_bf16 v[4:7], v[168:171], v[208:211], v[4:7]
	v_mfma_f32_16x16x32_bf16 v[0:3], v[176:179], v[208:211], v[0:3]
	v_mfma_f32_16x16x32_bf16 v[52:55], v[172:175], v[188:191], v[52:55]
	v_mfma_f32_16x16x32_bf16 v[48:51], v[180:183], v[188:191], v[48:51]
	v_mfma_f32_16x16x32_bf16 v[36:39], v[172:175], v[196:199], v[36:39]
	v_mfma_f32_16x16x32_bf16 v[32:35], v[180:183], v[196:199], v[32:35]
	v_mfma_f32_16x16x32_bf16 v[20:23], v[172:175], v[204:207], v[20:23]
	v_mfma_f32_16x16x32_bf16 v[16:19], v[180:183], v[204:207], v[16:19]
	v_mfma_f32_16x16x32_bf16 v[4:7], v[172:175], v[212:215], v[4:7]
	v_mfma_f32_16x16x32_bf16 v[0:3], v[180:183], v[212:215], v[0:3]
	s_setprio 0
	s_barrier
	s_add_i32 s68, 0, 0x18000
	s_add_i32 s69, 0, 0x1c000
	v_add_u32_e32 v164, s68, v154
	v_add_u32_e32 v180, s69, v154
	ds_read_b128 v[146:149], v164
	ds_read_b128 v[156:159], v164 offset:1024
	ds_read_b128 v[160:163], v164 offset:2048
	ds_read_b128 v[164:167], v164 offset:3072
	ds_read_b128 v[168:171], v180
	ds_read_b128 v[172:175], v180 offset:1024
	ds_read_b128 v[176:179], v180 offset:2048
	ds_read_b128 v[180:183], v180 offset:3072
	s_add_u32 s50, s50, 0x40000
	s_addc_u32 s51, s51, 0
	s_mov_b32 m0, s57
	v_lshl_add_u64 v[222:223], s[50:51], 0, v[136:137]
	ds_read_b128 v[184:187], v155 offset:32768
	ds_read_b128 v[188:191], v155 offset:33792
	ds_read_b128 v[192:195], v155 offset:34816
	ds_read_b128 v[196:199], v155 offset:35840
	ds_read_b128 v[200:203], v155 offset:36864
	ds_read_b128 v[204:207], v155 offset:37888
	ds_read_b128 v[208:211], v155 offset:38912
	ds_read_b128 v[212:215], v155 offset:39936
	global_load_lds_dwordx4 v[222:223], off
	v_lshl_add_u64 v[222:223], s[50:51], 0, v[132:133]
	s_mov_b32 m0, s58
	s_nop 0
	global_load_lds_dwordx4 v[222:223], off
	s_waitcnt vmcnt(8)
	s_waitcnt lgkmcnt(0)
	s_barrier
	s_setprio 1
	v_mfma_f32_16x16x32_bf16 v[124:127], v[146:149], v[184:187], v[124:127]
	v_mfma_f32_16x16x32_bf16 v[120:123], v[160:163], v[184:187], v[120:123]
	v_mfma_f32_16x16x32_bf16 v[108:111], v[146:149], v[192:195], v[108:111]
	v_mfma_f32_16x16x32_bf16 v[104:107], v[160:163], v[192:195], v[104:107]
	v_mfma_f32_16x16x32_bf16 v[92:95], v[146:149], v[200:203], v[92:95]
	v_mfma_f32_16x16x32_bf16 v[88:91], v[160:163], v[200:203], v[88:91]
	v_mfma_f32_16x16x32_bf16 v[76:79], v[146:149], v[208:211], v[76:79]
	v_mfma_f32_16x16x32_bf16 v[72:75], v[160:163], v[208:211], v[72:75]
	v_mfma_f32_16x16x32_bf16 v[124:127], v[156:159], v[188:191], v[124:127]
	v_mfma_f32_16x16x32_bf16 v[120:123], v[164:167], v[188:191], v[120:123]
	v_mfma_f32_16x16x32_bf16 v[108:111], v[156:159], v[196:199], v[108:111]
	v_mfma_f32_16x16x32_bf16 v[104:107], v[164:167], v[196:199], v[104:107]
	v_mfma_f32_16x16x32_bf16 v[92:95], v[156:159], v[204:207], v[92:95]
	v_mfma_f32_16x16x32_bf16 v[88:91], v[164:167], v[204:207], v[88:91]
	v_mfma_f32_16x16x32_bf16 v[76:79], v[156:159], v[212:215], v[76:79]
	v_mfma_f32_16x16x32_bf16 v[72:75], v[164:167], v[212:215], v[72:75]
	v_mfma_f32_16x16x32_bf16 v[116:119], v[168:171], v[184:187], v[116:119]
	v_mfma_f32_16x16x32_bf16 v[112:115], v[176:179], v[184:187], v[112:115]
	v_mfma_f32_16x16x32_bf16 v[100:103], v[168:171], v[192:195], v[100:103]
	v_mfma_f32_16x16x32_bf16 v[96:99], v[176:179], v[192:195], v[96:99]
	v_mfma_f32_16x16x32_bf16 v[84:87], v[168:171], v[200:203], v[84:87]
	v_mfma_f32_16x16x32_bf16 v[80:83], v[176:179], v[200:203], v[80:83]
	v_mfma_f32_16x16x32_bf16 v[68:71], v[168:171], v[208:211], v[68:71]
	v_mfma_f32_16x16x32_bf16 v[64:67], v[176:179], v[208:211], v[64:67]
	v_mfma_f32_16x16x32_bf16 v[116:119], v[172:175], v[188:191], v[116:119]
	v_mfma_f32_16x16x32_bf16 v[112:115], v[180:183], v[188:191], v[112:115]
	v_mfma_f32_16x16x32_bf16 v[100:103], v[172:175], v[196:199], v[100:103]
	v_mfma_f32_16x16x32_bf16 v[96:99], v[180:183], v[196:199], v[96:99]
	v_mfma_f32_16x16x32_bf16 v[84:87], v[172:175], v[204:207], v[84:87]
	v_mfma_f32_16x16x32_bf16 v[80:83], v[180:183], v[204:207], v[80:83]
	v_mfma_f32_16x16x32_bf16 v[68:71], v[172:175], v[212:215], v[68:71]
	v_mfma_f32_16x16x32_bf16 v[64:67], v[180:183], v[212:215], v[64:67]
	s_setprio 0
	s_barrier
; #define PG8_STAGE(bufoff, gbase, voff) do { _Pragma("unroll") for (int _i = 0; _i < 2; ++_i) \
;         __builtin_amdgcn_global_load_lds((const unsigned*)((const char*)(gbase) + (voff)[_i]), (LAS unsigned*)(lds + (bufoff) + ldsw + _i * 8192), 16, 0, 0); } while (0)
; #define PG8_LDA(dst, b, h) do { _Pragma("unroll") for (int m = 0; m < 4; ++m) _Pragma("unroll") for (int k = 0; k < 2; ++k) dst[m][k] = *(const LAS bf16x8*)(lds + PG8_SA(b, h) + aoff + m * 2048 + k * 1024); } while (0)
; #define PG8_MMA(ai, bj, At, Bt) do { __builtin_amdgcn_s_setprio(1); _Pragma("unroll") for (int m = 0; m < 4; ++m) _Pragma("unroll") for (int n = 0; n < 2; ++n) _Pragma("unroll") for (int k = 0; k < 2; ++k) \
;         acc[ai][bj][m][n] = __builtin_amdgcn_mfma_f32_16x16x32_bf16(Bt[n][k], At[m][k], acc[ai][bj][m][n], 0, 0, 0); __builtin_amdgcn_s_setprio(0); } while (0)
; #define PG8_WAIT_V(n) asm volatile("s_waitcnt vmcnt(" #n ")" ::: "memory")
; #define PG8_WAIT_L(n) asm volatile("s_waitcnt lgkmcnt(" #n ")" ::: "memory")
; #define PG8_BAR __builtin_amdgcn_s_barrier()
; #define PG8_SCHED __builtin_amdgcn_sched_barrier(0)
; template <class Epi, bool SP2 = false>
; __device__ __forceinline__ void gemm_phase(LAS unsigned char* lds, const Gemm g, const StaticOrder& S, const Epi& E) {
;     ...
;             PG8_LDA(At, 1, 1); PG8_STAGE(PG8_SB(1, 0), b3, voffB); PG8_STAGE(PG8_SB(1, 1), b3 + hstepB, voffB); PG8_STAGE(PG8_SA(1, 0), a3, voffA);
;             PG8_WAIT_V(8); PG8_WAIT_L(0); PG8_BAR; PG8_MMA(1, 0, At, B0); PG8_MMA(1, 1, At, B1); PG8_BAR; PG8_SCHED;
;     ...
;         if constexpr (SP2) { if (wr == 0) PG8_BAR; }
	s_add_i32 s50, s68, s53
	v_lshl_add_u64 v[150:151], v[150:151], 0, s[10:11]
	s_mov_b32 m0, s50
	ds_read_b128 v[184:187], v155 offset:49152
	ds_read_b128 v[188:191], v155 offset:50176
	ds_read_b128 v[192:195], v155 offset:51200
	ds_read_b128 v[196:199], v155 offset:52224
	ds_read_b128 v[200:203], v155 offset:53248
	ds_read_b128 v[204:207], v155 offset:54272
	ds_read_b128 v[208:211], v155 offset:55296
	ds_read_b128 v[212:215], v155 offset:56320
	global_load_lds_dwordx4 v[150:151], off
	s_add_i32 m0, s50, 0x2000
	s_add_u32 s48, s48, 0x40080
	v_lshl_add_u64 v[150:151], v[216:217], 0, s[10:11]
	s_addc_u32 s49, s49, 0
	s_add_i32 s50, s69, s53
	global_load_lds_dwordx4 v[150:151], off
	v_lshl_add_u64 v[150:151], s[48:49], 0, v[134:135]
	s_mov_b32 m0, s50
	s_nop 0
	global_load_lds_dwordx4 v[150:151], off
	v_lshl_add_u64 v[150:151], s[48:49], 0, v[130:131]
	s_add_i32 m0, s50, 0x2000
	s_nop 0
	global_load_lds_dwordx4 v[150:151], off
	v_lshl_add_u64 v[150:151], v[218:219], 0, s[10:11]
	s_mov_b32 m0, s62
	s_nop 0
	global_load_lds_dwordx4 v[150:151], off
	v_lshl_add_u64 v[150:151], v[220:221], 0, s[10:11]
	s_mov_b32 m0, s63
	s_nop 0
	global_load_lds_dwordx4 v[150:151], off
	s_waitcnt vmcnt(8)
	s_waitcnt lgkmcnt(0)
	s_barrier
	s_setprio 1
	v_mfma_f32_16x16x32_bf16 v[60:63], v[146:149], v[184:187], v[60:63]
	v_mfma_f32_16x16x32_bf16 v[56:59], v[160:163], v[184:187], v[56:59]
	v_mfma_f32_16x16x32_bf16 v[44:47], v[146:149], v[192:195], v[44:47]
	v_mfma_f32_16x16x32_bf16 v[40:43], v[160:163], v[192:195], v[40:43]
	v_mfma_f32_16x16x32_bf16 v[28:31], v[146:149], v[200:203], v[28:31]
	v_mfma_f32_16x16x32_bf16 v[24:27], v[160:163], v[200:203], v[24:27]
	v_mfma_f32_16x16x32_bf16 v[12:15], v[146:149], v[208:211], v[12:15]
	v_mfma_f32_16x16x32_bf16 v[8:11], v[160:163], v[208:211], v[8:11]
	v_mfma_f32_16x16x32_bf16 v[60:63], v[156:159], v[188:191], v[60:63]
	v_mfma_f32_16x16x32_bf16 v[56:59], v[164:167], v[188:191], v[56:59]
	v_mfma_f32_16x16x32_bf16 v[44:47], v[156:159], v[196:199], v[44:47]
	v_mfma_f32_16x16x32_bf16 v[40:43], v[164:167], v[196:199], v[40:43]
	v_mfma_f32_16x16x32_bf16 v[28:31], v[156:159], v[204:207], v[28:31]
	v_mfma_f32_16x16x32_bf16 v[24:27], v[164:167], v[204:207], v[24:27]
	v_mfma_f32_16x16x32_bf16 v[12:15], v[156:159], v[212:215], v[12:15]
	v_mfma_f32_16x16x32_bf16 v[8:11], v[164:167], v[212:215], v[8:11]
	v_mfma_f32_16x16x32_bf16 v[52:55], v[168:171], v[184:187], v[52:55]
	v_mfma_f32_16x16x32_bf16 v[48:51], v[176:179], v[184:187], v[48:51]
	v_mfma_f32_16x16x32_bf16 v[36:39], v[168:171], v[192:195], v[36:39]
	v_mfma_f32_16x16x32_bf16 v[32:35], v[176:179], v[192:195], v[32:35]
	v_mfma_f32_16x16x32_bf16 v[20:23], v[168:171], v[200:203], v[20:23]
	v_mfma_f32_16x16x32_bf16 v[16:19], v[176:179], v[200:203], v[16:19]
	v_mfma_f32_16x16x32_bf16 v[4:7], v[168:171], v[208:211], v[4:7]
	v_mfma_f32_16x16x32_bf16 v[0:3], v[176:179], v[208:211], v[0:3]
	v_mfma_f32_16x16x32_bf16 v[52:55], v[172:175], v[188:191], v[52:55]
	v_mfma_f32_16x16x32_bf16 v[48:51], v[180:183], v[188:191], v[48:51]
	v_mfma_f32_16x16x32_bf16 v[36:39], v[172:175], v[196:199], v[36:39]
	v_mfma_f32_16x16x32_bf16 v[32:35], v[180:183], v[196:199], v[32:35]
	v_mfma_f32_16x16x32_bf16 v[20:23], v[172:175], v[204:207], v[20:23]
	v_mfma_f32_16x16x32_bf16 v[16:19], v[180:183], v[204:207], v[16:19]
	v_mfma_f32_16x16x32_bf16 v[4:7], v[172:175], v[212:215], v[4:7]
	v_mfma_f32_16x16x32_bf16 v[0:3], v[180:183], v[212:215], v[0:3]
	s_setprio 0
	s_barrier
	s_add_i32 s76, s76, 2
	s_add_u32 s34, s34, 0x100
	s_addc_u32 s35, s35, 0
	s_add_u32 s74, s74, 0x100
	s_addc_u32 s75, s75, 0
	s_cmp_gt_u32 s76, 13
	s_cbranch_scc0 .LBB0_888
	s_and_b64 vcc, exec, s[12:13]
	s_cbranch_vccz .LBB0_891
	s_barrier

; #define PG8_STAGE(bufoff, gbase, voff) do { _Pragma("unroll") for (int _i = 0; _i < 2; ++_i) \
;         __builtin_amdgcn_global_load_lds((const unsigned*)((const char*)(gbase) + (voff)[_i]), (LAS unsigned*)(lds + (bufoff) + ldsw + _i * 8192), 16, 0, 0); } while (0)
; #define PG8_LDA(dst, b, h) do { _Pragma("unroll") for (int m = 0; m < 4; ++m) _Pragma("unroll") for (int k = 0; k < 2; ++k) dst[m][k] = *(const LAS bf16x8*)(lds + PG8_SA(b, h) + aoff + m * 2048 + k * 1024); } while (0)
; #define PG8_LDB(dst, b, h) do { _Pragma("unroll") for (int n = 0; n < 2; ++n) _Pragma("unroll") for (int k = 0; k < 2; ++k) dst[n][k] = *(const LAS bf16x8*)(lds + PG8_SB(b, h) + boff + n * 2048 + k * 1024); } while (0)
; #define PG8_MMA(ai, bj, At, Bt) do { __builtin_amdgcn_s_setprio(1); _Pragma("unroll") for (int m = 0; m < 4; ++m) _Pragma("unroll") for (int n = 0; n < 2; ++n) _Pragma("unroll") for (int k = 0; k < 2; ++k) \
;         acc[ai][bj][m][n] = __builtin_amdgcn_mfma_f32_16x16x32_bf16(Bt[n][k], At[m][k], acc[ai][bj][m][n], 0, 0, 0); __builtin_amdgcn_s_setprio(0); } while (0)
; #define PG8_WAIT_V(n) asm volatile("s_waitcnt vmcnt(" #n ")" ::: "memory")
; #define PG8_WAIT_L(n) asm volatile("s_waitcnt lgkmcnt(" #n ")" ::: "memory")
; #define PG8_BAR __builtin_amdgcn_s_barrier()
; #define PG8_SCHED __builtin_amdgcn_sched_barrier(0)
; template <class Epi, bool SP2 = false>
; __device__ __forceinline__ void gemm_phase(LAS unsigned char* lds, const Gemm g, const StaticOrder& S, const Epi& E) {
;     ...
;             const bool last = (t == nt - 2);
;             const char* a1 = cA + (size_t)(t + 1) * kstep;
;             const char* a2 = last ? nA : cA + (size_t)(t + 2) * kstep; const char* b2 = last ? nB : cB + (size_t)(t + 2) * kstep;
;             const char* a3 = a2 + kstep; const char* b3 = b2 + kstep;
;             if constexpr (SP2) {
;             PG8_LDB(B0, 0, 0); PG8_LDB(B1, 0, 1); PG8_SCHED; PG8_LDA(At, 0, 0); PG8_STAGE(PG8_SA(1, 1), a1 + hstepA, voffA);
;             PG8_WAIT_V(8); PG8_WAIT_L(0); PG8_BAR; PG8_MMA(0, 0, At, B0); PG8_MMA(0, 1, At, B1); PG8_BAR; PG8_SCHED;
;             PG8_LDA(At, 0, 1); PG8_STAGE(PG8_SB(0, 0), b2, voffB); PG8_STAGE(PG8_SB(0, 1), b2 + hstepB, voffB); PG8_STAGE(PG8_SA(0, 0), a2, voffA);
;             PG8_WAIT_V(8); PG8_WAIT_L(0); PG8_BAR; PG8_MMA(1, 0, At, B0); PG8_MMA(1, 1, At, B1); PG8_BAR; PG8_SCHED;
.LBB0_955:
	ds_read_b128 v[150:153], v147
	ds_read_b128 v[154:157], v147 offset:1024
	ds_read_b128 v[158:161], v147 offset:2048
	ds_read_b128 v[162:165], v147 offset:3072
	ds_read_b128 v[166:169], v148
	ds_read_b128 v[170:173], v148 offset:1024
	ds_read_b128 v[174:177], v148 offset:2048
	ds_read_b128 v[178:181], v148 offset:3072
	s_add_u32 s46, s34, 0xfffc0080
	s_addc_u32 s47, s35, -1
	s_cmp_eq_u32 s78, 12
	s_cselect_b32 s49, s41, s47
	s_cselect_b32 s48, s74, s46
	s_cselect_b32 s47, s39, s77
	s_cselect_b32 s46, s75, s76
	v_lshl_add_u64 v[214:215], s[34:35], 0, v[138:139]
	s_add_i32 m0, s53, 0xc000
	ds_read_b128 v[182:185], v149
	ds_read_b128 v[186:189], v149 offset:1024
	ds_read_b128 v[190:193], v149 offset:2048
	ds_read_b128 v[194:197], v149 offset:3072
	ds_read_b128 v[198:201], v149 offset:4096
	ds_read_b128 v[202:205], v149 offset:5120
	ds_read_b128 v[206:209], v149 offset:6144
	ds_read_b128 v[210:213], v149 offset:7168
	global_load_lds_dwordx4 v[214:215], off
	v_lshl_add_u64 v[214:215], s[34:35], 0, v[140:141]
	s_add_i32 m0, s53, 0xe000
	s_nop 0
	global_load_lds_dwordx4 v[214:215], off
	s_waitcnt vmcnt(8)
	s_waitcnt lgkmcnt(0)
	s_barrier
	s_setprio 1
	v_mfma_f32_16x16x32_bf16 v[124:127], v[150:153], v[182:185], v[124:127]
	v_mfma_f32_16x16x32_bf16 v[120:123], v[158:161], v[182:185], v[120:123]
	v_mfma_f32_16x16x32_bf16 v[116:119], v[150:153], v[190:193], v[116:119]
	v_mfma_f32_16x16x32_bf16 v[112:115], v[158:161], v[190:193], v[112:115]
	v_mfma_f32_16x16x32_bf16 v[100:103], v[150:153], v[198:201], v[100:103]
	v_mfma_f32_16x16x32_bf16 v[96:99], v[158:161], v[198:201], v[96:99]
	v_mfma_f32_16x16x32_bf16 v[84:87], v[150:153], v[206:209], v[84:87]
	v_mfma_f32_16x16x32_bf16 v[80:83], v[158:161], v[206:209], v[80:83]
	v_mfma_f32_16x16x32_bf16 v[124:127], v[154:157], v[186:189], v[124:127]
	v_mfma_f32_16x16x32_bf16 v[120:123], v[162:165], v[186:189], v[120:123]
	v_mfma_f32_16x16x32_bf16 v[116:119], v[154:157], v[194:197], v[116:119]
	v_mfma_f32_16x16x32_bf16 v[112:115], v[162:165], v[194:197], v[112:115]
	v_mfma_f32_16x16x32_bf16 v[100:103], v[154:157], v[202:205], v[100:103]
	v_mfma_f32_16x16x32_bf16 v[96:99], v[162:165], v[202:205], v[96:99]
	v_mfma_f32_16x16x32_bf16 v[84:87], v[154:157], v[210:213], v[84:87]
	v_mfma_f32_16x16x32_bf16 v[80:83], v[162:165], v[210:213], v[80:83]
	v_mfma_f32_16x16x32_bf16 v[108:111], v[166:169], v[182:185], v[108:111]
	v_mfma_f32_16x16x32_bf16 v[104:107], v[174:177], v[182:185], v[104:107]
	v_mfma_f32_16x16x32_bf16 v[92:95], v[166:169], v[190:193], v[92:95]
	v_mfma_f32_16x16x32_bf16 v[88:91], v[174:177], v[190:193], v[88:91]
	v_mfma_f32_16x16x32_bf16 v[76:79], v[166:169], v[198:201], v[76:79]
	v_mfma_f32_16x16x32_bf16 v[72:75], v[174:177], v[198:201], v[72:75]
	v_mfma_f32_16x16x32_bf16 v[68:71], v[166:169], v[206:209], v[68:71]
	v_mfma_f32_16x16x32_bf16 v[64:67], v[174:177], v[206:209], v[64:67]
	v_mfma_f32_16x16x32_bf16 v[108:111], v[170:173], v[186:189], v[108:111]
	v_mfma_f32_16x16x32_bf16 v[104:107], v[178:181], v[186:189], v[104:107]
	v_mfma_f32_16x16x32_bf16 v[92:95], v[170:173], v[194:197], v[92:95]
	v_mfma_f32_16x16x32_bf16 v[88:91], v[178:181], v[194:197], v[88:91]
	v_mfma_f32_16x16x32_bf16 v[76:79], v[170:173], v[202:205], v[76:79]
	v_mfma_f32_16x16x32_bf16 v[72:75], v[178:181], v[202:205], v[72:75]
	v_mfma_f32_16x16x32_bf16 v[68:71], v[170:173], v[210:213], v[68:71]
	v_mfma_f32_16x16x32_bf16 v[64:67], v[178:181], v[210:213], v[64:67]
	s_setprio 0
	s_barrier
	s_add_i32 s68, s63, s50
	v_lshl_add_u64 v[214:215], s[46:47], 0, v[134:135]
	s_mov_b32 m0, s68
	ds_read_b128 v[182:185], v149 offset:16384
	ds_read_b128 v[186:189], v149 offset:17408
	ds_read_b128 v[190:193], v149 offset:18432
	ds_read_b128 v[194:197], v149 offset:19456
	ds_read_b128 v[198:201], v149 offset:20480
	ds_read_b128 v[202:205], v149 offset:21504
	ds_read_b128 v[206:209], v149 offset:22528
	ds_read_b128 v[210:213], v149 offset:23552
	global_load_lds_dwordx4 v[214:215], off
	s_add_i32 m0, s68, 0x2000
	s_add_u32 s68, s46, 0x40000
	v_lshl_add_u64 v[216:217], s[46:47], 0, v[130:131]
	s_addc_u32 s69, s47, 0
	s_add_i32 s70, s64, s50
	global_load_lds_dwordx4 v[216:217], off
	v_lshl_add_u64 v[218:219], s[68:69], 0, v[134:135]
	s_mov_b32 m0, s70
	v_lshl_add_u64 v[220:221], s[48:49], 0, v[132:133]
	global_load_lds_dwordx4 v[218:219], off
	v_lshl_add_u64 v[218:219], s[68:69], 0, v[130:131]
	s_add_i32 m0, s70, 0x2000
	s_nop 0
	global_load_lds_dwordx4 v[218:219], off
	v_lshl_add_u64 v[218:219], s[48:49], 0, v[136:137]
	s_mov_b32 m0, s53
	s_nop 0
	global_load_lds_dwordx4 v[218:219], off
	s_mov_b32 m0, s54
	s_nop 0
	global_load_lds_dwordx4 v[220:221], off
	s_waitcnt vmcnt(8)
	s_waitcnt lgkmcnt(0)
	s_barrier
; #define PG8_STAGE(bufoff, gbase, voff) do { _Pragma("unroll") for (int _i = 0; _i < 2; ++_i) \
;         __builtin_amdgcn_global_load_lds((const unsigned*)((const char*)(gbase) + (voff)[_i]), (LAS unsigned*)(lds + (bufoff) + ldsw + _i * 8192), 16, 0, 0); } while (0)
; #define PG8_LDA(dst, b, h) do { _Pragma("unroll") for (int m = 0; m < 4; ++m) _Pragma("unroll") for (int k = 0; k < 2; ++k) dst[m][k] = *(const LAS bf16x8*)(lds + PG8_SA(b, h) + aoff + m * 2048 + k * 1024); } while (0)
; #define PG8_LDB(dst, b, h) do { _Pragma("unroll") for (int n = 0; n < 2; ++n) _Pragma("unroll") for (int k = 0; k < 2; ++k) dst[n][k] = *(const LAS bf16x8*)(lds + PG8_SB(b, h) + boff + n * 2048 + k * 1024); } while (0)
; #define PG8_MMA(ai, bj, At, Bt) do { __builtin_amdgcn_s_setprio(1); _Pragma("unroll") for (int m = 0; m < 4; ++m) _Pragma("unroll") for (int n = 0; n < 2; ++n) _Pragma("unroll") for (int k = 0; k < 2; ++k) \
;         acc[ai][bj][m][n] = __builtin_amdgcn_mfma_f32_16x16x32_bf16(Bt[n][k], At[m][k], acc[ai][bj][m][n], 0, 0, 0); __builtin_amdgcn_s_setprio(0); } while (0)
; #define PG8_WAIT_V(n) asm volatile("s_waitcnt vmcnt(" #n ")" ::: "memory")
; #define PG8_WAIT_L(n) asm volatile("s_waitcnt lgkmcnt(" #n ")" ::: "memory")
; #define PG8_BAR __builtin_amdgcn_s_barrier()
; #define PG8_SCHED __builtin_amdgcn_sched_barrier(0)
; template <class Epi, bool SP2 = false>
; __device__ __forceinline__ void gemm_phase(LAS unsigned char* lds, const Gemm g, const StaticOrder& S, const Epi& E) {
;     ...
;             PG8_WAIT_V(8); PG8_WAIT_L(0); PG8_BAR; PG8_MMA(1, 0, At, B0); PG8_MMA(1, 1, At, B1); PG8_BAR; PG8_SCHED;
;             PG8_LDB(B0, 1, 0); PG8_LDB(B1, 1, 1); PG8_SCHED; PG8_LDA(At, 1, 0); PG8_STAGE(PG8_SA(0, 1), a2 + hstepA, voffA);
;             PG8_WAIT_V(8); PG8_WAIT_L(0); PG8_BAR; PG8_MMA(0, 0, At, B0); PG8_MMA(0, 1, At, B1); PG8_BAR; PG8_SCHED;
	s_setprio 1
	v_mfma_f32_16x16x32_bf16 v[60:63], v[150:153], v[182:185], v[60:63]
	v_mfma_f32_16x16x32_bf16 v[56:59], v[158:161], v[182:185], v[56:59]
	v_mfma_f32_16x16x32_bf16 v[52:55], v[150:153], v[190:193], v[52:55]
	v_mfma_f32_16x16x32_bf16 v[48:51], v[158:161], v[190:193], v[48:51]
	v_mfma_f32_16x16x32_bf16 v[36:39], v[150:153], v[198:201], v[36:39]
	v_mfma_f32_16x16x32_bf16 v[32:35], v[158:161], v[198:201], v[32:35]
	v_mfma_f32_16x16x32_bf16 v[20:23], v[150:153], v[206:209], v[20:23]
	v_mfma_f32_16x16x32_bf16 v[16:19], v[158:161], v[206:209], v[16:19]
	v_mfma_f32_16x16x32_bf16 v[60:63], v[154:157], v[186:189], v[60:63]
	v_mfma_f32_16x16x32_bf16 v[56:59], v[162:165], v[186:189], v[56:59]
	v_mfma_f32_16x16x32_bf16 v[52:55], v[154:157], v[194:197], v[52:55]
	v_mfma_f32_16x16x32_bf16 v[48:51], v[162:165], v[194:197], v[48:51]
	v_mfma_f32_16x16x32_bf16 v[36:39], v[154:157], v[202:205], v[36:39]
	v_mfma_f32_16x16x32_bf16 v[32:35], v[162:165], v[202:205], v[32:35]
	v_mfma_f32_16x16x32_bf16 v[20:23], v[154:157], v[210:213], v[20:23]
	v_mfma_f32_16x16x32_bf16 v[16:19], v[162:165], v[210:213], v[16:19]
	v_mfma_f32_16x16x32_bf16 v[44:47], v[166:169], v[182:185], v[44:47]
	v_mfma_f32_16x16x32_bf16 v[40:43], v[174:177], v[182:185], v[40:43]
	v_mfma_f32_16x16x32_bf16 v[28:31], v[166:169], v[190:193], v[28:31]
	v_mfma_f32_16x16x32_bf16 v[24:27], v[174:177], v[190:193], v[24:27]
	v_mfma_f32_16x16x32_bf16 v[12:15], v[166:169], v[198:201], v[12:15]
	v_mfma_f32_16x16x32_bf16 v[8:11], v[174:177], v[198:201], v[8:11]
	v_mfma_f32_16x16x32_bf16 v[4:7], v[166:169], v[206:209], v[4:7]
	v_mfma_f32_16x16x32_bf16 v[0:3], v[174:177], v[206:209], v[0:3]
	v_mfma_f32_16x16x32_bf16 v[44:47], v[170:173], v[186:189], v[44:47]
	v_mfma_f32_16x16x32_bf16 v[40:43], v[178:181], v[186:189], v[40:43]
	v_mfma_f32_16x16x32_bf16 v[28:31], v[170:173], v[194:197], v[28:31]
	v_mfma_f32_16x16x32_bf16 v[24:27], v[178:181], v[194:197], v[24:27]
	v_mfma_f32_16x16x32_bf16 v[12:15], v[170:173], v[202:205], v[12:15]
	v_mfma_f32_16x16x32_bf16 v[8:11], v[178:181], v[202:205], v[8:11]
	v_mfma_f32_16x16x32_bf16 v[4:7], v[170:173], v[210:213], v[4:7]
	v_mfma_f32_16x16x32_bf16 v[0:3], v[178:181], v[210:213], v[0:3]
	s_setprio 0
	s_barrier
	s_add_i32 s68, 0, 0x18000
	s_add_i32 s69, 0, 0x1c000
	v_add_u32_e32 v162, s68, v146
	v_add_u32_e32 v178, s69, v146
	ds_read_b128 v[150:153], v162
	ds_read_b128 v[154:157], v162 offset:1024
	ds_read_b128 v[158:161], v162 offset:2048
	ds_read_b128 v[162:165], v162 offset:3072
	ds_read_b128 v[166:169], v178
	ds_read_b128 v[170:173], v178 offset:1024
	ds_read_b128 v[174:177], v178 offset:2048
	ds_read_b128 v[178:181], v178 offset:3072
	s_add_u32 s48, s48, 0x40000
	s_addc_u32 s49, s49, 0
	s_mov_b32 m0, s55
	v_lshl_add_u64 v[222:223], s[48:49], 0, v[136:137]
	ds_read_b128 v[182:185], v149 offset:32768
	ds_read_b128 v[186:189], v149 offset:33792
	ds_read_b128 v[190:193], v149 offset:34816
	ds_read_b128 v[194:197], v149 offset:35840
	ds_read_b128 v[198:201], v149 offset:36864
	ds_read_b128 v[202:205], v149 offset:37888
	ds_read_b128 v[206:209], v149 offset:38912
	ds_read_b128 v[210:213], v149 offset:39936
	global_load_lds_dwordx4 v[222:223], off
	v_lshl_add_u64 v[222:223], s[48:49], 0, v[132:133]
	s_mov_b32 m0, s56
	s_nop 0
	global_load_lds_dwordx4 v[222:223], off
	s_waitcnt vmcnt(8)
	s_waitcnt lgkmcnt(0)
	s_barrier
	s_setprio 1
	v_mfma_f32_16x16x32_bf16 v[124:127], v[150:153], v[182:185], v[124:127]
	v_mfma_f32_16x16x32_bf16 v[120:123], v[158:161], v[182:185], v[120:123]
	v_mfma_f32_16x16x32_bf16 v[116:119], v[150:153], v[190:193], v[116:119]
	v_mfma_f32_16x16x32_bf16 v[112:115], v[158:161], v[190:193], v[112:115]
	v_mfma_f32_16x16x32_bf16 v[100:103], v[150:153], v[198:201], v[100:103]
	v_mfma_f32_16x16x32_bf16 v[96:99], v[158:161], v[198:201], v[96:99]
	v_mfma_f32_16x16x32_bf16 v[84:87], v[150:153], v[206:209], v[84:87]
	v_mfma_f32_16x16x32_bf16 v[80:83], v[158:161], v[206:209], v[80:83]
	v_mfma_f32_16x16x32_bf16 v[124:127], v[154:157], v[186:189], v[124:127]
	v_mfma_f32_16x16x32_bf16 v[120:123], v[162:165], v[186:189], v[120:123]
	v_mfma_f32_16x16x32_bf16 v[116:119], v[154:157], v[194:197], v[116:119]
	v_mfma_f32_16x16x32_bf16 v[112:115], v[162:165], v[194:197], v[112:115]
	v_mfma_f32_16x16x32_bf16 v[100:103], v[154:157], v[202:205], v[100:103]
	v_mfma_f32_16x16x32_bf16 v[96:99], v[162:165], v[202:205], v[96:99]
	v_mfma_f32_16x16x32_bf16 v[84:87], v[154:157], v[210:213], v[84:87]
	v_mfma_f32_16x16x32_bf16 v[80:83], v[162:165], v[210:213], v[80:83]
	v_mfma_f32_16x16x32_bf16 v[108:111], v[166:169], v[182:185], v[108:111]
	v_mfma_f32_16x16x32_bf16 v[104:107], v[174:177], v[182:185], v[104:107]
	v_mfma_f32_16x16x32_bf16 v[92:95], v[166:169], v[190:193], v[92:95]
	v_mfma_f32_16x16x32_bf16 v[88:91], v[174:177], v[190:193], v[88:91]
	v_mfma_f32_16x16x32_bf16 v[76:79], v[166:169], v[198:201], v[76:79]
	v_mfma_f32_16x16x32_bf16 v[72:75], v[174:177], v[198:201], v[72:75]
	v_mfma_f32_16x16x32_bf16 v[68:71], v[166:169], v[206:209], v[68:71]
	v_mfma_f32_16x16x32_bf16 v[64:67], v[174:177], v[206:209], v[64:67]
	v_mfma_f32_16x16x32_bf16 v[108:111], v[170:173], v[186:189], v[108:111]
	v_mfma_f32_16x16x32_bf16 v[104:107], v[178:181], v[186:189], v[104:107]
	v_mfma_f32_16x16x32_bf16 v[92:95], v[170:173], v[194:197], v[92:95]
	v_mfma_f32_16x16x32_bf16 v[88:91], v[178:181], v[194:197], v[88:91]
	v_mfma_f32_16x16x32_bf16 v[76:79], v[170:173], v[202:205], v[76:79]
	v_mfma_f32_16x16x32_bf16 v[72:75], v[178:181], v[202:205], v[72:75]
	v_mfma_f32_16x16x32_bf16 v[68:71], v[170:173], v[210:213], v[68:71]
	v_mfma_f32_16x16x32_bf16 v[64:67], v[178:181], v[210:213], v[64:67]
	s_setprio 0
	s_barrier
; #define PG8_STAGE(bufoff, gbase, voff) do { _Pragma("unroll") for (int _i = 0; _i < 2; ++_i) \
;         __builtin_amdgcn_global_load_lds((const unsigned*)((const char*)(gbase) + (voff)[_i]), (LAS unsigned*)(lds + (bufoff) + ldsw + _i * 8192), 16, 0, 0); } while (0)
; #define PG8_LDA(dst, b, h) do { _Pragma("unroll") for (int m = 0; m < 4; ++m) _Pragma("unroll") for (int k = 0; k < 2; ++k) dst[m][k] = *(const LAS bf16x8*)(lds + PG8_SA(b, h) + aoff + m * 2048 + k * 1024); } while (0)
; #define PG8_MMA(ai, bj, At, Bt) do { __builtin_amdgcn_s_setprio(1); _Pragma("unroll") for (int m = 0; m < 4; ++m) _Pragma("unroll") for (int n = 0; n < 2; ++n) _Pragma("unroll") for (int k = 0; k < 2; ++k) \
;         acc[ai][bj][m][n] = __builtin_amdgcn_mfma_f32_16x16x32_bf16(Bt[n][k], At[m][k], acc[ai][bj][m][n], 0, 0, 0); __builtin_amdgcn_s_setprio(0); } while (0)
; #define PG8_WAIT_V(n) asm volatile("s_waitcnt vmcnt(" #n ")" ::: "memory")
; #define PG8_WAIT_L(n) asm volatile("s_waitcnt lgkmcnt(" #n ")" ::: "memory")
; #define PG8_BAR __builtin_amdgcn_s_barrier()
; #define PG8_SCHED __builtin_amdgcn_sched_barrier(0)
; template <class Epi, bool SP2 = false>
; __device__ __forceinline__ void gemm_phase(LAS unsigned char* lds, const Gemm g, const StaticOrder& S, const Epi& E) {
;     ...
;             PG8_LDA(At, 1, 1); PG8_STAGE(PG8_SB(1, 0), b3, voffB); PG8_STAGE(PG8_SB(1, 1), b3 + hstepB, voffB); PG8_STAGE(PG8_SA(1, 0), a3, voffA);
;             PG8_WAIT_V(8); PG8_WAIT_L(0); PG8_BAR; PG8_MMA(1, 0, At, B0); PG8_MMA(1, 1, At, B1); PG8_BAR; PG8_SCHED;
;     ...
;         if constexpr (SP2) { if (wr == 0) PG8_BAR; }
	s_add_i32 s48, s68, s50
	v_lshl_add_u64 v[214:215], v[214:215], 0, s[12:13]
	s_mov_b32 m0, s48
	ds_read_b128 v[182:185], v149 offset:49152
	ds_read_b128 v[186:189], v149 offset:50176
	ds_read_b128 v[190:193], v149 offset:51200
	ds_read_b128 v[194:197], v149 offset:52224
	ds_read_b128 v[198:201], v149 offset:53248
	ds_read_b128 v[202:205], v149 offset:54272
	ds_read_b128 v[206:209], v149 offset:55296
	ds_read_b128 v[210:213], v149 offset:56320
	global_load_lds_dwordx4 v[214:215], off
	s_add_i32 m0, s48, 0x2000
	s_add_u32 s46, s46, 0x40080
	v_lshl_add_u64 v[214:215], v[216:217], 0, s[12:13]
	s_addc_u32 s47, s47, 0
	s_add_i32 s48, s69, s50
	global_load_lds_dwordx4 v[214:215], off
	v_lshl_add_u64 v[214:215], s[46:47], 0, v[134:135]
	s_mov_b32 m0, s48
	s_nop 0
	global_load_lds_dwordx4 v[214:215], off
	v_lshl_add_u64 v[214:215], s[46:47], 0, v[130:131]
	s_add_i32 m0, s48, 0x2000
	s_nop 0
	global_load_lds_dwordx4 v[214:215], off
	v_lshl_add_u64 v[214:215], v[218:219], 0, s[12:13]
	s_mov_b32 m0, s59
	s_nop 0
	global_load_lds_dwordx4 v[214:215], off
	v_lshl_add_u64 v[214:215], v[220:221], 0, s[12:13]
	s_mov_b32 m0, s60
	s_nop 0
	global_load_lds_dwordx4 v[214:215], off
	s_waitcnt vmcnt(8)
	s_waitcnt lgkmcnt(0)
	s_barrier
	s_setprio 1
	v_mfma_f32_16x16x32_bf16 v[60:63], v[150:153], v[182:185], v[60:63]
	v_mfma_f32_16x16x32_bf16 v[56:59], v[158:161], v[182:185], v[56:59]
	v_mfma_f32_16x16x32_bf16 v[52:55], v[150:153], v[190:193], v[52:55]
	v_mfma_f32_16x16x32_bf16 v[48:51], v[158:161], v[190:193], v[48:51]
	v_mfma_f32_16x16x32_bf16 v[36:39], v[150:153], v[198:201], v[36:39]
	v_mfma_f32_16x16x32_bf16 v[32:35], v[158:161], v[198:201], v[32:35]
	v_mfma_f32_16x16x32_bf16 v[20:23], v[150:153], v[206:209], v[20:23]
	v_mfma_f32_16x16x32_bf16 v[16:19], v[158:161], v[206:209], v[16:19]
	v_mfma_f32_16x16x32_bf16 v[60:63], v[154:157], v[186:189], v[60:63]
	v_mfma_f32_16x16x32_bf16 v[56:59], v[162:165], v[186:189], v[56:59]
	v_mfma_f32_16x16x32_bf16 v[52:55], v[154:157], v[194:197], v[52:55]
	v_mfma_f32_16x16x32_bf16 v[48:51], v[162:165], v[194:197], v[48:51]
	v_mfma_f32_16x16x32_bf16 v[36:39], v[154:157], v[202:205], v[36:39]
	v_mfma_f32_16x16x32_bf16 v[32:35], v[162:165], v[202:205], v[32:35]
	v_mfma_f32_16x16x32_bf16 v[20:23], v[154:157], v[210:213], v[20:23]
	v_mfma_f32_16x16x32_bf16 v[16:19], v[162:165], v[210:213], v[16:19]
	v_mfma_f32_16x16x32_bf16 v[44:47], v[166:169], v[182:185], v[44:47]
	v_mfma_f32_16x16x32_bf16 v[40:43], v[174:177], v[182:185], v[40:43]
	v_mfma_f32_16x16x32_bf16 v[28:31], v[166:169], v[190:193], v[28:31]
	v_mfma_f32_16x16x32_bf16 v[24:27], v[174:177], v[190:193], v[24:27]
	v_mfma_f32_16x16x32_bf16 v[12:15], v[166:169], v[198:201], v[12:15]
	v_mfma_f32_16x16x32_bf16 v[8:11], v[174:177], v[198:201], v[8:11]
	v_mfma_f32_16x16x32_bf16 v[4:7], v[166:169], v[206:209], v[4:7]
	v_mfma_f32_16x16x32_bf16 v[0:3], v[174:177], v[206:209], v[0:3]
	v_mfma_f32_16x16x32_bf16 v[44:47], v[170:173], v[186:189], v[44:47]
	v_mfma_f32_16x16x32_bf16 v[40:43], v[178:181], v[186:189], v[40:43]
	v_mfma_f32_16x16x32_bf16 v[28:31], v[170:173], v[194:197], v[28:31]
	v_mfma_f32_16x16x32_bf16 v[24:27], v[178:181], v[194:197], v[24:27]
	v_mfma_f32_16x16x32_bf16 v[12:15], v[170:173], v[202:205], v[12:15]
	v_mfma_f32_16x16x32_bf16 v[8:11], v[178:181], v[202:205], v[8:11]
	v_mfma_f32_16x16x32_bf16 v[4:7], v[170:173], v[210:213], v[4:7]
	v_mfma_f32_16x16x32_bf16 v[0:3], v[178:181], v[210:213], v[0:3]
	s_setprio 0
	s_barrier
	s_add_i32 s78, s78, 2
	s_add_u32 s34, s34, 0x100
	s_addc_u32 s35, s35, 0
	s_add_u32 s76, s76, 0x100
	s_addc_u32 s77, s77, 0
	s_cmp_gt_u32 s78, 13
	s_cbranch_scc0 .LBB0_955
	s_and_b64 vcc, exec, s[26:27]
	s_cbranch_vccz .LBB0_958
	s_barrier

; #define PG8_STAGE(bufoff, gbase, voff) do { _Pragma("unroll") for (int _i = 0; _i < 2; ++_i) \
;         __builtin_amdgcn_global_load_lds((const unsigned*)((const char*)(gbase) + (voff)[_i]), (LAS unsigned*)(lds + (bufoff) + ldsw + _i * 8192), 16, 0, 0); } while (0)
; #define PG8_LDA(dst, b, h) do { _Pragma("unroll") for (int m = 0; m < 4; ++m) _Pragma("unroll") for (int k = 0; k < 2; ++k) dst[m][k] = *(const LAS bf16x8*)(lds + PG8_SA(b, h) + aoff + m * 2048 + k * 1024); } while (0)
; #define PG8_LDB(dst, b, h) do { _Pragma("unroll") for (int n = 0; n < 2; ++n) _Pragma("unroll") for (int k = 0; k < 2; ++k) dst[n][k] = *(const LAS bf16x8*)(lds + PG8_SB(b, h) + boff + n * 2048 + k * 1024); } while (0)
; #define PG8_MMA(ai, bj, At, Bt) do { __builtin_amdgcn_s_setprio(1); _Pragma("unroll") for (int m = 0; m < 4; ++m) _Pragma("unroll") for (int n = 0; n < 2; ++n) _Pragma("unroll") for (int k = 0; k < 2; ++k) \
;         acc[ai][bj][m][n] = __builtin_amdgcn_mfma_f32_16x16x32_bf16(Bt[n][k], At[m][k], acc[ai][bj][m][n], 0, 0, 0); __builtin_amdgcn_s_setprio(0); } while (0)
; #define PG8_WAIT_V(n) asm volatile("s_waitcnt vmcnt(" #n ")" ::: "memory")
; #define PG8_WAIT_L(n) asm volatile("s_waitcnt lgkmcnt(" #n ")" ::: "memory")
; #define PG8_BAR __builtin_amdgcn_s_barrier()
; #define PG8_SCHED __builtin_amdgcn_sched_barrier(0)
; template <class Epi, bool SP2 = false>
; __device__ __forceinline__ void gemm_phase(LAS unsigned char* lds, const Gemm g, const StaticOrder& S, const Epi& E) {
;     ...
;             const bool last = (t == nt - 2);
;             const char* a1 = cA + (size_t)(t + 1) * kstep;
;             const char* a2 = last ? nA : cA + (size_t)(t + 2) * kstep; const char* b2 = last ? nB : cB + (size_t)(t + 2) * kstep;
;             const char* a3 = a2 + kstep; const char* b3 = b2 + kstep;
;             if constexpr (SP2) {
;             PG8_LDB(B0, 0, 0); PG8_LDB(B1, 0, 1); PG8_SCHED; PG8_LDA(At, 0, 0); PG8_STAGE(PG8_SA(1, 1), a1 + hstepA, voffA);
;             PG8_WAIT_V(8); PG8_WAIT_L(0); PG8_BAR; PG8_MMA(0, 0, At, B0); PG8_MMA(0, 1, At, B1); PG8_BAR; PG8_SCHED;
;             PG8_LDA(At, 0, 1); PG8_STAGE(PG8_SB(0, 0), b2, voffB); PG8_STAGE(PG8_SB(0, 1), b2 + hstepB, voffB); PG8_STAGE(PG8_SA(0, 0), a2, voffA);
;             PG8_WAIT_V(8); PG8_WAIT_L(0); PG8_BAR; PG8_MMA(1, 0, At, B0); PG8_MMA(1, 1, At, B1); PG8_BAR; PG8_SCHED;
.LBB0_1077:
	ds_read_b128 v[152:155], v149
	ds_read_b128 v[156:159], v149 offset:1024
	ds_read_b128 v[160:163], v149 offset:2048
	ds_read_b128 v[164:167], v149 offset:3072
	ds_read_b128 v[168:171], v150
	ds_read_b128 v[172:175], v150 offset:1024
	ds_read_b128 v[176:179], v150 offset:2048
	ds_read_b128 v[180:183], v150 offset:3072
	s_add_u32 s30, s28, 0xfffc0080
	s_addc_u32 s31, s29, -1
	s_cmp_eq_u32 s57, 12
	s_cselect_b32 s35, s19, s31
	s_cselect_b32 s34, s53, s30
	s_cselect_b32 s31, s13, s56
	s_cselect_b32 s30, s54, s55
	v_lshl_add_u64 v[146:147], s[28:29], 0, v[138:139]
	s_add_i32 m0, s27, 0xc000
	ds_read_b128 v[184:187], v151
	ds_read_b128 v[188:191], v151 offset:1024
	ds_read_b128 v[192:195], v151 offset:2048
	ds_read_b128 v[196:199], v151 offset:3072
	ds_read_b128 v[200:203], v151 offset:4096
	ds_read_b128 v[204:207], v151 offset:5120
	ds_read_b128 v[208:211], v151 offset:6144
	ds_read_b128 v[212:215], v151 offset:7168
	global_load_lds_dwordx4 v[146:147], off
	v_lshl_add_u64 v[146:147], s[28:29], 0, v[140:141]
	s_add_i32 m0, s27, 0xe000
	s_nop 0
	global_load_lds_dwordx4 v[146:147], off
	s_waitcnt vmcnt(8)
	s_waitcnt lgkmcnt(0)
	s_barrier
	s_setprio 1
	v_mfma_f32_16x16x32_bf16 v[124:127], v[152:155], v[184:187], v[124:127]
	v_mfma_f32_16x16x32_bf16 v[120:123], v[160:163], v[184:187], v[120:123]
	v_mfma_f32_16x16x32_bf16 v[108:111], v[152:155], v[192:195], v[108:111]
	v_mfma_f32_16x16x32_bf16 v[104:107], v[160:163], v[192:195], v[104:107]
	v_mfma_f32_16x16x32_bf16 v[92:95], v[152:155], v[200:203], v[92:95]
	v_mfma_f32_16x16x32_bf16 v[88:91], v[160:163], v[200:203], v[88:91]
	v_mfma_f32_16x16x32_bf16 v[76:79], v[152:155], v[208:211], v[76:79]
	v_mfma_f32_16x16x32_bf16 v[72:75], v[160:163], v[208:211], v[72:75]
	v_mfma_f32_16x16x32_bf16 v[124:127], v[156:159], v[188:191], v[124:127]
	v_mfma_f32_16x16x32_bf16 v[120:123], v[164:167], v[188:191], v[120:123]
	v_mfma_f32_16x16x32_bf16 v[108:111], v[156:159], v[196:199], v[108:111]
	v_mfma_f32_16x16x32_bf16 v[104:107], v[164:167], v[196:199], v[104:107]
	v_mfma_f32_16x16x32_bf16 v[92:95], v[156:159], v[204:207], v[92:95]
	v_mfma_f32_16x16x32_bf16 v[88:91], v[164:167], v[204:207], v[88:91]
	v_mfma_f32_16x16x32_bf16 v[76:79], v[156:159], v[212:215], v[76:79]
	v_mfma_f32_16x16x32_bf16 v[72:75], v[164:167], v[212:215], v[72:75]
	v_mfma_f32_16x16x32_bf16 v[116:119], v[168:171], v[184:187], v[116:119]
	v_mfma_f32_16x16x32_bf16 v[112:115], v[176:179], v[184:187], v[112:115]
	v_mfma_f32_16x16x32_bf16 v[100:103], v[168:171], v[192:195], v[100:103]
	v_mfma_f32_16x16x32_bf16 v[96:99], v[176:179], v[192:195], v[96:99]
	v_mfma_f32_16x16x32_bf16 v[84:87], v[168:171], v[200:203], v[84:87]
	v_mfma_f32_16x16x32_bf16 v[80:83], v[176:179], v[200:203], v[80:83]
	v_mfma_f32_16x16x32_bf16 v[68:71], v[168:171], v[208:211], v[68:71]
	v_mfma_f32_16x16x32_bf16 v[64:67], v[176:179], v[208:211], v[64:67]
	v_mfma_f32_16x16x32_bf16 v[116:119], v[172:175], v[188:191], v[116:119]
	v_mfma_f32_16x16x32_bf16 v[112:115], v[180:183], v[188:191], v[112:115]
	v_mfma_f32_16x16x32_bf16 v[100:103], v[172:175], v[196:199], v[100:103]
	v_mfma_f32_16x16x32_bf16 v[96:99], v[180:183], v[196:199], v[96:99]
	v_mfma_f32_16x16x32_bf16 v[84:87], v[172:175], v[204:207], v[84:87]
	v_mfma_f32_16x16x32_bf16 v[80:83], v[180:183], v[204:207], v[80:83]
	v_mfma_f32_16x16x32_bf16 v[68:71], v[172:175], v[212:215], v[68:71]
	v_mfma_f32_16x16x32_bf16 v[64:67], v[180:183], v[212:215], v[64:67]
	s_setprio 0
	s_barrier
	s_add_i32 s58, s50, s37
	v_lshl_add_u64 v[146:147], s[30:31], 0, v[134:135]
	s_mov_b32 m0, s58
	ds_read_b128 v[184:187], v151 offset:16384
	ds_read_b128 v[188:191], v151 offset:17408
	ds_read_b128 v[192:195], v151 offset:18432
	ds_read_b128 v[196:199], v151 offset:19456
	ds_read_b128 v[200:203], v151 offset:20480
	ds_read_b128 v[204:207], v151 offset:21504
	ds_read_b128 v[208:211], v151 offset:22528
	ds_read_b128 v[212:215], v151 offset:23552
	global_load_lds_dwordx4 v[146:147], off
	s_add_i32 m0, s58, 0x2000
	s_add_u32 s58, s30, 0x40000
	v_lshl_add_u64 v[216:217], s[30:31], 0, v[130:131]
	s_addc_u32 s59, s31, 0
	s_add_i32 s60, s51, s37
	global_load_lds_dwordx4 v[216:217], off
	v_lshl_add_u64 v[218:219], s[58:59], 0, v[134:135]
	s_mov_b32 m0, s60
	v_lshl_add_u64 v[220:221], s[34:35], 0, v[132:133]
	global_load_lds_dwordx4 v[218:219], off
	v_lshl_add_u64 v[218:219], s[58:59], 0, v[130:131]
	s_add_i32 m0, s60, 0x2000
	s_nop 0
	global_load_lds_dwordx4 v[218:219], off
	v_lshl_add_u64 v[218:219], s[34:35], 0, v[136:137]
	s_mov_b32 m0, s27
	s_nop 0
	global_load_lds_dwordx4 v[218:219], off
	s_mov_b32 m0, s40
	s_nop 0
	global_load_lds_dwordx4 v[220:221], off
	s_waitcnt vmcnt(8)
	s_waitcnt lgkmcnt(0)
	s_barrier
; #define PG8_STAGE(bufoff, gbase, voff) do { _Pragma("unroll") for (int _i = 0; _i < 2; ++_i) \
;         __builtin_amdgcn_global_load_lds((const unsigned*)((const char*)(gbase) + (voff)[_i]), (LAS unsigned*)(lds + (bufoff) + ldsw + _i * 8192), 16, 0, 0); } while (0)
; #define PG8_LDA(dst, b, h) do { _Pragma("unroll") for (int m = 0; m < 4; ++m) _Pragma("unroll") for (int k = 0; k < 2; ++k) dst[m][k] = *(const LAS bf16x8*)(lds + PG8_SA(b, h) + aoff + m * 2048 + k * 1024); } while (0)
; #define PG8_LDB(dst, b, h) do { _Pragma("unroll") for (int n = 0; n < 2; ++n) _Pragma("unroll") for (int k = 0; k < 2; ++k) dst[n][k] = *(const LAS bf16x8*)(lds + PG8_SB(b, h) + boff + n * 2048 + k * 1024); } while (0)
; #define PG8_MMA(ai, bj, At, Bt) do { __builtin_amdgcn_s_setprio(1); _Pragma("unroll") for (int m = 0; m < 4; ++m) _Pragma("unroll") for (int n = 0; n < 2; ++n) _Pragma("unroll") for (int k = 0; k < 2; ++k) \
;         acc[ai][bj][m][n] = __builtin_amdgcn_mfma_f32_16x16x32_bf16(Bt[n][k], At[m][k], acc[ai][bj][m][n], 0, 0, 0); __builtin_amdgcn_s_setprio(0); } while (0)
; #define PG8_WAIT_V(n) asm volatile("s_waitcnt vmcnt(" #n ")" ::: "memory")
; #define PG8_WAIT_L(n) asm volatile("s_waitcnt lgkmcnt(" #n ")" ::: "memory")
; #define PG8_BAR __builtin_amdgcn_s_barrier()
; #define PG8_SCHED __builtin_amdgcn_sched_barrier(0)
; template <class Epi, bool SP2 = false>
; __device__ __forceinline__ void gemm_phase(LAS unsigned char* lds, const Gemm g, const StaticOrder& S, const Epi& E) {
;     ...
;             PG8_WAIT_V(8); PG8_WAIT_L(0); PG8_BAR; PG8_MMA(1, 0, At, B0); PG8_MMA(1, 1, At, B1); PG8_BAR; PG8_SCHED;
;             PG8_LDB(B0, 1, 0); PG8_LDB(B1, 1, 1); PG8_SCHED; PG8_LDA(At, 1, 0); PG8_STAGE(PG8_SA(0, 1), a2 + hstepA, voffA);
;             PG8_WAIT_V(8); PG8_WAIT_L(0); PG8_BAR; PG8_MMA(0, 0, At, B0); PG8_MMA(0, 1, At, B1); PG8_BAR; PG8_SCHED;
	s_setprio 1
	v_mfma_f32_16x16x32_bf16 v[60:63], v[152:155], v[184:187], v[60:63]
	v_mfma_f32_16x16x32_bf16 v[56:59], v[160:163], v[184:187], v[56:59]
	v_mfma_f32_16x16x32_bf16 v[44:47], v[152:155], v[192:195], v[44:47]
	v_mfma_f32_16x16x32_bf16 v[40:43], v[160:163], v[192:195], v[40:43]
	v_mfma_f32_16x16x32_bf16 v[28:31], v[152:155], v[200:203], v[28:31]
	v_mfma_f32_16x16x32_bf16 v[24:27], v[160:163], v[200:203], v[24:27]
	v_mfma_f32_16x16x32_bf16 v[12:15], v[152:155], v[208:211], v[12:15]
	v_mfma_f32_16x16x32_bf16 v[8:11], v[160:163], v[208:211], v[8:11]
	v_mfma_f32_16x16x32_bf16 v[60:63], v[156:159], v[188:191], v[60:63]
	v_mfma_f32_16x16x32_bf16 v[56:59], v[164:167], v[188:191], v[56:59]
	v_mfma_f32_16x16x32_bf16 v[44:47], v[156:159], v[196:199], v[44:47]
	v_mfma_f32_16x16x32_bf16 v[40:43], v[164:167], v[196:199], v[40:43]
	v_mfma_f32_16x16x32_bf16 v[28:31], v[156:159], v[204:207], v[28:31]
	v_mfma_f32_16x16x32_bf16 v[24:27], v[164:167], v[204:207], v[24:27]
	v_mfma_f32_16x16x32_bf16 v[12:15], v[156:159], v[212:215], v[12:15]
	v_mfma_f32_16x16x32_bf16 v[8:11], v[164:167], v[212:215], v[8:11]
	v_mfma_f32_16x16x32_bf16 v[52:55], v[168:171], v[184:187], v[52:55]
	v_mfma_f32_16x16x32_bf16 v[48:51], v[176:179], v[184:187], v[48:51]
	v_mfma_f32_16x16x32_bf16 v[36:39], v[168:171], v[192:195], v[36:39]
	v_mfma_f32_16x16x32_bf16 v[32:35], v[176:179], v[192:195], v[32:35]
	v_mfma_f32_16x16x32_bf16 v[20:23], v[168:171], v[200:203], v[20:23]
	v_mfma_f32_16x16x32_bf16 v[16:19], v[176:179], v[200:203], v[16:19]
	v_mfma_f32_16x16x32_bf16 v[4:7], v[168:171], v[208:211], v[4:7]
	v_mfma_f32_16x16x32_bf16 v[0:3], v[176:179], v[208:211], v[0:3]
	v_mfma_f32_16x16x32_bf16 v[52:55], v[172:175], v[188:191], v[52:55]
	v_mfma_f32_16x16x32_bf16 v[48:51], v[180:183], v[188:191], v[48:51]
	v_mfma_f32_16x16x32_bf16 v[36:39], v[172:175], v[196:199], v[36:39]
	v_mfma_f32_16x16x32_bf16 v[32:35], v[180:183], v[196:199], v[32:35]
	v_mfma_f32_16x16x32_bf16 v[20:23], v[172:175], v[204:207], v[20:23]
	v_mfma_f32_16x16x32_bf16 v[16:19], v[180:183], v[204:207], v[16:19]
	v_mfma_f32_16x16x32_bf16 v[4:7], v[172:175], v[212:215], v[4:7]
	v_mfma_f32_16x16x32_bf16 v[0:3], v[180:183], v[212:215], v[0:3]
	s_setprio 0
	s_barrier
	s_add_i32 s58, 0, 0x18000
	s_add_i32 s59, 0, 0x1c000
	v_add_u32_e32 v164, s58, v148
	v_add_u32_e32 v180, s59, v148
	ds_read_b128 v[152:155], v164
	ds_read_b128 v[156:159], v164 offset:1024
	ds_read_b128 v[160:163], v164 offset:2048
	ds_read_b128 v[164:167], v164 offset:3072
	ds_read_b128 v[168:171], v180
	ds_read_b128 v[172:175], v180 offset:1024
	ds_read_b128 v[176:179], v180 offset:2048
	ds_read_b128 v[180:183], v180 offset:3072
	s_add_u32 s34, s34, 0x40000
	s_addc_u32 s35, s35, 0
	s_mov_b32 m0, s41
	v_lshl_add_u64 v[222:223], s[34:35], 0, v[136:137]
	ds_read_b128 v[184:187], v151 offset:32768
	ds_read_b128 v[188:191], v151 offset:33792
	ds_read_b128 v[192:195], v151 offset:34816
	ds_read_b128 v[196:199], v151 offset:35840
	ds_read_b128 v[200:203], v151 offset:36864
	ds_read_b128 v[204:207], v151 offset:37888
	ds_read_b128 v[208:211], v151 offset:38912
	ds_read_b128 v[212:215], v151 offset:39936
	global_load_lds_dwordx4 v[222:223], off
	v_lshl_add_u64 v[222:223], s[34:35], 0, v[132:133]
	s_mov_b32 m0, s42
	s_nop 0
	global_load_lds_dwordx4 v[222:223], off
	s_waitcnt vmcnt(8)
	s_waitcnt lgkmcnt(0)
	s_barrier
	s_setprio 1
	v_mfma_f32_16x16x32_bf16 v[124:127], v[152:155], v[184:187], v[124:127]
	v_mfma_f32_16x16x32_bf16 v[120:123], v[160:163], v[184:187], v[120:123]
	v_mfma_f32_16x16x32_bf16 v[108:111], v[152:155], v[192:195], v[108:111]
	v_mfma_f32_16x16x32_bf16 v[104:107], v[160:163], v[192:195], v[104:107]
	v_mfma_f32_16x16x32_bf16 v[92:95], v[152:155], v[200:203], v[92:95]
	v_mfma_f32_16x16x32_bf16 v[88:91], v[160:163], v[200:203], v[88:91]
	v_mfma_f32_16x16x32_bf16 v[76:79], v[152:155], v[208:211], v[76:79]
	v_mfma_f32_16x16x32_bf16 v[72:75], v[160:163], v[208:211], v[72:75]
	v_mfma_f32_16x16x32_bf16 v[124:127], v[156:159], v[188:191], v[124:127]
	v_mfma_f32_16x16x32_bf16 v[120:123], v[164:167], v[188:191], v[120:123]
	v_mfma_f32_16x16x32_bf16 v[108:111], v[156:159], v[196:199], v[108:111]
	v_mfma_f32_16x16x32_bf16 v[104:107], v[164:167], v[196:199], v[104:107]
	v_mfma_f32_16x16x32_bf16 v[92:95], v[156:159], v[204:207], v[92:95]
	v_mfma_f32_16x16x32_bf16 v[88:91], v[164:167], v[204:207], v[88:91]
	v_mfma_f32_16x16x32_bf16 v[76:79], v[156:159], v[212:215], v[76:79]
	v_mfma_f32_16x16x32_bf16 v[72:75], v[164:167], v[212:215], v[72:75]
	v_mfma_f32_16x16x32_bf16 v[116:119], v[168:171], v[184:187], v[116:119]
	v_mfma_f32_16x16x32_bf16 v[112:115], v[176:179], v[184:187], v[112:115]
	v_mfma_f32_16x16x32_bf16 v[100:103], v[168:171], v[192:195], v[100:103]
	v_mfma_f32_16x16x32_bf16 v[96:99], v[176:179], v[192:195], v[96:99]
	v_mfma_f32_16x16x32_bf16 v[84:87], v[168:171], v[200:203], v[84:87]
	v_mfma_f32_16x16x32_bf16 v[80:83], v[176:179], v[200:203], v[80:83]
	v_mfma_f32_16x16x32_bf16 v[68:71], v[168:171], v[208:211], v[68:71]
	v_mfma_f32_16x16x32_bf16 v[64:67], v[176:179], v[208:211], v[64:67]
	v_mfma_f32_16x16x32_bf16 v[116:119], v[172:175], v[188:191], v[116:119]
	v_mfma_f32_16x16x32_bf16 v[112:115], v[180:183], v[188:191], v[112:115]
	v_mfma_f32_16x16x32_bf16 v[100:103], v[172:175], v[196:199], v[100:103]
	v_mfma_f32_16x16x32_bf16 v[96:99], v[180:183], v[196:199], v[96:99]
	v_mfma_f32_16x16x32_bf16 v[84:87], v[172:175], v[204:207], v[84:87]
	v_mfma_f32_16x16x32_bf16 v[80:83], v[180:183], v[204:207], v[80:83]
	v_mfma_f32_16x16x32_bf16 v[68:71], v[172:175], v[212:215], v[68:71]
	v_mfma_f32_16x16x32_bf16 v[64:67], v[180:183], v[212:215], v[64:67]
	s_setprio 0
	s_barrier
; #define PG8_STAGE(bufoff, gbase, voff) do { _Pragma("unroll") for (int _i = 0; _i < 2; ++_i) \
;         __builtin_amdgcn_global_load_lds((const unsigned*)((const char*)(gbase) + (voff)[_i]), (LAS unsigned*)(lds + (bufoff) + ldsw + _i * 8192), 16, 0, 0); } while (0)
; #define PG8_LDA(dst, b, h) do { _Pragma("unroll") for (int m = 0; m < 4; ++m) _Pragma("unroll") for (int k = 0; k < 2; ++k) dst[m][k] = *(const LAS bf16x8*)(lds + PG8_SA(b, h) + aoff + m * 2048 + k * 1024); } while (0)
; #define PG8_MMA(ai, bj, At, Bt) do { __builtin_amdgcn_s_setprio(1); _Pragma("unroll") for (int m = 0; m < 4; ++m) _Pragma("unroll") for (int n = 0; n < 2; ++n) _Pragma("unroll") for (int k = 0; k < 2; ++k) \
;         acc[ai][bj][m][n] = __builtin_amdgcn_mfma_f32_16x16x32_bf16(Bt[n][k], At[m][k], acc[ai][bj][m][n], 0, 0, 0); __builtin_amdgcn_s_setprio(0); } while (0)
; #define PG8_WAIT_V(n) asm volatile("s_waitcnt vmcnt(" #n ")" ::: "memory")
; #define PG8_WAIT_L(n) asm volatile("s_waitcnt lgkmcnt(" #n ")" ::: "memory")
; #define PG8_BAR __builtin_amdgcn_s_barrier()
; #define PG8_SCHED __builtin_amdgcn_sched_barrier(0)
; template <class Epi, bool SP2 = false>
; __device__ __forceinline__ void gemm_phase(LAS unsigned char* lds, const Gemm g, const StaticOrder& S, const Epi& E) {
;     ...
;             PG8_LDA(At, 1, 1); PG8_STAGE(PG8_SB(1, 0), b3, voffB); PG8_STAGE(PG8_SB(1, 1), b3 + hstepB, voffB); PG8_STAGE(PG8_SA(1, 0), a3, voffA);
;             PG8_WAIT_V(8); PG8_WAIT_L(0); PG8_BAR; PG8_MMA(1, 0, At, B0); PG8_MMA(1, 1, At, B1); PG8_BAR; PG8_SCHED;
;     ...
;         if constexpr (SP2) { if (wr == 0) PG8_BAR; }
	s_add_i32 s34, s58, s37
	v_lshl_add_u64 v[146:147], v[146:147], 0, s[8:9]
	s_mov_b32 m0, s34
	ds_read_b128 v[184:187], v151 offset:49152
	ds_read_b128 v[188:191], v151 offset:50176
	ds_read_b128 v[192:195], v151 offset:51200
	ds_read_b128 v[196:199], v151 offset:52224
	ds_read_b128 v[200:203], v151 offset:53248
	ds_read_b128 v[204:207], v151 offset:54272
	ds_read_b128 v[208:211], v151 offset:55296
	ds_read_b128 v[212:215], v151 offset:56320
	global_load_lds_dwordx4 v[146:147], off
	s_add_i32 m0, s34, 0x2000
	s_add_u32 s30, s30, 0x40080
	v_lshl_add_u64 v[146:147], v[216:217], 0, s[8:9]
	s_addc_u32 s31, s31, 0
	s_add_i32 s34, s59, s37
	global_load_lds_dwordx4 v[146:147], off
	v_lshl_add_u64 v[146:147], s[30:31], 0, v[134:135]
	s_mov_b32 m0, s34
	s_nop 0
	global_load_lds_dwordx4 v[146:147], off
	v_lshl_add_u64 v[146:147], s[30:31], 0, v[130:131]
	s_add_i32 m0, s34, 0x2000
	s_nop 0
	global_load_lds_dwordx4 v[146:147], off
	v_lshl_add_u64 v[146:147], v[218:219], 0, s[8:9]
	s_mov_b32 m0, s46
	s_nop 0
	global_load_lds_dwordx4 v[146:147], off
	v_lshl_add_u64 v[146:147], v[220:221], 0, s[8:9]
	s_mov_b32 m0, s47
	s_nop 0
	global_load_lds_dwordx4 v[146:147], off
	s_waitcnt vmcnt(8)
	s_waitcnt lgkmcnt(0)
	s_barrier
	s_setprio 1
	v_mfma_f32_16x16x32_bf16 v[60:63], v[152:155], v[184:187], v[60:63]
	v_mfma_f32_16x16x32_bf16 v[56:59], v[160:163], v[184:187], v[56:59]
	v_mfma_f32_16x16x32_bf16 v[44:47], v[152:155], v[192:195], v[44:47]
	v_mfma_f32_16x16x32_bf16 v[40:43], v[160:163], v[192:195], v[40:43]
	v_mfma_f32_16x16x32_bf16 v[28:31], v[152:155], v[200:203], v[28:31]
	v_mfma_f32_16x16x32_bf16 v[24:27], v[160:163], v[200:203], v[24:27]
	v_mfma_f32_16x16x32_bf16 v[12:15], v[152:155], v[208:211], v[12:15]
	v_mfma_f32_16x16x32_bf16 v[8:11], v[160:163], v[208:211], v[8:11]
	v_mfma_f32_16x16x32_bf16 v[60:63], v[156:159], v[188:191], v[60:63]
	v_mfma_f32_16x16x32_bf16 v[56:59], v[164:167], v[188:191], v[56:59]
	v_mfma_f32_16x16x32_bf16 v[44:47], v[156:159], v[196:199], v[44:47]
	v_mfma_f32_16x16x32_bf16 v[40:43], v[164:167], v[196:199], v[40:43]
	v_mfma_f32_16x16x32_bf16 v[28:31], v[156:159], v[204:207], v[28:31]
	v_mfma_f32_16x16x32_bf16 v[24:27], v[164:167], v[204:207], v[24:27]
	v_mfma_f32_16x16x32_bf16 v[12:15], v[156:159], v[212:215], v[12:15]
	v_mfma_f32_16x16x32_bf16 v[8:11], v[164:167], v[212:215], v[8:11]
	v_mfma_f32_16x16x32_bf16 v[52:55], v[168:171], v[184:187], v[52:55]
	v_mfma_f32_16x16x32_bf16 v[48:51], v[176:179], v[184:187], v[48:51]
	v_mfma_f32_16x16x32_bf16 v[36:39], v[168:171], v[192:195], v[36:39]
	v_mfma_f32_16x16x32_bf16 v[32:35], v[176:179], v[192:195], v[32:35]
	v_mfma_f32_16x16x32_bf16 v[20:23], v[168:171], v[200:203], v[20:23]
	v_mfma_f32_16x16x32_bf16 v[16:19], v[176:179], v[200:203], v[16:19]
	v_mfma_f32_16x16x32_bf16 v[4:7], v[168:171], v[208:211], v[4:7]
	v_mfma_f32_16x16x32_bf16 v[0:3], v[176:179], v[208:211], v[0:3]
	v_mfma_f32_16x16x32_bf16 v[52:55], v[172:175], v[188:191], v[52:55]
	v_mfma_f32_16x16x32_bf16 v[48:51], v[180:183], v[188:191], v[48:51]
	v_mfma_f32_16x16x32_bf16 v[36:39], v[172:175], v[196:199], v[36:39]
	v_mfma_f32_16x16x32_bf16 v[32:35], v[180:183], v[196:199], v[32:35]
	v_mfma_f32_16x16x32_bf16 v[20:23], v[172:175], v[204:207], v[20:23]
	v_mfma_f32_16x16x32_bf16 v[16:19], v[180:183], v[204:207], v[16:19]
	v_mfma_f32_16x16x32_bf16 v[4:7], v[172:175], v[212:215], v[4:7]
	v_mfma_f32_16x16x32_bf16 v[0:3], v[180:183], v[212:215], v[0:3]
	s_setprio 0
	s_barrier
	s_add_i32 s57, s57, 2
	s_add_u32 s28, s28, 0x100
	s_addc_u32 s29, s29, 0
	s_add_u32 s55, s55, 0x100
	s_addc_u32 s56, s56, 0
	s_cmp_gt_u32 s57, 13
	s_cbranch_scc0 .LBB0_1077
	s_and_b64 vcc, exec, s[10:11]
	s_cbranch_vccz .LBB0_1080
	s_barrier

; #define PG8_STAGE(bufoff, gbase, voff) do { _Pragma("unroll") for (int _i = 0; _i < 2; ++_i) \
;         __builtin_amdgcn_global_load_lds((const unsigned*)((const char*)(gbase) + (voff)[_i]), (LAS unsigned*)(lds + (bufoff) + ldsw + _i * 8192), 16, 0, 0); } while (0)
; #define PG8_LDA(dst, b, h) do { _Pragma("unroll") for (int m = 0; m < 4; ++m) _Pragma("unroll") for (int k = 0; k < 2; ++k) dst[m][k] = *(const LAS bf16x8*)(lds + PG8_SA(b, h) + aoff + m * 2048 + k * 1024); } while (0)
; #define PG8_LDB(dst, b, h) do { _Pragma("unroll") for (int n = 0; n < 2; ++n) _Pragma("unroll") for (int k = 0; k < 2; ++k) dst[n][k] = *(const LAS bf16x8*)(lds + PG8_SB(b, h) + boff + n * 2048 + k * 1024); } while (0)
; #define PG8_MMA(ai, bj, At, Bt) do { __builtin_amdgcn_s_setprio(1); _Pragma("unroll") for (int m = 0; m < 4; ++m) _Pragma("unroll") for (int n = 0; n < 2; ++n) _Pragma("unroll") for (int k = 0; k < 2; ++k) \
;         acc[ai][bj][m][n] = __builtin_amdgcn_mfma_f32_16x16x32_bf16(Bt[n][k], At[m][k], acc[ai][bj][m][n], 0, 0, 0); __builtin_amdgcn_s_setprio(0); } while (0)
; #define PG8_WAIT_V(n) asm volatile("s_waitcnt vmcnt(" #n ")" ::: "memory")
; #define PG8_WAIT_L(n) asm volatile("s_waitcnt lgkmcnt(" #n ")" ::: "memory")
; #define PG8_BAR __builtin_amdgcn_s_barrier()
; #define PG8_SCHED __builtin_amdgcn_sched_barrier(0)
; template <class Epi, bool SP2 = false>
; __device__ __forceinline__ void gemm_phase(LAS unsigned char* lds, const Gemm g, const StaticOrder& S, const Epi& E) {
;     ...
;             const bool last = (t == nt - 2);
;             const char* a1 = cA + (size_t)(t + 1) * kstep;
;             const char* a2 = last ? nA : cA + (size_t)(t + 2) * kstep; const char* b2 = last ? nB : cB + (size_t)(t + 2) * kstep;
;             const char* a3 = a2 + kstep; const char* b3 = b2 + kstep;
;             if constexpr (SP2) {
;             PG8_LDB(B0, 0, 0); PG8_LDB(B1, 0, 1); PG8_SCHED; PG8_LDA(At, 0, 0); PG8_STAGE(PG8_SA(1, 1), a1 + hstepA, voffA);
;             PG8_WAIT_V(8); PG8_WAIT_L(0); PG8_BAR; PG8_MMA(0, 0, At, B0); PG8_MMA(0, 1, At, B1); PG8_BAR; PG8_SCHED;
;             PG8_LDA(At, 0, 1); PG8_STAGE(PG8_SB(0, 0), b2, voffB); PG8_STAGE(PG8_SB(0, 1), b2 + hstepB, voffB); PG8_STAGE(PG8_SA(0, 0), a2, voffA);
;             PG8_WAIT_V(8); PG8_WAIT_L(0); PG8_BAR; PG8_MMA(1, 0, At, B0); PG8_MMA(1, 1, At, B1); PG8_BAR; PG8_SCHED;
.LBB0_1148:
	ds_read_b128 v[150:153], v147
	ds_read_b128 v[154:157], v147 offset:1024
	ds_read_b128 v[158:161], v147 offset:2048
	ds_read_b128 v[162:165], v147 offset:3072
	ds_read_b128 v[166:169], v148
	ds_read_b128 v[170:173], v148 offset:1024
	ds_read_b128 v[174:177], v148 offset:2048
	ds_read_b128 v[178:181], v148 offset:3072
	s_add_u32 s34, s30, 0xfff50080
	s_addc_u32 s35, s31, -1
	s_cmp_eq_u32 s64, 40
	s_cselect_b32 s37, s5, s35
	s_cselect_b32 s36, s4, s34
	s_cselect_b32 s35, s29, s63
	s_cselect_b32 s34, s28, s62
	v_lshl_add_u64 v[214:215], s[30:31], 0, v[138:139]
	s_add_i32 m0, s41, 0xc000
	ds_read_b128 v[182:185], v149
	ds_read_b128 v[186:189], v149 offset:1024
	ds_read_b128 v[190:193], v149 offset:2048
	ds_read_b128 v[194:197], v149 offset:3072
	ds_read_b128 v[198:201], v149 offset:4096
	ds_read_b128 v[202:205], v149 offset:5120
	ds_read_b128 v[206:209], v149 offset:6144
	ds_read_b128 v[210:213], v149 offset:7168
	global_load_lds_dwordx4 v[214:215], off
	v_lshl_add_u64 v[214:215], s[30:31], 0, v[140:141]
	s_add_i32 m0, s41, 0xe000
	s_nop 0
	global_load_lds_dwordx4 v[214:215], off
	s_waitcnt vmcnt(8)
	s_waitcnt lgkmcnt(0)
	s_barrier
	s_setprio 1
	v_mfma_f32_16x16x32_bf16 v[124:127], v[150:153], v[182:185], v[124:127]
	v_mfma_f32_16x16x32_bf16 v[120:123], v[158:161], v[182:185], v[120:123]
	v_mfma_f32_16x16x32_bf16 v[116:119], v[150:153], v[190:193], v[116:119]
	v_mfma_f32_16x16x32_bf16 v[112:115], v[158:161], v[190:193], v[112:115]
	v_mfma_f32_16x16x32_bf16 v[100:103], v[150:153], v[198:201], v[100:103]
	v_mfma_f32_16x16x32_bf16 v[96:99], v[158:161], v[198:201], v[96:99]
	v_mfma_f32_16x16x32_bf16 v[84:87], v[150:153], v[206:209], v[84:87]
	v_mfma_f32_16x16x32_bf16 v[80:83], v[158:161], v[206:209], v[80:83]
	v_mfma_f32_16x16x32_bf16 v[124:127], v[154:157], v[186:189], v[124:127]
	v_mfma_f32_16x16x32_bf16 v[120:123], v[162:165], v[186:189], v[120:123]
	v_mfma_f32_16x16x32_bf16 v[116:119], v[154:157], v[194:197], v[116:119]
	v_mfma_f32_16x16x32_bf16 v[112:115], v[162:165], v[194:197], v[112:115]
	v_mfma_f32_16x16x32_bf16 v[100:103], v[154:157], v[202:205], v[100:103]
	v_mfma_f32_16x16x32_bf16 v[96:99], v[162:165], v[202:205], v[96:99]
	v_mfma_f32_16x16x32_bf16 v[84:87], v[154:157], v[210:213], v[84:87]
	v_mfma_f32_16x16x32_bf16 v[80:83], v[162:165], v[210:213], v[80:83]
	v_mfma_f32_16x16x32_bf16 v[108:111], v[166:169], v[182:185], v[108:111]
	v_mfma_f32_16x16x32_bf16 v[104:107], v[174:177], v[182:185], v[104:107]
	v_mfma_f32_16x16x32_bf16 v[92:95], v[166:169], v[190:193], v[92:95]
	v_mfma_f32_16x16x32_bf16 v[88:91], v[174:177], v[190:193], v[88:91]
	v_mfma_f32_16x16x32_bf16 v[76:79], v[166:169], v[198:201], v[76:79]
	v_mfma_f32_16x16x32_bf16 v[72:75], v[174:177], v[198:201], v[72:75]
	v_mfma_f32_16x16x32_bf16 v[68:71], v[166:169], v[206:209], v[68:71]
	v_mfma_f32_16x16x32_bf16 v[64:67], v[174:177], v[206:209], v[64:67]
	v_mfma_f32_16x16x32_bf16 v[108:111], v[170:173], v[186:189], v[108:111]
	v_mfma_f32_16x16x32_bf16 v[104:107], v[178:181], v[186:189], v[104:107]
	v_mfma_f32_16x16x32_bf16 v[92:95], v[170:173], v[194:197], v[92:95]
	v_mfma_f32_16x16x32_bf16 v[88:91], v[178:181], v[194:197], v[88:91]
	v_mfma_f32_16x16x32_bf16 v[76:79], v[170:173], v[202:205], v[76:79]
	v_mfma_f32_16x16x32_bf16 v[72:75], v[178:181], v[202:205], v[72:75]
	v_mfma_f32_16x16x32_bf16 v[68:71], v[170:173], v[210:213], v[68:71]
	v_mfma_f32_16x16x32_bf16 v[64:67], v[178:181], v[210:213], v[64:67]
	s_setprio 0
	s_barrier
	s_add_i32 s65, s52, s38
	v_lshl_add_u64 v[214:215], s[34:35], 0, v[134:135]
	s_mov_b32 m0, s65
	ds_read_b128 v[182:185], v149 offset:16384
	ds_read_b128 v[186:189], v149 offset:17408
	ds_read_b128 v[190:193], v149 offset:18432
	ds_read_b128 v[194:197], v149 offset:19456
	ds_read_b128 v[198:201], v149 offset:20480
	ds_read_b128 v[202:205], v149 offset:21504
	ds_read_b128 v[206:209], v149 offset:22528
	ds_read_b128 v[210:213], v149 offset:23552
	global_load_lds_dwordx4 v[214:215], off
	s_add_i32 m0, s65, 0x2000
	s_add_u32 s66, s34, 0xb0000
	v_lshl_add_u64 v[216:217], s[34:35], 0, v[130:131]
	s_addc_u32 s67, s35, 0
	s_add_i32 s65, s53, s38
	global_load_lds_dwordx4 v[216:217], off
	v_lshl_add_u64 v[218:219], s[66:67], 0, v[134:135]
	s_mov_b32 m0, s65
	v_lshl_add_u64 v[220:221], s[36:37], 0, v[132:133]
	global_load_lds_dwordx4 v[218:219], off
	v_lshl_add_u64 v[218:219], s[66:67], 0, v[130:131]
	s_add_i32 m0, s65, 0x2000
	s_nop 0
	global_load_lds_dwordx4 v[218:219], off
	v_lshl_add_u64 v[218:219], s[36:37], 0, v[136:137]
	s_mov_b32 m0, s41
	s_nop 0
	global_load_lds_dwordx4 v[218:219], off
	s_mov_b32 m0, s42
	s_nop 0
	global_load_lds_dwordx4 v[220:221], off
	s_waitcnt vmcnt(8)
	s_waitcnt lgkmcnt(0)
	s_barrier
; #define PG8_STAGE(bufoff, gbase, voff) do { _Pragma("unroll") for (int _i = 0; _i < 2; ++_i) \
;         __builtin_amdgcn_global_load_lds((const unsigned*)((const char*)(gbase) + (voff)[_i]), (LAS unsigned*)(lds + (bufoff) + ldsw + _i * 8192), 16, 0, 0); } while (0)
; #define PG8_LDA(dst, b, h) do { _Pragma("unroll") for (int m = 0; m < 4; ++m) _Pragma("unroll") for (int k = 0; k < 2; ++k) dst[m][k] = *(const LAS bf16x8*)(lds + PG8_SA(b, h) + aoff + m * 2048 + k * 1024); } while (0)
; #define PG8_LDB(dst, b, h) do { _Pragma("unroll") for (int n = 0; n < 2; ++n) _Pragma("unroll") for (int k = 0; k < 2; ++k) dst[n][k] = *(const LAS bf16x8*)(lds + PG8_SB(b, h) + boff + n * 2048 + k * 1024); } while (0)
; #define PG8_MMA(ai, bj, At, Bt) do { __builtin_amdgcn_s_setprio(1); _Pragma("unroll") for (int m = 0; m < 4; ++m) _Pragma("unroll") for (int n = 0; n < 2; ++n) _Pragma("unroll") for (int k = 0; k < 2; ++k) \
;         acc[ai][bj][m][n] = __builtin_amdgcn_mfma_f32_16x16x32_bf16(Bt[n][k], At[m][k], acc[ai][bj][m][n], 0, 0, 0); __builtin_amdgcn_s_setprio(0); } while (0)
; #define PG8_WAIT_V(n) asm volatile("s_waitcnt vmcnt(" #n ")" ::: "memory")
; #define PG8_WAIT_L(n) asm volatile("s_waitcnt lgkmcnt(" #n ")" ::: "memory")
; #define PG8_BAR __builtin_amdgcn_s_barrier()
; #define PG8_SCHED __builtin_amdgcn_sched_barrier(0)
; template <class Epi, bool SP2 = false>
; __device__ __forceinline__ void gemm_phase(LAS unsigned char* lds, const Gemm g, const StaticOrder& S, const Epi& E) {
;     ...
;             PG8_WAIT_V(8); PG8_WAIT_L(0); PG8_BAR; PG8_MMA(1, 0, At, B0); PG8_MMA(1, 1, At, B1); PG8_BAR; PG8_SCHED;
;             PG8_LDB(B0, 1, 0); PG8_LDB(B1, 1, 1); PG8_SCHED; PG8_LDA(At, 1, 0); PG8_STAGE(PG8_SA(0, 1), a2 + hstepA, voffA);
;             PG8_WAIT_V(8); PG8_WAIT_L(0); PG8_BAR; PG8_MMA(0, 0, At, B0); PG8_MMA(0, 1, At, B1); PG8_BAR; PG8_SCHED;
	s_setprio 1
	v_mfma_f32_16x16x32_bf16 v[60:63], v[150:153], v[182:185], v[60:63]
	v_mfma_f32_16x16x32_bf16 v[56:59], v[158:161], v[182:185], v[56:59]
	v_mfma_f32_16x16x32_bf16 v[52:55], v[150:153], v[190:193], v[52:55]
	v_mfma_f32_16x16x32_bf16 v[48:51], v[158:161], v[190:193], v[48:51]
	v_mfma_f32_16x16x32_bf16 v[36:39], v[150:153], v[198:201], v[36:39]
	v_mfma_f32_16x16x32_bf16 v[32:35], v[158:161], v[198:201], v[32:35]
	v_mfma_f32_16x16x32_bf16 v[20:23], v[150:153], v[206:209], v[20:23]
	v_mfma_f32_16x16x32_bf16 v[16:19], v[158:161], v[206:209], v[16:19]
	v_mfma_f32_16x16x32_bf16 v[60:63], v[154:157], v[186:189], v[60:63]
	v_mfma_f32_16x16x32_bf16 v[56:59], v[162:165], v[186:189], v[56:59]
	v_mfma_f32_16x16x32_bf16 v[52:55], v[154:157], v[194:197], v[52:55]
	v_mfma_f32_16x16x32_bf16 v[48:51], v[162:165], v[194:197], v[48:51]
	v_mfma_f32_16x16x32_bf16 v[36:39], v[154:157], v[202:205], v[36:39]
	v_mfma_f32_16x16x32_bf16 v[32:35], v[162:165], v[202:205], v[32:35]
	v_mfma_f32_16x16x32_bf16 v[20:23], v[154:157], v[210:213], v[20:23]
	v_mfma_f32_16x16x32_bf16 v[16:19], v[162:165], v[210:213], v[16:19]
	v_mfma_f32_16x16x32_bf16 v[44:47], v[166:169], v[182:185], v[44:47]
	v_mfma_f32_16x16x32_bf16 v[40:43], v[174:177], v[182:185], v[40:43]
	v_mfma_f32_16x16x32_bf16 v[28:31], v[166:169], v[190:193], v[28:31]
	v_mfma_f32_16x16x32_bf16 v[24:27], v[174:177], v[190:193], v[24:27]
	v_mfma_f32_16x16x32_bf16 v[12:15], v[166:169], v[198:201], v[12:15]
	v_mfma_f32_16x16x32_bf16 v[8:11], v[174:177], v[198:201], v[8:11]
	v_mfma_f32_16x16x32_bf16 v[4:7], v[166:169], v[206:209], v[4:7]
	v_mfma_f32_16x16x32_bf16 v[0:3], v[174:177], v[206:209], v[0:3]
	v_mfma_f32_16x16x32_bf16 v[44:47], v[170:173], v[186:189], v[44:47]
	v_mfma_f32_16x16x32_bf16 v[40:43], v[178:181], v[186:189], v[40:43]
	v_mfma_f32_16x16x32_bf16 v[28:31], v[170:173], v[194:197], v[28:31]
	v_mfma_f32_16x16x32_bf16 v[24:27], v[178:181], v[194:197], v[24:27]
	v_mfma_f32_16x16x32_bf16 v[12:15], v[170:173], v[202:205], v[12:15]
	v_mfma_f32_16x16x32_bf16 v[8:11], v[178:181], v[202:205], v[8:11]
	v_mfma_f32_16x16x32_bf16 v[4:7], v[170:173], v[210:213], v[4:7]
	v_mfma_f32_16x16x32_bf16 v[0:3], v[178:181], v[210:213], v[0:3]
	s_setprio 0
	s_barrier
	s_add_i32 s65, 0, 0x18000
	s_add_i32 s66, 0, 0x1c000
	v_add_u32_e32 v162, s65, v146
	v_add_u32_e32 v178, s66, v146
	ds_read_b128 v[150:153], v162
	ds_read_b128 v[154:157], v162 offset:1024
	ds_read_b128 v[158:161], v162 offset:2048
	ds_read_b128 v[162:165], v162 offset:3072
	ds_read_b128 v[166:169], v178
	ds_read_b128 v[170:173], v178 offset:1024
	ds_read_b128 v[174:177], v178 offset:2048
	ds_read_b128 v[178:181], v178 offset:3072
	s_add_u32 s36, s36, 0xb0000
	s_addc_u32 s37, s37, 0
	s_mov_b32 m0, s43
	v_lshl_add_u64 v[222:223], s[36:37], 0, v[136:137]
	ds_read_b128 v[182:185], v149 offset:32768
	ds_read_b128 v[186:189], v149 offset:33792
	ds_read_b128 v[190:193], v149 offset:34816
	ds_read_b128 v[194:197], v149 offset:35840
	ds_read_b128 v[198:201], v149 offset:36864
	ds_read_b128 v[202:205], v149 offset:37888
	ds_read_b128 v[206:209], v149 offset:38912
	ds_read_b128 v[210:213], v149 offset:39936
	global_load_lds_dwordx4 v[222:223], off
	v_lshl_add_u64 v[222:223], s[36:37], 0, v[132:133]
	s_mov_b32 m0, s44
	s_nop 0
	global_load_lds_dwordx4 v[222:223], off
	s_waitcnt vmcnt(8)
	s_waitcnt lgkmcnt(0)
	s_barrier
	s_setprio 1
	v_mfma_f32_16x16x32_bf16 v[124:127], v[150:153], v[182:185], v[124:127]
	v_mfma_f32_16x16x32_bf16 v[120:123], v[158:161], v[182:185], v[120:123]
	v_mfma_f32_16x16x32_bf16 v[116:119], v[150:153], v[190:193], v[116:119]
	v_mfma_f32_16x16x32_bf16 v[112:115], v[158:161], v[190:193], v[112:115]
	v_mfma_f32_16x16x32_bf16 v[100:103], v[150:153], v[198:201], v[100:103]
	v_mfma_f32_16x16x32_bf16 v[96:99], v[158:161], v[198:201], v[96:99]
	v_mfma_f32_16x16x32_bf16 v[84:87], v[150:153], v[206:209], v[84:87]
	v_mfma_f32_16x16x32_bf16 v[80:83], v[158:161], v[206:209], v[80:83]
	v_mfma_f32_16x16x32_bf16 v[124:127], v[154:157], v[186:189], v[124:127]
	v_mfma_f32_16x16x32_bf16 v[120:123], v[162:165], v[186:189], v[120:123]
	v_mfma_f32_16x16x32_bf16 v[116:119], v[154:157], v[194:197], v[116:119]
	v_mfma_f32_16x16x32_bf16 v[112:115], v[162:165], v[194:197], v[112:115]
	v_mfma_f32_16x16x32_bf16 v[100:103], v[154:157], v[202:205], v[100:103]
	v_mfma_f32_16x16x32_bf16 v[96:99], v[162:165], v[202:205], v[96:99]
	v_mfma_f32_16x16x32_bf16 v[84:87], v[154:157], v[210:213], v[84:87]
	v_mfma_f32_16x16x32_bf16 v[80:83], v[162:165], v[210:213], v[80:83]
	v_mfma_f32_16x16x32_bf16 v[108:111], v[166:169], v[182:185], v[108:111]
	v_mfma_f32_16x16x32_bf16 v[104:107], v[174:177], v[182:185], v[104:107]
	v_mfma_f32_16x16x32_bf16 v[92:95], v[166:169], v[190:193], v[92:95]
	v_mfma_f32_16x16x32_bf16 v[88:91], v[174:177], v[190:193], v[88:91]
	v_mfma_f32_16x16x32_bf16 v[76:79], v[166:169], v[198:201], v[76:79]
	v_mfma_f32_16x16x32_bf16 v[72:75], v[174:177], v[198:201], v[72:75]
	v_mfma_f32_16x16x32_bf16 v[68:71], v[166:169], v[206:209], v[68:71]
	v_mfma_f32_16x16x32_bf16 v[64:67], v[174:177], v[206:209], v[64:67]
	v_mfma_f32_16x16x32_bf16 v[108:111], v[170:173], v[186:189], v[108:111]
	v_mfma_f32_16x16x32_bf16 v[104:107], v[178:181], v[186:189], v[104:107]
	v_mfma_f32_16x16x32_bf16 v[92:95], v[170:173], v[194:197], v[92:95]
	v_mfma_f32_16x16x32_bf16 v[88:91], v[178:181], v[194:197], v[88:91]
	v_mfma_f32_16x16x32_bf16 v[76:79], v[170:173], v[202:205], v[76:79]
	v_mfma_f32_16x16x32_bf16 v[72:75], v[178:181], v[202:205], v[72:75]
	v_mfma_f32_16x16x32_bf16 v[68:71], v[170:173], v[210:213], v[68:71]
	v_mfma_f32_16x16x32_bf16 v[64:67], v[178:181], v[210:213], v[64:67]
	s_setprio 0
	s_barrier
; #define PG8_STAGE(bufoff, gbase, voff) do { _Pragma("unroll") for (int _i = 0; _i < 2; ++_i) \
;         __builtin_amdgcn_global_load_lds((const unsigned*)((const char*)(gbase) + (voff)[_i]), (LAS unsigned*)(lds + (bufoff) + ldsw + _i * 8192), 16, 0, 0); } while (0)
; #define PG8_LDA(dst, b, h) do { _Pragma("unroll") for (int m = 0; m < 4; ++m) _Pragma("unroll") for (int k = 0; k < 2; ++k) dst[m][k] = *(const LAS bf16x8*)(lds + PG8_SA(b, h) + aoff + m * 2048 + k * 1024); } while (0)
; #define PG8_MMA(ai, bj, At, Bt) do { __builtin_amdgcn_s_setprio(1); _Pragma("unroll") for (int m = 0; m < 4; ++m) _Pragma("unroll") for (int n = 0; n < 2; ++n) _Pragma("unroll") for (int k = 0; k < 2; ++k) \
;         acc[ai][bj][m][n] = __builtin_amdgcn_mfma_f32_16x16x32_bf16(Bt[n][k], At[m][k], acc[ai][bj][m][n], 0, 0, 0); __builtin_amdgcn_s_setprio(0); } while (0)
; #define PG8_WAIT_V(n) asm volatile("s_waitcnt vmcnt(" #n ")" ::: "memory")
; #define PG8_WAIT_L(n) asm volatile("s_waitcnt lgkmcnt(" #n ")" ::: "memory")
; #define PG8_BAR __builtin_amdgcn_s_barrier()
; #define PG8_SCHED __builtin_amdgcn_sched_barrier(0)
; template <class Epi, bool SP2 = false>
; __device__ __forceinline__ void gemm_phase(LAS unsigned char* lds, const Gemm g, const StaticOrder& S, const Epi& E) {
;     ...
;             PG8_LDA(At, 1, 1); PG8_STAGE(PG8_SB(1, 0), b3, voffB); PG8_STAGE(PG8_SB(1, 1), b3 + hstepB, voffB); PG8_STAGE(PG8_SA(1, 0), a3, voffA);
;             PG8_WAIT_V(8); PG8_WAIT_L(0); PG8_BAR; PG8_MMA(1, 0, At, B0); PG8_MMA(1, 1, At, B1); PG8_BAR; PG8_SCHED;
;     ...
;         if constexpr (SP2) { if (wr == 0) PG8_BAR; }
	s_add_i32 s36, s65, s38
	v_lshl_add_u64 v[214:215], v[214:215], 0, s[10:11]
	s_mov_b32 m0, s36
	ds_read_b128 v[182:185], v149 offset:49152
	ds_read_b128 v[186:189], v149 offset:50176
	ds_read_b128 v[190:193], v149 offset:51200
	ds_read_b128 v[194:197], v149 offset:52224
	ds_read_b128 v[198:201], v149 offset:53248
	ds_read_b128 v[202:205], v149 offset:54272
	ds_read_b128 v[206:209], v149 offset:55296
	ds_read_b128 v[210:213], v149 offset:56320
	global_load_lds_dwordx4 v[214:215], off
	s_add_i32 m0, s36, 0x2000
	s_add_u32 s34, s34, 0xb0080
	v_lshl_add_u64 v[214:215], v[216:217], 0, s[10:11]
	s_addc_u32 s35, s35, 0
	s_add_i32 s36, s66, s38
	global_load_lds_dwordx4 v[214:215], off
	v_lshl_add_u64 v[214:215], s[34:35], 0, v[134:135]
	s_mov_b32 m0, s36
	s_nop 0
	global_load_lds_dwordx4 v[214:215], off
	v_lshl_add_u64 v[214:215], s[34:35], 0, v[130:131]
	s_add_i32 m0, s36, 0x2000
	s_nop 0
	global_load_lds_dwordx4 v[214:215], off
	v_lshl_add_u64 v[214:215], v[218:219], 0, s[10:11]
	s_mov_b32 m0, s48
	s_nop 0
	global_load_lds_dwordx4 v[214:215], off
	v_lshl_add_u64 v[214:215], v[220:221], 0, s[10:11]
	s_mov_b32 m0, s49
	s_nop 0
	global_load_lds_dwordx4 v[214:215], off
	s_waitcnt vmcnt(8)
	s_waitcnt lgkmcnt(0)
	s_barrier
	s_setprio 1
	v_mfma_f32_16x16x32_bf16 v[60:63], v[150:153], v[182:185], v[60:63]
	v_mfma_f32_16x16x32_bf16 v[56:59], v[158:161], v[182:185], v[56:59]
	v_mfma_f32_16x16x32_bf16 v[52:55], v[150:153], v[190:193], v[52:55]
	v_mfma_f32_16x16x32_bf16 v[48:51], v[158:161], v[190:193], v[48:51]
	v_mfma_f32_16x16x32_bf16 v[36:39], v[150:153], v[198:201], v[36:39]
	v_mfma_f32_16x16x32_bf16 v[32:35], v[158:161], v[198:201], v[32:35]
	v_mfma_f32_16x16x32_bf16 v[20:23], v[150:153], v[206:209], v[20:23]
	v_mfma_f32_16x16x32_bf16 v[16:19], v[158:161], v[206:209], v[16:19]
	v_mfma_f32_16x16x32_bf16 v[60:63], v[154:157], v[186:189], v[60:63]
	v_mfma_f32_16x16x32_bf16 v[56:59], v[162:165], v[186:189], v[56:59]
	v_mfma_f32_16x16x32_bf16 v[52:55], v[154:157], v[194:197], v[52:55]
	v_mfma_f32_16x16x32_bf16 v[48:51], v[162:165], v[194:197], v[48:51]
	v_mfma_f32_16x16x32_bf16 v[36:39], v[154:157], v[202:205], v[36:39]
	v_mfma_f32_16x16x32_bf16 v[32:35], v[162:165], v[202:205], v[32:35]
	v_mfma_f32_16x16x32_bf16 v[20:23], v[154:157], v[210:213], v[20:23]
	v_mfma_f32_16x16x32_bf16 v[16:19], v[162:165], v[210:213], v[16:19]
	v_mfma_f32_16x16x32_bf16 v[44:47], v[166:169], v[182:185], v[44:47]
	v_mfma_f32_16x16x32_bf16 v[40:43], v[174:177], v[182:185], v[40:43]
	v_mfma_f32_16x16x32_bf16 v[28:31], v[166:169], v[190:193], v[28:31]
	v_mfma_f32_16x16x32_bf16 v[24:27], v[174:177], v[190:193], v[24:27]
	v_mfma_f32_16x16x32_bf16 v[12:15], v[166:169], v[198:201], v[12:15]
	v_mfma_f32_16x16x32_bf16 v[8:11], v[174:177], v[198:201], v[8:11]
	v_mfma_f32_16x16x32_bf16 v[4:7], v[166:169], v[206:209], v[4:7]
	v_mfma_f32_16x16x32_bf16 v[0:3], v[174:177], v[206:209], v[0:3]
	v_mfma_f32_16x16x32_bf16 v[44:47], v[170:173], v[186:189], v[44:47]
	v_mfma_f32_16x16x32_bf16 v[40:43], v[178:181], v[186:189], v[40:43]
	v_mfma_f32_16x16x32_bf16 v[28:31], v[170:173], v[194:197], v[28:31]
	v_mfma_f32_16x16x32_bf16 v[24:27], v[178:181], v[194:197], v[24:27]
	v_mfma_f32_16x16x32_bf16 v[12:15], v[170:173], v[202:205], v[12:15]
	v_mfma_f32_16x16x32_bf16 v[8:11], v[178:181], v[202:205], v[8:11]
	v_mfma_f32_16x16x32_bf16 v[4:7], v[170:173], v[210:213], v[4:7]
	v_mfma_f32_16x16x32_bf16 v[0:3], v[178:181], v[210:213], v[0:3]
	s_setprio 0
	s_barrier
	s_add_i32 s64, s64, 2
	s_add_u32 s30, s30, 0x100
	s_addc_u32 s31, s31, 0
	s_add_u32 s62, s62, 0x100
	s_addc_u32 s63, s63, 0
	s_cmp_gt_u32 s64, 41
	s_cbranch_scc0 .LBB0_1148
	s_and_b64 vcc, exec, s[12:13]
	s_cbranch_vccz .LBB0_1151
	s_barrier
